# GEMM K-loops: half of the LDS-DMA loads now use SGPR base + 32-bit VGPR offset (no v_lshl_add_u64 VALU in the load segments for them), on top of v28 tight barrier turnaround
# speedup vs baseline: 1.0074x; 1.0004x over previous
; #define PG8_STAGE(bufoff, gbase, voff) do { _Pragma("unroll") for (int _i = 0; _i < 2; ++_i) \
;         __builtin_amdgcn_global_load_lds((const unsigned*)((const char*)(gbase) + (voff)[_i]), (LAS unsigned*)(lds + (bufoff) + ldsw + _i * 8192), 16, 0, 0); } while (0)
; #define PG8_LDA(dst, b, h) do { _Pragma("unroll") for (int m = 0; m < 4; ++m) _Pragma("unroll") for (int k = 0; k < 2; ++k) dst[m][k] = *(const LAS bf16x8*)(lds + PG8_SA(b, h) + aoff + m * 2048 + k * 1024); } while (0)
; #define PG8_LDB(dst, b, h) do { _Pragma("unroll") for (int n = 0; n < 2; ++n) _Pragma("unroll") for (int k = 0; k < 2; ++k) dst[n][k] = *(const LAS bf16x8*)(lds + PG8_SB(b, h) + boff + n * 2048 + k * 1024); } while (0)
; #define PG8_MMA(ai, bj, At, Bt) do { __builtin_amdgcn_s_setprio(1); _Pragma("unroll") for (int m = 0; m < 4; ++m) _Pragma("unroll") for (int n = 0; n < 2; ++n) _Pragma("unroll") for (int k = 0; k < 2; ++k) \
;         acc[ai][bj][m][n] = __builtin_amdgcn_mfma_f32_16x16x32_bf16(Bt[n][k], At[m][k], acc[ai][bj][m][n], 0, 0, 0); __builtin_amdgcn_s_setprio(0); } while (0)
; #define PG8_WAIT_V(n) asm volatile("s_waitcnt vmcnt(" #n ")" ::: "memory")
; #define PG8_WAIT_L(n) asm volatile("s_waitcnt lgkmcnt(" #n ")" ::: "memory")
; #define PG8_BAR __builtin_amdgcn_s_barrier()
; #define PG8_SCHED __builtin_amdgcn_sched_barrier(0)
; template <class Epi, class Sched, bool ALIGN_EPI = true, bool SP2 = true>
; __device__ __forceinline__ void gemm_phase(LAS unsigned char* lds, const Gemm g, const Sched& S, const Epi& E) {
;     ...
;             const char* a1 = cA + (size_t)(t + 1) * kstep;
;             const char* a2 = last ? nA : cA + (size_t)(t + 2) * kstep; const char* b2 = last ? nB : cB + (size_t)(t + 2) * kstep;
;             const char* a3 = a2 + kstep; const char* b3 = b2 + kstep;
;             if (last && has_next) S.a_ready(nxt);
;             if constexpr (SP2) {
;             PG8_LDB(B0, 0, 0); PG8_LDB(B1, 0, 1); PG8_SCHED; PG8_LDA(At, 0, 0); PG8_STAGE(PG8_SA(1, 1), a1 + hstep, voffA);
;             PG8_WAIT_V(8); PG8_WAIT_L(0); PG8_BAR; PG8_MMA(0, 0, At, B0); PG8_MMA(0, 1, At, B1); PG8_BAR; PG8_SCHED;
;             PG8_LDA(At, 0, 1); PG8_STAGE(PG8_SB(0, 0), b2, voffB); PG8_STAGE(PG8_SB(0, 1), b2 + hstep, voffB); PG8_STAGE(PG8_SA(0, 0), a2, voffA);
;             PG8_WAIT_V(8); PG8_WAIT_L(0); PG8_BAR; PG8_MMA(1, 0, At, B0); PG8_MMA(1, 1, At, B1); PG8_BAR; PG8_SCHED;
.LBB0_138:
	ds_read_b128 v[130:133], v170
	ds_read_b128 v[134:137], v170 offset:1024
	ds_read_b128 v[176:179], v170 offset:2048
	ds_read_b128 v[180:183], v170 offset:3072
	ds_read_b128 v[184:187], v171
	ds_read_b128 v[188:191], v171 offset:1024
	ds_read_b128 v[192:195], v171 offset:2048
	ds_read_b128 v[196:199], v171 offset:3072
	s_add_u32 s40, s38, 0xfff00080
	s_addc_u32 s41, s39, -1
	s_cmp_eq_u32 s66, 60
	s_cselect_b32 s43, s5, s41
	s_cselect_b32 s42, s18, s40
	s_cselect_b32 s41, s27, s65
	s_cselect_b32 s40, s29, s64
	s_add_i32 m0, s37, 0xc000
	ds_read_b128 v[200:203], v172
	ds_read_b128 v[204:207], v172 offset:1024
	ds_read_b128 v[208:211], v172 offset:2048
	ds_read_b128 v[212:215], v172 offset:3072
	ds_read_b128 v[220:223], v172 offset:4096
	ds_read_b128 v[224:227], v172 offset:5120
	ds_read_b128 v[228:231], v172 offset:6144
	ds_read_b128 v[232:235], v172 offset:7168
	global_load_lds_dwordx4 v152, s[38:39]
	s_add_i32 m0, s37, 0xe000
	s_nop 0
	global_load_lds_dwordx4 v154, s[38:39]
	s_waitcnt vmcnt(8)
	s_waitcnt lgkmcnt(0)
	s_setprio 1
	s_barrier
	v_mfma_f32_16x16x32_bf16 v[126:129], v[130:133], v[200:203], v[126:129]
	v_mfma_f32_16x16x32_bf16 v[122:125], v[176:179], v[200:203], v[122:125]
	v_mfma_f32_16x16x32_bf16 v[106:109], v[176:179], v[208:211], v[106:109]
	v_mfma_f32_16x16x32_bf16 v[110:113], v[130:133], v[208:211], v[110:113]
	v_mfma_f32_16x16x32_bf16 v[94:97], v[130:133], v[220:223], v[94:97]
	v_mfma_f32_16x16x32_bf16 v[90:93], v[176:179], v[220:223], v[90:93]
	v_mfma_f32_16x16x32_bf16 v[74:77], v[176:179], v[228:231], v[74:77]
	v_mfma_f32_16x16x32_bf16 v[78:81], v[130:133], v[228:231], v[78:81]
	v_mfma_f32_16x16x32_bf16 v[126:129], v[134:137], v[204:207], v[126:129]
	v_mfma_f32_16x16x32_bf16 v[122:125], v[180:183], v[204:207], v[122:125]
	v_mfma_f32_16x16x32_bf16 v[106:109], v[180:183], v[212:215], v[106:109]
	v_mfma_f32_16x16x32_bf16 v[110:113], v[134:137], v[212:215], v[110:113]
	v_mfma_f32_16x16x32_bf16 v[94:97], v[134:137], v[224:227], v[94:97]
	v_mfma_f32_16x16x32_bf16 v[90:93], v[180:183], v[224:227], v[90:93]
	v_mfma_f32_16x16x32_bf16 v[74:77], v[180:183], v[232:235], v[74:77]
	v_mfma_f32_16x16x32_bf16 v[78:81], v[134:137], v[232:235], v[78:81]
	v_mfma_f32_16x16x32_bf16 v[118:121], v[184:187], v[200:203], v[118:121]
	v_mfma_f32_16x16x32_bf16 v[114:117], v[192:195], v[200:203], v[114:117]
	v_mfma_f32_16x16x32_bf16 v[98:101], v[192:195], v[208:211], v[98:101]
	v_mfma_f32_16x16x32_bf16 v[102:105], v[184:187], v[208:211], v[102:105]
	v_mfma_f32_16x16x32_bf16 v[86:89], v[184:187], v[220:223], v[86:89]
	v_mfma_f32_16x16x32_bf16 v[82:85], v[192:195], v[220:223], v[82:85]
	v_mfma_f32_16x16x32_bf16 v[66:69], v[192:195], v[228:231], v[66:69]
	v_mfma_f32_16x16x32_bf16 v[70:73], v[184:187], v[228:231], v[70:73]
	v_mfma_f32_16x16x32_bf16 v[118:121], v[188:191], v[204:207], v[118:121]
	v_mfma_f32_16x16x32_bf16 v[114:117], v[196:199], v[204:207], v[114:117]
	v_mfma_f32_16x16x32_bf16 v[98:101], v[196:199], v[212:215], v[98:101]
	v_mfma_f32_16x16x32_bf16 v[102:105], v[188:191], v[212:215], v[102:105]
	v_mfma_f32_16x16x32_bf16 v[86:89], v[188:191], v[224:227], v[86:89]
	v_mfma_f32_16x16x32_bf16 v[82:85], v[196:199], v[224:227], v[82:85]
	v_mfma_f32_16x16x32_bf16 v[66:69], v[196:199], v[232:235], v[66:69]
	v_mfma_f32_16x16x32_bf16 v[70:73], v[188:191], v[232:235], v[70:73]
	s_barrier
	s_setprio 0
	s_add_i32 s67, s60, s45
	v_lshl_add_u64 v[216:217], s[40:41], 0, v[140:141]
	s_mov_b32 m0, s67
	ds_read_b128 v[200:203], v172 offset:16384
	ds_read_b128 v[204:207], v172 offset:17408
	ds_read_b128 v[208:211], v172 offset:18432
	ds_read_b128 v[212:215], v172 offset:19456
	ds_read_b128 v[220:223], v172 offset:20480
	ds_read_b128 v[224:227], v172 offset:21504
	ds_read_b128 v[228:231], v172 offset:22528
	ds_read_b128 v[232:235], v172 offset:23552
	global_load_lds_dwordx4 v[216:217], off
	s_add_i32 m0, s67, 0x2000
	s_add_u32 s68, s40, 0x100000
	v_lshl_add_u64 v[218:219], s[40:41], 0, v[144:145]
	s_addc_u32 s69, s41, 0
	s_add_i32 s67, s61, s45
	global_load_lds_dwordx4 v[218:219], off
	s_mov_b32 m0, s67
	v_lshl_add_u64 v[238:239], s[42:43], 0, v[142:143]
	global_load_lds_dwordx4 v140, s[68:69]
	s_add_i32 m0, s67, 0x2000
	s_nop 0
	global_load_lds_dwordx4 v144, s[68:69]
	v_lshl_add_u64 v[236:237], s[42:43], 0, v[138:139]
	s_mov_b32 m0, s37
	s_nop 0
	global_load_lds_dwordx4 v[236:237], off
	s_mov_b32 m0, s47
	s_nop 0
	global_load_lds_dwordx4 v[238:239], off
	s_waitcnt vmcnt(8)
	s_waitcnt lgkmcnt(0)
	s_setprio 1
	s_barrier
	v_mfma_f32_16x16x32_bf16 v[62:65], v[130:133], v[200:203], v[62:65]
	v_mfma_f32_16x16x32_bf16 v[58:61], v[176:179], v[200:203], v[58:61]
	v_mfma_f32_16x16x32_bf16 v[42:45], v[176:179], v[208:211], v[42:45]
	v_mfma_f32_16x16x32_bf16 v[46:49], v[130:133], v[208:211], v[46:49]
	v_mfma_f32_16x16x32_bf16 v[30:33], v[130:133], v[220:223], v[30:33]
	v_mfma_f32_16x16x32_bf16 v[26:29], v[176:179], v[220:223], v[26:29]
	v_mfma_f32_16x16x32_bf16 v[10:13], v[176:179], v[228:231], v[10:13]
	v_mfma_f32_16x16x32_bf16 v[14:17], v[130:133], v[228:231], v[14:17]
	v_mfma_f32_16x16x32_bf16 v[62:65], v[134:137], v[204:207], v[62:65]
	v_mfma_f32_16x16x32_bf16 v[58:61], v[180:183], v[204:207], v[58:61]
	v_mfma_f32_16x16x32_bf16 v[42:45], v[180:183], v[212:215], v[42:45]
	v_mfma_f32_16x16x32_bf16 v[46:49], v[134:137], v[212:215], v[46:49]
	v_mfma_f32_16x16x32_bf16 v[30:33], v[134:137], v[224:227], v[30:33]
	v_mfma_f32_16x16x32_bf16 v[26:29], v[180:183], v[224:227], v[26:29]
	v_mfma_f32_16x16x32_bf16 v[10:13], v[180:183], v[232:235], v[10:13]
	v_mfma_f32_16x16x32_bf16 v[14:17], v[134:137], v[232:235], v[14:17]
	v_mfma_f32_16x16x32_bf16 v[54:57], v[184:187], v[200:203], v[54:57]
	v_mfma_f32_16x16x32_bf16 v[50:53], v[192:195], v[200:203], v[50:53]
	v_mfma_f32_16x16x32_bf16 v[34:37], v[192:195], v[208:211], v[34:37]
	v_mfma_f32_16x16x32_bf16 v[38:41], v[184:187], v[208:211], v[38:41]
	v_mfma_f32_16x16x32_bf16 v[22:25], v[184:187], v[220:223], v[22:25]
	v_mfma_f32_16x16x32_bf16 v[18:21], v[192:195], v[220:223], v[18:21]
	v_mfma_f32_16x16x32_bf16 v[2:5], v[192:195], v[228:231], v[2:5]
	v_mfma_f32_16x16x32_bf16 v[6:9], v[184:187], v[228:231], v[6:9]
	v_mfma_f32_16x16x32_bf16 v[54:57], v[188:191], v[204:207], v[54:57]
	v_mfma_f32_16x16x32_bf16 v[50:53], v[196:199], v[204:207], v[50:53]
	v_mfma_f32_16x16x32_bf16 v[34:37], v[196:199], v[212:215], v[34:37]
	v_mfma_f32_16x16x32_bf16 v[38:41], v[188:191], v[212:215], v[38:41]
	v_mfma_f32_16x16x32_bf16 v[22:25], v[188:191], v[224:227], v[22:25]
	v_mfma_f32_16x16x32_bf16 v[18:21], v[196:199], v[224:227], v[18:21]
	v_mfma_f32_16x16x32_bf16 v[2:5], v[196:199], v[232:235], v[2:5]
	v_mfma_f32_16x16x32_bf16 v[6:9], v[188:191], v[232:235], v[6:9]
	s_barrier
; #define PG8_STAGE(bufoff, gbase, voff) do { _Pragma("unroll") for (int _i = 0; _i < 2; ++_i) \
;         __builtin_amdgcn_global_load_lds((const unsigned*)((const char*)(gbase) + (voff)[_i]), (LAS unsigned*)(lds + (bufoff) + ldsw + _i * 8192), 16, 0, 0); } while (0)
; #define PG8_LDA(dst, b, h) do { _Pragma("unroll") for (int m = 0; m < 4; ++m) _Pragma("unroll") for (int k = 0; k < 2; ++k) dst[m][k] = *(const LAS bf16x8*)(lds + PG8_SA(b, h) + aoff + m * 2048 + k * 1024); } while (0)
; #define PG8_LDB(dst, b, h) do { _Pragma("unroll") for (int n = 0; n < 2; ++n) _Pragma("unroll") for (int k = 0; k < 2; ++k) dst[n][k] = *(const LAS bf16x8*)(lds + PG8_SB(b, h) + boff + n * 2048 + k * 1024); } while (0)
; #define PG8_MMA(ai, bj, At, Bt) do { __builtin_amdgcn_s_setprio(1); _Pragma("unroll") for (int m = 0; m < 4; ++m) _Pragma("unroll") for (int n = 0; n < 2; ++n) _Pragma("unroll") for (int k = 0; k < 2; ++k) \
;         acc[ai][bj][m][n] = __builtin_amdgcn_mfma_f32_16x16x32_bf16(Bt[n][k], At[m][k], acc[ai][bj][m][n], 0, 0, 0); __builtin_amdgcn_s_setprio(0); } while (0)
; #define PG8_WAIT_V(n) asm volatile("s_waitcnt vmcnt(" #n ")" ::: "memory")
; #define PG8_WAIT_L(n) asm volatile("s_waitcnt lgkmcnt(" #n ")" ::: "memory")
; #define PG8_BAR __builtin_amdgcn_s_barrier()
; #define PG8_SCHED __builtin_amdgcn_sched_barrier(0)
; template <class Epi, class Sched, bool ALIGN_EPI = true, bool SP2 = true>
; __device__ __forceinline__ void gemm_phase(LAS unsigned char* lds, const Gemm g, const Sched& S, const Epi& E) {
;     ...
;             PG8_LDB(B0, 1, 0); PG8_LDB(B1, 1, 1); PG8_SCHED; PG8_LDA(At, 1, 0); PG8_STAGE(PG8_SA(0, 1), a2 + hstep, voffA);
;             PG8_WAIT_V(8); PG8_WAIT_L(0); PG8_BAR; PG8_MMA(0, 0, At, B0); PG8_MMA(0, 1, At, B1); PG8_BAR; PG8_SCHED;
;             PG8_LDA(At, 1, 1); PG8_STAGE(PG8_SB(1, 0), b3, voffB); PG8_STAGE(PG8_SB(1, 1), b3 + hstep, voffB); PG8_STAGE(PG8_SA(1, 0), a3, voffA);
;             PG8_WAIT_V(8); PG8_WAIT_L(0); PG8_BAR; PG8_MMA(1, 0, At, B0); PG8_MMA(1, 1, At, B1); PG8_BAR; PG8_SCHED;
	s_setprio 0
	s_add_i32 s67, 0, 0x18000
	v_add_u32_e32 v146, s67, v160
	s_add_i32 s68, 0, 0x1c000
	ds_read_b128 v[130:133], v146
	ds_read_b128 v[134:137], v146 offset:1024
	ds_read_b128 v[176:179], v146 offset:2048
	ds_read_b128 v[180:183], v146 offset:3072
	v_add_u32_e32 v146, s68, v160
	ds_read_b128 v[184:187], v146
	ds_read_b128 v[188:191], v146 offset:1024
	ds_read_b128 v[192:195], v146 offset:2048
	ds_read_b128 v[196:199], v146 offset:3072
	s_add_u32 s42, s42, 0x100000
	s_addc_u32 s43, s43, 0
	s_mov_b32 m0, s48
	ds_read_b128 v[200:203], v172 offset:32768
	ds_read_b128 v[204:207], v172 offset:33792
	ds_read_b128 v[208:211], v172 offset:34816
	ds_read_b128 v[212:215], v172 offset:35840
	ds_read_b128 v[220:223], v172 offset:36864
	ds_read_b128 v[224:227], v172 offset:37888
	ds_read_b128 v[228:231], v172 offset:38912
	ds_read_b128 v[232:235], v172 offset:39936
	global_load_lds_dwordx4 v138, s[42:43]
	s_mov_b32 m0, s49
	s_nop 0
	global_load_lds_dwordx4 v142, s[42:43]
	s_waitcnt vmcnt(8)
	s_waitcnt lgkmcnt(0)
	s_setprio 1
	s_barrier
	v_mfma_f32_16x16x32_bf16 v[126:129], v[130:133], v[200:203], v[126:129]
	v_mfma_f32_16x16x32_bf16 v[122:125], v[176:179], v[200:203], v[122:125]
	v_mfma_f32_16x16x32_bf16 v[106:109], v[176:179], v[208:211], v[106:109]
	v_mfma_f32_16x16x32_bf16 v[110:113], v[130:133], v[208:211], v[110:113]
	v_mfma_f32_16x16x32_bf16 v[94:97], v[130:133], v[220:223], v[94:97]
	v_mfma_f32_16x16x32_bf16 v[90:93], v[176:179], v[220:223], v[90:93]
	v_mfma_f32_16x16x32_bf16 v[74:77], v[176:179], v[228:231], v[74:77]
	v_mfma_f32_16x16x32_bf16 v[78:81], v[130:133], v[228:231], v[78:81]
	v_mfma_f32_16x16x32_bf16 v[126:129], v[134:137], v[204:207], v[126:129]
	v_mfma_f32_16x16x32_bf16 v[122:125], v[180:183], v[204:207], v[122:125]
	v_mfma_f32_16x16x32_bf16 v[106:109], v[180:183], v[212:215], v[106:109]
	v_mfma_f32_16x16x32_bf16 v[110:113], v[134:137], v[212:215], v[110:113]
	v_mfma_f32_16x16x32_bf16 v[94:97], v[134:137], v[224:227], v[94:97]
	v_mfma_f32_16x16x32_bf16 v[90:93], v[180:183], v[224:227], v[90:93]
	v_mfma_f32_16x16x32_bf16 v[74:77], v[180:183], v[232:235], v[74:77]
	v_mfma_f32_16x16x32_bf16 v[78:81], v[134:137], v[232:235], v[78:81]
	v_mfma_f32_16x16x32_bf16 v[118:121], v[184:187], v[200:203], v[118:121]
	v_mfma_f32_16x16x32_bf16 v[114:117], v[192:195], v[200:203], v[114:117]
	v_mfma_f32_16x16x32_bf16 v[98:101], v[192:195], v[208:211], v[98:101]
	v_mfma_f32_16x16x32_bf16 v[102:105], v[184:187], v[208:211], v[102:105]
	v_mfma_f32_16x16x32_bf16 v[86:89], v[184:187], v[220:223], v[86:89]
	v_mfma_f32_16x16x32_bf16 v[82:85], v[192:195], v[220:223], v[82:85]
	v_mfma_f32_16x16x32_bf16 v[66:69], v[192:195], v[228:231], v[66:69]
	v_mfma_f32_16x16x32_bf16 v[70:73], v[184:187], v[228:231], v[70:73]
	v_mfma_f32_16x16x32_bf16 v[118:121], v[188:191], v[204:207], v[118:121]
	v_mfma_f32_16x16x32_bf16 v[114:117], v[196:199], v[204:207], v[114:117]
	v_mfma_f32_16x16x32_bf16 v[98:101], v[196:199], v[212:215], v[98:101]
	v_mfma_f32_16x16x32_bf16 v[102:105], v[188:191], v[212:215], v[102:105]
	v_mfma_f32_16x16x32_bf16 v[86:89], v[188:191], v[224:227], v[86:89]
	v_mfma_f32_16x16x32_bf16 v[82:85], v[196:199], v[224:227], v[82:85]
	v_mfma_f32_16x16x32_bf16 v[66:69], v[196:199], v[232:235], v[66:69]
	v_mfma_f32_16x16x32_bf16 v[70:73], v[188:191], v[232:235], v[70:73]
	s_barrier
	s_setprio 0
	s_add_i32 s42, s67, s45
	v_lshl_add_u64 v[216:217], v[216:217], 0, s[22:23]
	s_mov_b32 m0, s42
	ds_read_b128 v[200:203], v172 offset:49152
	ds_read_b128 v[204:207], v172 offset:50176
	ds_read_b128 v[208:211], v172 offset:51200
	ds_read_b128 v[212:215], v172 offset:52224
	ds_read_b128 v[220:223], v172 offset:53248
	ds_read_b128 v[224:227], v172 offset:54272
	ds_read_b128 v[228:231], v172 offset:55296
	ds_read_b128 v[232:235], v172 offset:56320
	global_load_lds_dwordx4 v[216:217], off
	s_add_i32 m0, s42, 0x2000
	s_add_u32 s40, s40, 0x100080
	v_lshl_add_u64 v[216:217], v[218:219], 0, s[22:23]
	s_addc_u32 s41, s41, 0
	s_add_i32 s42, s68, s45
	global_load_lds_dwordx4 v[216:217], off
	s_mov_b32 m0, s42
	s_nop 0
	global_load_lds_dwordx4 v140, s[40:41]
	s_add_i32 m0, s42, 0x2000
	s_nop 0
	global_load_lds_dwordx4 v144, s[40:41]
	v_lshl_add_u64 v[216:217], v[236:237], 0, s[22:23]
	s_mov_b32 m0, s54
	s_nop 0
	global_load_lds_dwordx4 v[216:217], off
	v_lshl_add_u64 v[216:217], v[238:239], 0, s[22:23]
	s_mov_b32 m0, s55
	s_nop 0
	global_load_lds_dwordx4 v[216:217], off
	s_waitcnt vmcnt(8)
	s_waitcnt lgkmcnt(0)
	s_setprio 1
	s_barrier
	v_mfma_f32_16x16x32_bf16 v[62:65], v[130:133], v[200:203], v[62:65]
	v_mfma_f32_16x16x32_bf16 v[58:61], v[176:179], v[200:203], v[58:61]
	v_mfma_f32_16x16x32_bf16 v[42:45], v[176:179], v[208:211], v[42:45]
	v_mfma_f32_16x16x32_bf16 v[46:49], v[130:133], v[208:211], v[46:49]
	v_mfma_f32_16x16x32_bf16 v[30:33], v[130:133], v[220:223], v[30:33]
	v_mfma_f32_16x16x32_bf16 v[26:29], v[176:179], v[220:223], v[26:29]
	v_mfma_f32_16x16x32_bf16 v[10:13], v[176:179], v[228:231], v[10:13]
	v_mfma_f32_16x16x32_bf16 v[14:17], v[130:133], v[228:231], v[14:17]
	v_mfma_f32_16x16x32_bf16 v[62:65], v[134:137], v[204:207], v[62:65]
	v_mfma_f32_16x16x32_bf16 v[58:61], v[180:183], v[204:207], v[58:61]
	v_mfma_f32_16x16x32_bf16 v[42:45], v[180:183], v[212:215], v[42:45]
	v_mfma_f32_16x16x32_bf16 v[46:49], v[134:137], v[212:215], v[46:49]
	v_mfma_f32_16x16x32_bf16 v[30:33], v[134:137], v[224:227], v[30:33]
	v_mfma_f32_16x16x32_bf16 v[26:29], v[180:183], v[224:227], v[26:29]
	v_mfma_f32_16x16x32_bf16 v[10:13], v[180:183], v[232:235], v[10:13]
	v_mfma_f32_16x16x32_bf16 v[14:17], v[134:137], v[232:235], v[14:17]
	v_mfma_f32_16x16x32_bf16 v[54:57], v[184:187], v[200:203], v[54:57]
	v_mfma_f32_16x16x32_bf16 v[50:53], v[192:195], v[200:203], v[50:53]
	v_mfma_f32_16x16x32_bf16 v[34:37], v[192:195], v[208:211], v[34:37]
	v_mfma_f32_16x16x32_bf16 v[38:41], v[184:187], v[208:211], v[38:41]
	v_mfma_f32_16x16x32_bf16 v[22:25], v[184:187], v[220:223], v[22:25]
	v_mfma_f32_16x16x32_bf16 v[18:21], v[192:195], v[220:223], v[18:21]
	v_mfma_f32_16x16x32_bf16 v[2:5], v[192:195], v[228:231], v[2:5]
	v_mfma_f32_16x16x32_bf16 v[6:9], v[184:187], v[228:231], v[6:9]
	v_mfma_f32_16x16x32_bf16 v[54:57], v[188:191], v[204:207], v[54:57]
	v_mfma_f32_16x16x32_bf16 v[50:53], v[196:199], v[204:207], v[50:53]
	v_mfma_f32_16x16x32_bf16 v[34:37], v[196:199], v[212:215], v[34:37]
	v_mfma_f32_16x16x32_bf16 v[38:41], v[188:191], v[212:215], v[38:41]
	v_mfma_f32_16x16x32_bf16 v[22:25], v[188:191], v[224:227], v[22:25]
	v_mfma_f32_16x16x32_bf16 v[18:21], v[196:199], v[224:227], v[18:21]
	v_mfma_f32_16x16x32_bf16 v[2:5], v[196:199], v[232:235], v[2:5]
	v_mfma_f32_16x16x32_bf16 v[6:9], v[188:191], v[232:235], v[6:9]
	s_barrier
	s_setprio 0
	s_add_i32 s66, s66, 2
	s_add_u32 s38, s38, 0x100
	s_addc_u32 s39, s39, 0
	s_add_u32 s64, s64, 0x100
	s_addc_u32 s65, s65, 0
	s_cmp_gt_u32 s66, 61
	s_cbranch_scc0 .LBB0_138
	s_and_b64 vcc, exec, s[24:25]
	s_cbranch_vccz .LBB0_141
	s_barrier

; #define PG8_STAGE(bufoff, gbase, voff) do { _Pragma("unroll") for (int _i = 0; _i < 2; ++_i) \
;         __builtin_amdgcn_global_load_lds((const unsigned*)((const char*)(gbase) + (voff)[_i]), (LAS unsigned*)(lds + (bufoff) + ldsw + _i * 8192), 16, 0, 0); } while (0)
; #define PG8_LDA(dst, b, h) do { _Pragma("unroll") for (int m = 0; m < 4; ++m) _Pragma("unroll") for (int k = 0; k < 2; ++k) dst[m][k] = *(const LAS bf16x8*)(lds + PG8_SA(b, h) + aoff + m * 2048 + k * 1024); } while (0)
; #define PG8_LDB(dst, b, h) do { _Pragma("unroll") for (int n = 0; n < 2; ++n) _Pragma("unroll") for (int k = 0; k < 2; ++k) dst[n][k] = *(const LAS bf16x8*)(lds + PG8_SB(b, h) + boff + n * 2048 + k * 1024); } while (0)
; #define PG8_MMA(ai, bj, At, Bt) do { __builtin_amdgcn_s_setprio(1); _Pragma("unroll") for (int m = 0; m < 4; ++m) _Pragma("unroll") for (int n = 0; n < 2; ++n) _Pragma("unroll") for (int k = 0; k < 2; ++k) \
;         acc[ai][bj][m][n] = __builtin_amdgcn_mfma_f32_16x16x32_bf16(Bt[n][k], At[m][k], acc[ai][bj][m][n], 0, 0, 0); __builtin_amdgcn_s_setprio(0); } while (0)
; #define PG8_WAIT_V(n) asm volatile("s_waitcnt vmcnt(" #n ")" ::: "memory")
; #define PG8_WAIT_L(n) asm volatile("s_waitcnt lgkmcnt(" #n ")" ::: "memory")
; #define PG8_BAR __builtin_amdgcn_s_barrier()
; #define PG8_SCHED __builtin_amdgcn_sched_barrier(0)
; template <class Epi, class Sched, bool ALIGN_EPI = true, bool SP2 = true>
; __device__ __forceinline__ void gemm_phase(LAS unsigned char* lds, const Gemm g, const Sched& S, const Epi& E) {
;     ...
;             PG8_LDB(B0, 0, 0); PG8_LDB(B1, 0, 1); PG8_SCHED; PG8_LDA(At, 0, 0); PG8_STAGE(PG8_SA(1, 1), a1 + hstep, voffA);
;             PG8_WAIT_V(8); PG8_WAIT_L(0); PG8_BAR; PG8_MMA(0, 0, At, B0); PG8_MMA(0, 1, At, B1); PG8_BAR; PG8_SCHED;
;             PG8_LDA(At, 0, 1); PG8_STAGE(PG8_SB(0, 0), b2, voffB); PG8_STAGE(PG8_SB(0, 1), b2 + hstep, voffB); PG8_STAGE(PG8_SA(0, 0), a2, voffA);
;             PG8_WAIT_V(8); PG8_WAIT_L(0); PG8_BAR; PG8_MMA(1, 0, At, B0); PG8_MMA(1, 1, At, B1); PG8_BAR; PG8_SCHED;
.LBB0_451:
	ds_read_b128 v[146:149], v152
	ds_read_b128 v[156:159], v152 offset:1024
	ds_read_b128 v[160:163], v152 offset:2048
	ds_read_b128 v[164:167], v152 offset:3072
	ds_read_b128 v[168:171], v153
	ds_read_b128 v[172:175], v153 offset:1024
	ds_read_b128 v[176:179], v153 offset:2048
	ds_read_b128 v[180:183], v153 offset:3072
	s_add_u32 s22, s20, 0xfffc0080
	s_addc_u32 s23, s21, -1
	s_cmp_eq_u32 s49, 12
	s_cselect_b32 s25, s13, s23
	s_cselect_b32 s24, s45, s22
	s_cselect_b32 s23, s11, s48
	s_cselect_b32 s22, s46, s47
	s_add_i32 m0, s19, 0xc000
	ds_read_b128 v[184:187], v154
	ds_read_b128 v[188:191], v154 offset:1024
	ds_read_b128 v[192:195], v154 offset:2048
	ds_read_b128 v[196:199], v154 offset:3072
	ds_read_b128 v[200:203], v154 offset:4096
	ds_read_b128 v[204:207], v154 offset:5120
	ds_read_b128 v[208:211], v154 offset:6144
	ds_read_b128 v[212:215], v154 offset:7168
	global_load_lds_dwordx4 v138, s[20:21]
	s_add_i32 m0, s19, 0xe000
	s_nop 0
	global_load_lds_dwordx4 v140, s[20:21]
	s_waitcnt vmcnt(8)
	s_waitcnt lgkmcnt(0)
	s_setprio 1
	s_barrier
	v_mfma_f32_16x16x32_bf16 v[126:129], v[146:149], v[184:187], v[126:129]
	v_mfma_f32_16x16x32_bf16 v[122:125], v[160:163], v[184:187], v[122:125]
	v_mfma_f32_16x16x32_bf16 v[118:121], v[146:149], v[192:195], v[118:121]
	v_mfma_f32_16x16x32_bf16 v[110:113], v[160:163], v[192:195], v[110:113]
	v_mfma_f32_16x16x32_bf16 v[102:105], v[146:149], v[200:203], v[102:105]
	v_mfma_f32_16x16x32_bf16 v[94:97], v[160:163], v[200:203], v[94:97]
	v_mfma_f32_16x16x32_bf16 v[86:89], v[146:149], v[208:211], v[86:89]
	v_mfma_f32_16x16x32_bf16 v[78:81], v[160:163], v[208:211], v[78:81]
	v_mfma_f32_16x16x32_bf16 v[126:129], v[156:159], v[188:191], v[126:129]
	v_mfma_f32_16x16x32_bf16 v[122:125], v[164:167], v[188:191], v[122:125]
	v_mfma_f32_16x16x32_bf16 v[118:121], v[156:159], v[196:199], v[118:121]
	v_mfma_f32_16x16x32_bf16 v[110:113], v[164:167], v[196:199], v[110:113]
	v_mfma_f32_16x16x32_bf16 v[102:105], v[156:159], v[204:207], v[102:105]
	v_mfma_f32_16x16x32_bf16 v[94:97], v[164:167], v[204:207], v[94:97]
	v_mfma_f32_16x16x32_bf16 v[86:89], v[156:159], v[212:215], v[86:89]
	v_mfma_f32_16x16x32_bf16 v[78:81], v[164:167], v[212:215], v[78:81]
	v_mfma_f32_16x16x32_bf16 v[114:117], v[168:171], v[184:187], v[114:117]
	v_mfma_f32_16x16x32_bf16 v[106:109], v[176:179], v[184:187], v[106:109]
	v_mfma_f32_16x16x32_bf16 v[98:101], v[168:171], v[192:195], v[98:101]
	v_mfma_f32_16x16x32_bf16 v[90:93], v[176:179], v[192:195], v[90:93]
	v_mfma_f32_16x16x32_bf16 v[82:85], v[168:171], v[200:203], v[82:85]
	v_mfma_f32_16x16x32_bf16 v[74:77], v[176:179], v[200:203], v[74:77]
	v_mfma_f32_16x16x32_bf16 v[70:73], v[168:171], v[208:211], v[70:73]
	v_mfma_f32_16x16x32_bf16 v[66:69], v[176:179], v[208:211], v[66:69]
	v_mfma_f32_16x16x32_bf16 v[114:117], v[172:175], v[188:191], v[114:117]
	v_mfma_f32_16x16x32_bf16 v[106:109], v[180:183], v[188:191], v[106:109]
	v_mfma_f32_16x16x32_bf16 v[98:101], v[172:175], v[196:199], v[98:101]
	v_mfma_f32_16x16x32_bf16 v[90:93], v[180:183], v[196:199], v[90:93]
	v_mfma_f32_16x16x32_bf16 v[82:85], v[172:175], v[204:207], v[82:85]
	v_mfma_f32_16x16x32_bf16 v[74:77], v[180:183], v[204:207], v[74:77]
	v_mfma_f32_16x16x32_bf16 v[70:73], v[172:175], v[212:215], v[70:73]
	v_mfma_f32_16x16x32_bf16 v[66:69], v[180:183], v[212:215], v[66:69]
	s_barrier
	s_setprio 0
	s_add_i32 s50, s42, s31
	v_lshl_add_u64 v[216:217], s[22:23], 0, v[132:133]
	s_mov_b32 m0, s50
	ds_read_b128 v[184:187], v154 offset:16384
	ds_read_b128 v[188:191], v154 offset:17408
	ds_read_b128 v[192:195], v154 offset:18432
	ds_read_b128 v[196:199], v154 offset:19456
	ds_read_b128 v[200:203], v154 offset:20480
	ds_read_b128 v[204:207], v154 offset:21504
	ds_read_b128 v[208:211], v154 offset:22528
	ds_read_b128 v[212:215], v154 offset:23552
	global_load_lds_dwordx4 v[216:217], off
	s_add_i32 m0, s50, 0x2000
	s_add_u32 s50, s22, 0x40000
	v_lshl_add_u64 v[218:219], s[22:23], 0, v[136:137]
	s_addc_u32 s51, s23, 0
	s_add_i32 s52, s43, s31
	global_load_lds_dwordx4 v[218:219], off
	s_mov_b32 m0, s52
	v_lshl_add_u64 v[222:223], s[24:25], 0, v[134:135]
	global_load_lds_dwordx4 v132, s[50:51]
	s_add_i32 m0, s52, 0x2000
	s_nop 0
	global_load_lds_dwordx4 v136, s[50:51]
	v_lshl_add_u64 v[220:221], s[24:25], 0, v[130:131]
	s_mov_b32 m0, s19
	s_nop 0
	global_load_lds_dwordx4 v[220:221], off
	s_mov_b32 m0, s33
	s_nop 0
	global_load_lds_dwordx4 v[222:223], off
	s_waitcnt vmcnt(8)
	s_waitcnt lgkmcnt(0)
	s_setprio 1
	s_barrier
	v_mfma_f32_16x16x32_bf16 v[62:65], v[146:149], v[184:187], v[62:65]
	v_mfma_f32_16x16x32_bf16 v[58:61], v[160:163], v[184:187], v[58:61]
	v_mfma_f32_16x16x32_bf16 v[54:57], v[146:149], v[192:195], v[54:57]
	v_mfma_f32_16x16x32_bf16 v[46:49], v[160:163], v[192:195], v[46:49]
	v_mfma_f32_16x16x32_bf16 v[38:41], v[146:149], v[200:203], v[38:41]
	v_mfma_f32_16x16x32_bf16 v[30:33], v[160:163], v[200:203], v[30:33]
	v_mfma_f32_16x16x32_bf16 v[22:25], v[146:149], v[208:211], v[22:25]
	v_mfma_f32_16x16x32_bf16 v[14:17], v[160:163], v[208:211], v[14:17]
	v_mfma_f32_16x16x32_bf16 v[62:65], v[156:159], v[188:191], v[62:65]
	v_mfma_f32_16x16x32_bf16 v[58:61], v[164:167], v[188:191], v[58:61]
	v_mfma_f32_16x16x32_bf16 v[54:57], v[156:159], v[196:199], v[54:57]
	v_mfma_f32_16x16x32_bf16 v[46:49], v[164:167], v[196:199], v[46:49]
	v_mfma_f32_16x16x32_bf16 v[38:41], v[156:159], v[204:207], v[38:41]
	v_mfma_f32_16x16x32_bf16 v[30:33], v[164:167], v[204:207], v[30:33]
	v_mfma_f32_16x16x32_bf16 v[22:25], v[156:159], v[212:215], v[22:25]
	v_mfma_f32_16x16x32_bf16 v[14:17], v[164:167], v[212:215], v[14:17]
	v_mfma_f32_16x16x32_bf16 v[50:53], v[168:171], v[184:187], v[50:53]
	v_mfma_f32_16x16x32_bf16 v[42:45], v[176:179], v[184:187], v[42:45]
	v_mfma_f32_16x16x32_bf16 v[34:37], v[168:171], v[192:195], v[34:37]
	v_mfma_f32_16x16x32_bf16 v[26:29], v[176:179], v[192:195], v[26:29]
	v_mfma_f32_16x16x32_bf16 v[18:21], v[168:171], v[200:203], v[18:21]
	v_mfma_f32_16x16x32_bf16 v[10:13], v[176:179], v[200:203], v[10:13]
	v_mfma_f32_16x16x32_bf16 v[6:9], v[168:171], v[208:211], v[6:9]
	v_mfma_f32_16x16x32_bf16 v[2:5], v[176:179], v[208:211], v[2:5]
	v_mfma_f32_16x16x32_bf16 v[50:53], v[172:175], v[188:191], v[50:53]
	v_mfma_f32_16x16x32_bf16 v[42:45], v[180:183], v[188:191], v[42:45]
	v_mfma_f32_16x16x32_bf16 v[34:37], v[172:175], v[196:199], v[34:37]
	v_mfma_f32_16x16x32_bf16 v[26:29], v[180:183], v[196:199], v[26:29]
	v_mfma_f32_16x16x32_bf16 v[18:21], v[172:175], v[204:207], v[18:21]
	v_mfma_f32_16x16x32_bf16 v[10:13], v[180:183], v[204:207], v[10:13]
	v_mfma_f32_16x16x32_bf16 v[6:9], v[172:175], v[212:215], v[6:9]
	v_mfma_f32_16x16x32_bf16 v[2:5], v[180:183], v[212:215], v[2:5]
	s_barrier
; #define PG8_STAGE(bufoff, gbase, voff) do { _Pragma("unroll") for (int _i = 0; _i < 2; ++_i) \
;         __builtin_amdgcn_global_load_lds((const unsigned*)((const char*)(gbase) + (voff)[_i]), (LAS unsigned*)(lds + (bufoff) + ldsw + _i * 8192), 16, 0, 0); } while (0)
; #define PG8_LDA(dst, b, h) do { _Pragma("unroll") for (int m = 0; m < 4; ++m) _Pragma("unroll") for (int k = 0; k < 2; ++k) dst[m][k] = *(const LAS bf16x8*)(lds + PG8_SA(b, h) + aoff + m * 2048 + k * 1024); } while (0)
; #define PG8_LDB(dst, b, h) do { _Pragma("unroll") for (int n = 0; n < 2; ++n) _Pragma("unroll") for (int k = 0; k < 2; ++k) dst[n][k] = *(const LAS bf16x8*)(lds + PG8_SB(b, h) + boff + n * 2048 + k * 1024); } while (0)
; #define PG8_MMA(ai, bj, At, Bt) do { __builtin_amdgcn_s_setprio(1); _Pragma("unroll") for (int m = 0; m < 4; ++m) _Pragma("unroll") for (int n = 0; n < 2; ++n) _Pragma("unroll") for (int k = 0; k < 2; ++k) \
;         acc[ai][bj][m][n] = __builtin_amdgcn_mfma_f32_16x16x32_bf16(Bt[n][k], At[m][k], acc[ai][bj][m][n], 0, 0, 0); __builtin_amdgcn_s_setprio(0); } while (0)
; #define PG8_WAIT_V(n) asm volatile("s_waitcnt vmcnt(" #n ")" ::: "memory")
; #define PG8_WAIT_L(n) asm volatile("s_waitcnt lgkmcnt(" #n ")" ::: "memory")
; #define PG8_BAR __builtin_amdgcn_s_barrier()
; #define PG8_SCHED __builtin_amdgcn_sched_barrier(0)
; template <class Epi, class Sched, bool ALIGN_EPI = true, bool SP2 = true>
; __device__ __forceinline__ void gemm_phase(LAS unsigned char* lds, const Gemm g, const Sched& S, const Epi& E) {
;     ...
;             PG8_LDB(B0, 1, 0); PG8_LDB(B1, 1, 1); PG8_SCHED; PG8_LDA(At, 1, 0); PG8_STAGE(PG8_SA(0, 1), a2 + hstep, voffA);
;             PG8_WAIT_V(8); PG8_WAIT_L(0); PG8_BAR; PG8_MMA(0, 0, At, B0); PG8_MMA(0, 1, At, B1); PG8_BAR; PG8_SCHED;
;             PG8_LDA(At, 1, 1); PG8_STAGE(PG8_SB(1, 0), b3, voffB); PG8_STAGE(PG8_SB(1, 1), b3 + hstep, voffB); PG8_STAGE(PG8_SA(1, 0), a3, voffA);
;             PG8_WAIT_V(8); PG8_WAIT_L(0); PG8_BAR; PG8_MMA(1, 0, At, B0); PG8_MMA(1, 1, At, B1); PG8_BAR; PG8_SCHED;
	s_setprio 0
	s_add_i32 s50, 0, 0x18000
	v_add_u32_e32 v155, s50, v150
	s_add_i32 s51, 0, 0x1c000
	ds_read_b128 v[146:149], v155
	ds_read_b128 v[156:159], v155 offset:1024
	ds_read_b128 v[160:163], v155 offset:2048
	ds_read_b128 v[164:167], v155 offset:3072
	v_add_u32_e32 v155, s51, v150
	ds_read_b128 v[168:171], v155
	ds_read_b128 v[172:175], v155 offset:1024
	ds_read_b128 v[176:179], v155 offset:2048
	ds_read_b128 v[180:183], v155 offset:3072
	s_add_u32 s24, s24, 0x40000
	s_addc_u32 s25, s25, 0
	s_mov_b32 m0, s34
	ds_read_b128 v[184:187], v154 offset:32768
	ds_read_b128 v[188:191], v154 offset:33792
	ds_read_b128 v[192:195], v154 offset:34816
	ds_read_b128 v[196:199], v154 offset:35840
	ds_read_b128 v[200:203], v154 offset:36864
	ds_read_b128 v[204:207], v154 offset:37888
	ds_read_b128 v[208:211], v154 offset:38912
	ds_read_b128 v[212:215], v154 offset:39936
	global_load_lds_dwordx4 v130, s[24:25]
	s_mov_b32 m0, s35
	s_nop 0
	global_load_lds_dwordx4 v134, s[24:25]
	s_waitcnt vmcnt(8)
	s_waitcnt lgkmcnt(0)
	s_setprio 1
	s_barrier
	v_mfma_f32_16x16x32_bf16 v[126:129], v[146:149], v[184:187], v[126:129]
	v_mfma_f32_16x16x32_bf16 v[122:125], v[160:163], v[184:187], v[122:125]
	v_mfma_f32_16x16x32_bf16 v[118:121], v[146:149], v[192:195], v[118:121]
	v_mfma_f32_16x16x32_bf16 v[110:113], v[160:163], v[192:195], v[110:113]
	v_mfma_f32_16x16x32_bf16 v[102:105], v[146:149], v[200:203], v[102:105]
	v_mfma_f32_16x16x32_bf16 v[94:97], v[160:163], v[200:203], v[94:97]
	v_mfma_f32_16x16x32_bf16 v[86:89], v[146:149], v[208:211], v[86:89]
	v_mfma_f32_16x16x32_bf16 v[78:81], v[160:163], v[208:211], v[78:81]
	v_mfma_f32_16x16x32_bf16 v[126:129], v[156:159], v[188:191], v[126:129]
	v_mfma_f32_16x16x32_bf16 v[122:125], v[164:167], v[188:191], v[122:125]
	v_mfma_f32_16x16x32_bf16 v[118:121], v[156:159], v[196:199], v[118:121]
	v_mfma_f32_16x16x32_bf16 v[110:113], v[164:167], v[196:199], v[110:113]
	v_mfma_f32_16x16x32_bf16 v[102:105], v[156:159], v[204:207], v[102:105]
	v_mfma_f32_16x16x32_bf16 v[94:97], v[164:167], v[204:207], v[94:97]
	v_mfma_f32_16x16x32_bf16 v[86:89], v[156:159], v[212:215], v[86:89]
	v_mfma_f32_16x16x32_bf16 v[78:81], v[164:167], v[212:215], v[78:81]
	v_mfma_f32_16x16x32_bf16 v[114:117], v[168:171], v[184:187], v[114:117]
	v_mfma_f32_16x16x32_bf16 v[106:109], v[176:179], v[184:187], v[106:109]
	v_mfma_f32_16x16x32_bf16 v[98:101], v[168:171], v[192:195], v[98:101]
	v_mfma_f32_16x16x32_bf16 v[90:93], v[176:179], v[192:195], v[90:93]
	v_mfma_f32_16x16x32_bf16 v[82:85], v[168:171], v[200:203], v[82:85]
	v_mfma_f32_16x16x32_bf16 v[74:77], v[176:179], v[200:203], v[74:77]
	v_mfma_f32_16x16x32_bf16 v[70:73], v[168:171], v[208:211], v[70:73]
	v_mfma_f32_16x16x32_bf16 v[66:69], v[176:179], v[208:211], v[66:69]
	v_mfma_f32_16x16x32_bf16 v[114:117], v[172:175], v[188:191], v[114:117]
	v_mfma_f32_16x16x32_bf16 v[106:109], v[180:183], v[188:191], v[106:109]
	v_mfma_f32_16x16x32_bf16 v[98:101], v[172:175], v[196:199], v[98:101]
	v_mfma_f32_16x16x32_bf16 v[90:93], v[180:183], v[196:199], v[90:93]
	v_mfma_f32_16x16x32_bf16 v[82:85], v[172:175], v[204:207], v[82:85]
	v_mfma_f32_16x16x32_bf16 v[74:77], v[180:183], v[204:207], v[74:77]
	v_mfma_f32_16x16x32_bf16 v[70:73], v[172:175], v[212:215], v[70:73]
	v_mfma_f32_16x16x32_bf16 v[66:69], v[180:183], v[212:215], v[66:69]
	s_barrier
	s_setprio 0
	s_add_i32 s24, s50, s31
	v_lshl_add_u64 v[216:217], v[216:217], 0, s[6:7]
	s_mov_b32 m0, s24
	ds_read_b128 v[184:187], v154 offset:49152
	ds_read_b128 v[188:191], v154 offset:50176
	ds_read_b128 v[192:195], v154 offset:51200
	ds_read_b128 v[196:199], v154 offset:52224
	ds_read_b128 v[200:203], v154 offset:53248
	ds_read_b128 v[204:207], v154 offset:54272
	ds_read_b128 v[208:211], v154 offset:55296
	ds_read_b128 v[212:215], v154 offset:56320
	global_load_lds_dwordx4 v[216:217], off
	s_add_i32 m0, s24, 0x2000
	s_add_u32 s22, s22, 0x40080
	v_lshl_add_u64 v[216:217], v[218:219], 0, s[6:7]
	s_addc_u32 s23, s23, 0
	s_add_i32 s24, s51, s31
	global_load_lds_dwordx4 v[216:217], off
	s_mov_b32 m0, s24
	s_nop 0
	global_load_lds_dwordx4 v132, s[22:23]
	s_add_i32 m0, s24, 0x2000
	s_nop 0
	global_load_lds_dwordx4 v136, s[22:23]
	v_lshl_add_u64 v[216:217], v[220:221], 0, s[6:7]
	s_mov_b32 m0, s39
	s_nop 0
	global_load_lds_dwordx4 v[216:217], off
	v_lshl_add_u64 v[216:217], v[222:223], 0, s[6:7]
	s_mov_b32 m0, s40
	s_nop 0
	global_load_lds_dwordx4 v[216:217], off
	s_waitcnt vmcnt(8)
	s_waitcnt lgkmcnt(0)
	s_setprio 1
	s_barrier
	v_mfma_f32_16x16x32_bf16 v[62:65], v[146:149], v[184:187], v[62:65]
	v_mfma_f32_16x16x32_bf16 v[58:61], v[160:163], v[184:187], v[58:61]
	v_mfma_f32_16x16x32_bf16 v[54:57], v[146:149], v[192:195], v[54:57]
	v_mfma_f32_16x16x32_bf16 v[46:49], v[160:163], v[192:195], v[46:49]
	v_mfma_f32_16x16x32_bf16 v[38:41], v[146:149], v[200:203], v[38:41]
	v_mfma_f32_16x16x32_bf16 v[30:33], v[160:163], v[200:203], v[30:33]
	v_mfma_f32_16x16x32_bf16 v[22:25], v[146:149], v[208:211], v[22:25]
	v_mfma_f32_16x16x32_bf16 v[14:17], v[160:163], v[208:211], v[14:17]
	v_mfma_f32_16x16x32_bf16 v[62:65], v[156:159], v[188:191], v[62:65]
	v_mfma_f32_16x16x32_bf16 v[58:61], v[164:167], v[188:191], v[58:61]
	v_mfma_f32_16x16x32_bf16 v[54:57], v[156:159], v[196:199], v[54:57]
	v_mfma_f32_16x16x32_bf16 v[46:49], v[164:167], v[196:199], v[46:49]
	v_mfma_f32_16x16x32_bf16 v[38:41], v[156:159], v[204:207], v[38:41]
	v_mfma_f32_16x16x32_bf16 v[30:33], v[164:167], v[204:207], v[30:33]
	v_mfma_f32_16x16x32_bf16 v[22:25], v[156:159], v[212:215], v[22:25]
	v_mfma_f32_16x16x32_bf16 v[14:17], v[164:167], v[212:215], v[14:17]
	v_mfma_f32_16x16x32_bf16 v[50:53], v[168:171], v[184:187], v[50:53]
	v_mfma_f32_16x16x32_bf16 v[42:45], v[176:179], v[184:187], v[42:45]
	v_mfma_f32_16x16x32_bf16 v[34:37], v[168:171], v[192:195], v[34:37]
	v_mfma_f32_16x16x32_bf16 v[26:29], v[176:179], v[192:195], v[26:29]
	v_mfma_f32_16x16x32_bf16 v[18:21], v[168:171], v[200:203], v[18:21]
	v_mfma_f32_16x16x32_bf16 v[10:13], v[176:179], v[200:203], v[10:13]
	v_mfma_f32_16x16x32_bf16 v[6:9], v[168:171], v[208:211], v[6:9]
	v_mfma_f32_16x16x32_bf16 v[2:5], v[176:179], v[208:211], v[2:5]
	v_mfma_f32_16x16x32_bf16 v[50:53], v[172:175], v[188:191], v[50:53]
	v_mfma_f32_16x16x32_bf16 v[42:45], v[180:183], v[188:191], v[42:45]
	v_mfma_f32_16x16x32_bf16 v[34:37], v[172:175], v[196:199], v[34:37]
	v_mfma_f32_16x16x32_bf16 v[26:29], v[180:183], v[196:199], v[26:29]
	v_mfma_f32_16x16x32_bf16 v[18:21], v[172:175], v[204:207], v[18:21]
	v_mfma_f32_16x16x32_bf16 v[10:13], v[180:183], v[204:207], v[10:13]
	v_mfma_f32_16x16x32_bf16 v[6:9], v[172:175], v[212:215], v[6:9]
	v_mfma_f32_16x16x32_bf16 v[2:5], v[180:183], v[212:215], v[2:5]
	s_barrier
	s_setprio 0
	s_add_i32 s49, s49, 2
	s_add_u32 s20, s20, 0x100
	s_addc_u32 s21, s21, 0
	s_add_u32 s47, s47, 0x100
	s_addc_u32 s48, s48, 0
	s_cmp_gt_u32 s49, 13
	s_cbranch_scc0 .LBB0_451
	s_and_b64 vcc, exec, s[8:9]
	s_cbranch_vccz .LBB0_454
	s_barrier

; #define PG8_STAGE(bufoff, gbase, voff) do { _Pragma("unroll") for (int _i = 0; _i < 2; ++_i) \
;         __builtin_amdgcn_global_load_lds((const unsigned*)((const char*)(gbase) + (voff)[_i]), (LAS unsigned*)(lds + (bufoff) + ldsw + _i * 8192), 16, 0, 0); } while (0)
; #define PG8_LDA(dst, b, h) do { _Pragma("unroll") for (int m = 0; m < 4; ++m) _Pragma("unroll") for (int k = 0; k < 2; ++k) dst[m][k] = *(const LAS bf16x8*)(lds + PG8_SA(b, h) + aoff + m * 2048 + k * 1024); } while (0)
; #define PG8_LDB(dst, b, h) do { _Pragma("unroll") for (int n = 0; n < 2; ++n) _Pragma("unroll") for (int k = 0; k < 2; ++k) dst[n][k] = *(const LAS bf16x8*)(lds + PG8_SB(b, h) + boff + n * 2048 + k * 1024); } while (0)
; #define PG8_MMA(ai, bj, At, Bt) do { __builtin_amdgcn_s_setprio(1); _Pragma("unroll") for (int m = 0; m < 4; ++m) _Pragma("unroll") for (int n = 0; n < 2; ++n) _Pragma("unroll") for (int k = 0; k < 2; ++k) \
;         acc[ai][bj][m][n] = __builtin_amdgcn_mfma_f32_16x16x32_bf16(Bt[n][k], At[m][k], acc[ai][bj][m][n], 0, 0, 0); __builtin_amdgcn_s_setprio(0); } while (0)
; #define PG8_WAIT_V(n) asm volatile("s_waitcnt vmcnt(" #n ")" ::: "memory")
; #define PG8_WAIT_L(n) asm volatile("s_waitcnt lgkmcnt(" #n ")" ::: "memory")
; #define PG8_BAR __builtin_amdgcn_s_barrier()
; #define PG8_SCHED __builtin_amdgcn_sched_barrier(0)
; template <class Epi, class Sched, bool ALIGN_EPI = true, bool SP2 = true>
; __device__ __forceinline__ void gemm_phase(LAS unsigned char* lds, const Gemm g, const Sched& S, const Epi& E) {
;     ...
;             PG8_LDB(B0, 0, 0); PG8_LDB(B1, 0, 1); PG8_SCHED; PG8_LDA(At, 0, 0); PG8_STAGE(PG8_SA(1, 1), a1 + hstep, voffA);
;             PG8_WAIT_V(8); PG8_WAIT_L(0); PG8_BAR; PG8_MMA(0, 0, At, B0); PG8_MMA(0, 1, At, B1); PG8_BAR; PG8_SCHED;
;             PG8_LDA(At, 0, 1); PG8_STAGE(PG8_SB(0, 0), b2, voffB); PG8_STAGE(PG8_SB(0, 1), b2 + hstep, voffB); PG8_STAGE(PG8_SA(0, 0), a2, voffA);
;             PG8_WAIT_V(8); PG8_WAIT_L(0); PG8_BAR; PG8_MMA(1, 0, At, B0); PG8_MMA(1, 1, At, B1); PG8_BAR; PG8_SCHED;
.LBB0_1460:
	ds_read_b128 v[114:117], v221
	ds_read_b128 v[118:121], v221 offset:1024
	ds_read_b128 v[130:133], v221 offset:2048
	ds_read_b128 v[134:137], v221 offset:3072
	ds_read_b128 v[142:145], v222
	ds_read_b128 v[150:153], v222 offset:1024
	ds_read_b128 v[154:157], v222 offset:2048
	ds_read_b128 v[158:161], v222 offset:3072
	s_add_u32 s36, s34, 0xfff80080
	s_addc_u32 s37, s35, -1
	s_cmp_eq_u32 s64, 28
	s_cselect_b32 s39, s25, s37
	s_cselect_b32 s38, s31, s36
	s_cselect_b32 s37, s23, s63
	s_cselect_b32 s36, s61, s62
	s_add_i32 m0, s44, 0xc000
	ds_read_b128 v[162:165], v223
	ds_read_b128 v[166:169], v223 offset:1024
	ds_read_b128 v[170:173], v223 offset:2048
	ds_read_b128 v[174:177], v223 offset:3072
	ds_read_b128 v[178:181], v223 offset:4096
	ds_read_b128 v[182:185], v223 offset:5120
	ds_read_b128 v[186:189], v223 offset:6144
	ds_read_b128 v[190:193], v223 offset:7168
	global_load_lds_dwordx4 v202, s[34:35]
	s_add_i32 m0, s44, 0xe000
	s_nop 0
	global_load_lds_dwordx4 v204, s[34:35]
	s_waitcnt vmcnt(8)
	s_waitcnt lgkmcnt(0)
	s_setprio 1
	s_barrier
	v_mfma_f32_16x16x32_bf16 v[146:149], v[114:117], v[162:165], v[146:149]
	v_mfma_f32_16x16x32_bf16 v[138:141], v[130:133], v[162:165], v[138:141]
	v_mfma_f32_16x16x32_bf16 v[110:113], v[114:117], v[170:173], v[110:113]
	v_mfma_f32_16x16x32_bf16 v[106:109], v[130:133], v[170:173], v[106:109]
	v_mfma_f32_16x16x32_bf16 v[94:97], v[114:117], v[178:181], v[94:97]
	v_mfma_f32_16x16x32_bf16 v[90:93], v[130:133], v[178:181], v[90:93]
	v_mfma_f32_16x16x32_bf16 v[78:81], v[114:117], v[186:189], v[78:81]
	v_mfma_f32_16x16x32_bf16 v[74:77], v[130:133], v[186:189], v[74:77]
	v_mfma_f32_16x16x32_bf16 v[146:149], v[118:121], v[166:169], v[146:149]
	v_mfma_f32_16x16x32_bf16 v[138:141], v[134:137], v[166:169], v[138:141]
	v_mfma_f32_16x16x32_bf16 v[110:113], v[118:121], v[174:177], v[110:113]
	v_mfma_f32_16x16x32_bf16 v[106:109], v[134:137], v[174:177], v[106:109]
	v_mfma_f32_16x16x32_bf16 v[94:97], v[118:121], v[182:185], v[94:97]
	v_mfma_f32_16x16x32_bf16 v[90:93], v[134:137], v[182:185], v[90:93]
	v_mfma_f32_16x16x32_bf16 v[78:81], v[118:121], v[190:193], v[78:81]
	v_mfma_f32_16x16x32_bf16 v[74:77], v[134:137], v[190:193], v[74:77]
	v_mfma_f32_16x16x32_bf16 v[126:129], v[142:145], v[162:165], v[126:129]
	v_mfma_f32_16x16x32_bf16 v[122:125], v[154:157], v[162:165], v[122:125]
	v_mfma_f32_16x16x32_bf16 v[102:105], v[142:145], v[170:173], v[102:105]
	v_mfma_f32_16x16x32_bf16 v[98:101], v[154:157], v[170:173], v[98:101]
	v_mfma_f32_16x16x32_bf16 v[86:89], v[142:145], v[178:181], v[86:89]
	v_mfma_f32_16x16x32_bf16 v[82:85], v[154:157], v[178:181], v[82:85]
	v_mfma_f32_16x16x32_bf16 v[70:73], v[142:145], v[186:189], v[70:73]
	v_mfma_f32_16x16x32_bf16 v[66:69], v[154:157], v[186:189], v[66:69]
	v_mfma_f32_16x16x32_bf16 v[126:129], v[150:153], v[166:169], v[126:129]
	v_mfma_f32_16x16x32_bf16 v[122:125], v[158:161], v[166:169], v[122:125]
	v_mfma_f32_16x16x32_bf16 v[102:105], v[150:153], v[174:177], v[102:105]
	v_mfma_f32_16x16x32_bf16 v[98:101], v[158:161], v[174:177], v[98:101]
	v_mfma_f32_16x16x32_bf16 v[86:89], v[150:153], v[182:185], v[86:89]
	v_mfma_f32_16x16x32_bf16 v[82:85], v[158:161], v[182:185], v[82:85]
	v_mfma_f32_16x16x32_bf16 v[70:73], v[150:153], v[190:193], v[70:73]
	v_mfma_f32_16x16x32_bf16 v[66:69], v[158:161], v[190:193], v[66:69]
	s_barrier
	s_setprio 0
	s_add_i32 s65, s57, s43
	v_lshl_add_u64 v[210:211], s[36:37], 0, v[196:197]
	s_mov_b32 m0, s65
	ds_read_b128 v[162:165], v223 offset:16384
	ds_read_b128 v[166:169], v223 offset:17408
	ds_read_b128 v[170:173], v223 offset:18432
	ds_read_b128 v[174:177], v223 offset:19456
	ds_read_b128 v[178:181], v223 offset:20480
	ds_read_b128 v[182:185], v223 offset:21504
	ds_read_b128 v[186:189], v223 offset:22528
	ds_read_b128 v[190:193], v223 offset:23552
	global_load_lds_dwordx4 v[210:211], off
	s_add_i32 m0, s65, 0x2000
	s_add_u32 s66, s36, 0x80000
	v_lshl_add_u64 v[212:213], s[36:37], 0, v[200:201]
	s_addc_u32 s67, s37, 0
	s_add_i32 s65, s58, s43
	global_load_lds_dwordx4 v[212:213], off
	s_mov_b32 m0, s65
	v_lshl_add_u64 v[216:217], s[38:39], 0, v[198:199]
	global_load_lds_dwordx4 v196, s[66:67]
	s_add_i32 m0, s65, 0x2000
	s_nop 0
	global_load_lds_dwordx4 v200, s[66:67]
	v_lshl_add_u64 v[214:215], s[38:39], 0, v[194:195]
	s_mov_b32 m0, s44
	s_nop 0
	global_load_lds_dwordx4 v[214:215], off
	s_mov_b32 m0, s45
	s_nop 0
	global_load_lds_dwordx4 v[216:217], off
	s_waitcnt vmcnt(8)
	s_waitcnt lgkmcnt(0)
	s_setprio 1
	s_barrier
	v_mfma_f32_16x16x32_bf16 v[62:65], v[114:117], v[162:165], v[62:65]
	v_mfma_f32_16x16x32_bf16 v[58:61], v[130:133], v[162:165], v[58:61]
	v_mfma_f32_16x16x32_bf16 v[46:49], v[114:117], v[170:173], v[46:49]
	v_mfma_f32_16x16x32_bf16 v[42:45], v[130:133], v[170:173], v[42:45]
	v_mfma_f32_16x16x32_bf16 v[30:33], v[114:117], v[178:181], v[30:33]
	v_mfma_f32_16x16x32_bf16 v[26:29], v[130:133], v[178:181], v[26:29]
	v_mfma_f32_16x16x32_bf16 v[14:17], v[114:117], v[186:189], v[14:17]
	v_mfma_f32_16x16x32_bf16 v[10:13], v[130:133], v[186:189], v[10:13]
	v_mfma_f32_16x16x32_bf16 v[62:65], v[118:121], v[166:169], v[62:65]
	v_mfma_f32_16x16x32_bf16 v[58:61], v[134:137], v[166:169], v[58:61]
	v_mfma_f32_16x16x32_bf16 v[46:49], v[118:121], v[174:177], v[46:49]
	v_mfma_f32_16x16x32_bf16 v[42:45], v[134:137], v[174:177], v[42:45]
	v_mfma_f32_16x16x32_bf16 v[30:33], v[118:121], v[182:185], v[30:33]
	v_mfma_f32_16x16x32_bf16 v[26:29], v[134:137], v[182:185], v[26:29]
	v_mfma_f32_16x16x32_bf16 v[14:17], v[118:121], v[190:193], v[14:17]
	v_mfma_f32_16x16x32_bf16 v[10:13], v[134:137], v[190:193], v[10:13]
	v_mfma_f32_16x16x32_bf16 v[54:57], v[142:145], v[162:165], v[54:57]
	v_mfma_f32_16x16x32_bf16 v[50:53], v[154:157], v[162:165], v[50:53]
	v_mfma_f32_16x16x32_bf16 v[38:41], v[142:145], v[170:173], v[38:41]
	v_mfma_f32_16x16x32_bf16 v[34:37], v[154:157], v[170:173], v[34:37]
	v_mfma_f32_16x16x32_bf16 v[22:25], v[142:145], v[178:181], v[22:25]
	v_mfma_f32_16x16x32_bf16 v[18:21], v[154:157], v[178:181], v[18:21]
	v_mfma_f32_16x16x32_bf16 v[6:9], v[142:145], v[186:189], v[6:9]
	v_mfma_f32_16x16x32_bf16 v[2:5], v[154:157], v[186:189], v[2:5]
	v_mfma_f32_16x16x32_bf16 v[54:57], v[150:153], v[166:169], v[54:57]
	v_mfma_f32_16x16x32_bf16 v[50:53], v[158:161], v[166:169], v[50:53]
	v_mfma_f32_16x16x32_bf16 v[38:41], v[150:153], v[174:177], v[38:41]
	v_mfma_f32_16x16x32_bf16 v[34:37], v[158:161], v[174:177], v[34:37]
	v_mfma_f32_16x16x32_bf16 v[22:25], v[150:153], v[182:185], v[22:25]
	v_mfma_f32_16x16x32_bf16 v[18:21], v[158:161], v[182:185], v[18:21]
	v_mfma_f32_16x16x32_bf16 v[6:9], v[150:153], v[190:193], v[6:9]
	v_mfma_f32_16x16x32_bf16 v[2:5], v[158:161], v[190:193], v[2:5]
	s_barrier
; #define PG8_STAGE(bufoff, gbase, voff) do { _Pragma("unroll") for (int _i = 0; _i < 2; ++_i) \
;         __builtin_amdgcn_global_load_lds((const unsigned*)((const char*)(gbase) + (voff)[_i]), (LAS unsigned*)(lds + (bufoff) + ldsw + _i * 8192), 16, 0, 0); } while (0)
; #define PG8_LDA(dst, b, h) do { _Pragma("unroll") for (int m = 0; m < 4; ++m) _Pragma("unroll") for (int k = 0; k < 2; ++k) dst[m][k] = *(const LAS bf16x8*)(lds + PG8_SA(b, h) + aoff + m * 2048 + k * 1024); } while (0)
; #define PG8_LDB(dst, b, h) do { _Pragma("unroll") for (int n = 0; n < 2; ++n) _Pragma("unroll") for (int k = 0; k < 2; ++k) dst[n][k] = *(const LAS bf16x8*)(lds + PG8_SB(b, h) + boff + n * 2048 + k * 1024); } while (0)
; #define PG8_MMA(ai, bj, At, Bt) do { __builtin_amdgcn_s_setprio(1); _Pragma("unroll") for (int m = 0; m < 4; ++m) _Pragma("unroll") for (int n = 0; n < 2; ++n) _Pragma("unroll") for (int k = 0; k < 2; ++k) \
;         acc[ai][bj][m][n] = __builtin_amdgcn_mfma_f32_16x16x32_bf16(Bt[n][k], At[m][k], acc[ai][bj][m][n], 0, 0, 0); __builtin_amdgcn_s_setprio(0); } while (0)
; #define PG8_WAIT_V(n) asm volatile("s_waitcnt vmcnt(" #n ")" ::: "memory")
; #define PG8_WAIT_L(n) asm volatile("s_waitcnt lgkmcnt(" #n ")" ::: "memory")
; #define PG8_BAR __builtin_amdgcn_s_barrier()
; #define PG8_SCHED __builtin_amdgcn_sched_barrier(0)
; template <class Epi, class Sched, bool ALIGN_EPI = true, bool SP2 = true>
; __device__ __forceinline__ void gemm_phase(LAS unsigned char* lds, const Gemm g, const Sched& S, const Epi& E) {
;     ...
;             PG8_LDB(B0, 1, 0); PG8_LDB(B1, 1, 1); PG8_SCHED; PG8_LDA(At, 1, 0); PG8_STAGE(PG8_SA(0, 1), a2 + hstep, voffA);
;             PG8_WAIT_V(8); PG8_WAIT_L(0); PG8_BAR; PG8_MMA(0, 0, At, B0); PG8_MMA(0, 1, At, B1); PG8_BAR; PG8_SCHED;
;             PG8_LDA(At, 1, 1); PG8_STAGE(PG8_SB(1, 0), b3, voffB); PG8_STAGE(PG8_SB(1, 1), b3 + hstep, voffB); PG8_STAGE(PG8_SA(1, 0), a3, voffA);
;             PG8_WAIT_V(8); PG8_WAIT_L(0); PG8_BAR; PG8_MMA(1, 0, At, B0); PG8_MMA(1, 1, At, B1); PG8_BAR; PG8_SCHED;
	s_setprio 0
	s_add_i32 s65, 0, 0x18000
	s_add_i32 s66, 0, 0x1c000
	v_add_u32_e32 v134, s65, v219
	v_add_u32_e32 v158, s66, v219
	ds_read_b128 v[114:117], v134
	ds_read_b128 v[118:121], v134 offset:1024
	ds_read_b128 v[130:133], v134 offset:2048
	ds_read_b128 v[134:137], v134 offset:3072
	ds_read_b128 v[142:145], v158
	ds_read_b128 v[150:153], v158 offset:1024
	ds_read_b128 v[154:157], v158 offset:2048
	ds_read_b128 v[158:161], v158 offset:3072
	s_add_u32 s38, s38, 0x80000
	s_addc_u32 s39, s39, 0
	s_mov_b32 m0, s46
	ds_read_b128 v[162:165], v223 offset:32768
	ds_read_b128 v[166:169], v223 offset:33792
	ds_read_b128 v[170:173], v223 offset:34816
	ds_read_b128 v[174:177], v223 offset:35840
	ds_read_b128 v[178:181], v223 offset:36864
	ds_read_b128 v[182:185], v223 offset:37888
	ds_read_b128 v[186:189], v223 offset:38912
	ds_read_b128 v[190:193], v223 offset:39936
	global_load_lds_dwordx4 v194, s[38:39]
	s_mov_b32 m0, s47
	s_nop 0
	global_load_lds_dwordx4 v198, s[38:39]
	s_waitcnt vmcnt(8)
	s_waitcnt lgkmcnt(0)
	s_setprio 1
	s_barrier
	v_mfma_f32_16x16x32_bf16 v[146:149], v[114:117], v[162:165], v[146:149]
	v_mfma_f32_16x16x32_bf16 v[138:141], v[130:133], v[162:165], v[138:141]
	v_mfma_f32_16x16x32_bf16 v[110:113], v[114:117], v[170:173], v[110:113]
	v_mfma_f32_16x16x32_bf16 v[106:109], v[130:133], v[170:173], v[106:109]
	v_mfma_f32_16x16x32_bf16 v[94:97], v[114:117], v[178:181], v[94:97]
	v_mfma_f32_16x16x32_bf16 v[90:93], v[130:133], v[178:181], v[90:93]
	v_mfma_f32_16x16x32_bf16 v[78:81], v[114:117], v[186:189], v[78:81]
	v_mfma_f32_16x16x32_bf16 v[74:77], v[130:133], v[186:189], v[74:77]
	v_mfma_f32_16x16x32_bf16 v[146:149], v[118:121], v[166:169], v[146:149]
	v_mfma_f32_16x16x32_bf16 v[138:141], v[134:137], v[166:169], v[138:141]
	v_mfma_f32_16x16x32_bf16 v[110:113], v[118:121], v[174:177], v[110:113]
	v_mfma_f32_16x16x32_bf16 v[106:109], v[134:137], v[174:177], v[106:109]
	v_mfma_f32_16x16x32_bf16 v[94:97], v[118:121], v[182:185], v[94:97]
	v_mfma_f32_16x16x32_bf16 v[90:93], v[134:137], v[182:185], v[90:93]
	v_mfma_f32_16x16x32_bf16 v[78:81], v[118:121], v[190:193], v[78:81]
	v_mfma_f32_16x16x32_bf16 v[74:77], v[134:137], v[190:193], v[74:77]
	v_mfma_f32_16x16x32_bf16 v[126:129], v[142:145], v[162:165], v[126:129]
	v_mfma_f32_16x16x32_bf16 v[122:125], v[154:157], v[162:165], v[122:125]
	v_mfma_f32_16x16x32_bf16 v[102:105], v[142:145], v[170:173], v[102:105]
	v_mfma_f32_16x16x32_bf16 v[98:101], v[154:157], v[170:173], v[98:101]
	v_mfma_f32_16x16x32_bf16 v[86:89], v[142:145], v[178:181], v[86:89]
	v_mfma_f32_16x16x32_bf16 v[82:85], v[154:157], v[178:181], v[82:85]
	v_mfma_f32_16x16x32_bf16 v[70:73], v[142:145], v[186:189], v[70:73]
	v_mfma_f32_16x16x32_bf16 v[66:69], v[154:157], v[186:189], v[66:69]
	v_mfma_f32_16x16x32_bf16 v[126:129], v[150:153], v[166:169], v[126:129]
	v_mfma_f32_16x16x32_bf16 v[122:125], v[158:161], v[166:169], v[122:125]
	v_mfma_f32_16x16x32_bf16 v[102:105], v[150:153], v[174:177], v[102:105]
	v_mfma_f32_16x16x32_bf16 v[98:101], v[158:161], v[174:177], v[98:101]
	v_mfma_f32_16x16x32_bf16 v[86:89], v[150:153], v[182:185], v[86:89]
	v_mfma_f32_16x16x32_bf16 v[82:85], v[158:161], v[182:185], v[82:85]
	v_mfma_f32_16x16x32_bf16 v[70:73], v[150:153], v[190:193], v[70:73]
	v_mfma_f32_16x16x32_bf16 v[66:69], v[158:161], v[190:193], v[66:69]
	s_barrier
	s_setprio 0
	s_add_i32 s38, s65, s43
	v_lshl_add_u64 v[210:211], v[210:211], 0, s[12:13]
	s_mov_b32 m0, s38
	ds_read_b128 v[162:165], v223 offset:49152
	ds_read_b128 v[166:169], v223 offset:50176
	ds_read_b128 v[170:173], v223 offset:51200
	ds_read_b128 v[174:177], v223 offset:52224
	ds_read_b128 v[178:181], v223 offset:53248
	ds_read_b128 v[182:185], v223 offset:54272
	ds_read_b128 v[186:189], v223 offset:55296
	ds_read_b128 v[190:193], v223 offset:56320
	global_load_lds_dwordx4 v[210:211], off
	s_add_i32 m0, s38, 0x2000
	s_add_u32 s36, s36, 0x80080
	v_lshl_add_u64 v[210:211], v[212:213], 0, s[12:13]
	s_addc_u32 s37, s37, 0
	s_add_i32 s38, s66, s43
	global_load_lds_dwordx4 v[210:211], off
	s_mov_b32 m0, s38
	s_nop 0
	global_load_lds_dwordx4 v196, s[36:37]
	s_add_i32 m0, s38, 0x2000
	s_nop 0
	global_load_lds_dwordx4 v200, s[36:37]
	v_lshl_add_u64 v[210:211], v[214:215], 0, s[12:13]
	s_mov_b32 m0, s54
	s_nop 0
	global_load_lds_dwordx4 v[210:211], off
	v_lshl_add_u64 v[210:211], v[216:217], 0, s[12:13]
	s_mov_b32 m0, s55
	s_nop 0
	global_load_lds_dwordx4 v[210:211], off
	s_waitcnt vmcnt(8)
	s_waitcnt lgkmcnt(0)
	s_setprio 1
	s_barrier
	v_mfma_f32_16x16x32_bf16 v[62:65], v[114:117], v[162:165], v[62:65]
	v_mfma_f32_16x16x32_bf16 v[58:61], v[130:133], v[162:165], v[58:61]
	v_mfma_f32_16x16x32_bf16 v[46:49], v[114:117], v[170:173], v[46:49]
	v_mfma_f32_16x16x32_bf16 v[42:45], v[130:133], v[170:173], v[42:45]
	v_mfma_f32_16x16x32_bf16 v[30:33], v[114:117], v[178:181], v[30:33]
	v_mfma_f32_16x16x32_bf16 v[26:29], v[130:133], v[178:181], v[26:29]
	v_mfma_f32_16x16x32_bf16 v[14:17], v[114:117], v[186:189], v[14:17]
	v_mfma_f32_16x16x32_bf16 v[10:13], v[130:133], v[186:189], v[10:13]
	v_mfma_f32_16x16x32_bf16 v[62:65], v[118:121], v[166:169], v[62:65]
	v_mfma_f32_16x16x32_bf16 v[58:61], v[134:137], v[166:169], v[58:61]
	v_mfma_f32_16x16x32_bf16 v[46:49], v[118:121], v[174:177], v[46:49]
	v_mfma_f32_16x16x32_bf16 v[42:45], v[134:137], v[174:177], v[42:45]
	v_mfma_f32_16x16x32_bf16 v[30:33], v[118:121], v[182:185], v[30:33]
	v_mfma_f32_16x16x32_bf16 v[26:29], v[134:137], v[182:185], v[26:29]
	v_mfma_f32_16x16x32_bf16 v[14:17], v[118:121], v[190:193], v[14:17]
	v_mfma_f32_16x16x32_bf16 v[10:13], v[134:137], v[190:193], v[10:13]
	v_mfma_f32_16x16x32_bf16 v[54:57], v[142:145], v[162:165], v[54:57]
	v_mfma_f32_16x16x32_bf16 v[50:53], v[154:157], v[162:165], v[50:53]
	v_mfma_f32_16x16x32_bf16 v[38:41], v[142:145], v[170:173], v[38:41]
	v_mfma_f32_16x16x32_bf16 v[34:37], v[154:157], v[170:173], v[34:37]
	v_mfma_f32_16x16x32_bf16 v[22:25], v[142:145], v[178:181], v[22:25]
	v_mfma_f32_16x16x32_bf16 v[18:21], v[154:157], v[178:181], v[18:21]
	v_mfma_f32_16x16x32_bf16 v[6:9], v[142:145], v[186:189], v[6:9]
	v_mfma_f32_16x16x32_bf16 v[2:5], v[154:157], v[186:189], v[2:5]
	v_mfma_f32_16x16x32_bf16 v[54:57], v[150:153], v[166:169], v[54:57]
	v_mfma_f32_16x16x32_bf16 v[50:53], v[158:161], v[166:169], v[50:53]
	v_mfma_f32_16x16x32_bf16 v[38:41], v[150:153], v[174:177], v[38:41]
	v_mfma_f32_16x16x32_bf16 v[34:37], v[158:161], v[174:177], v[34:37]
	v_mfma_f32_16x16x32_bf16 v[22:25], v[150:153], v[182:185], v[22:25]
	v_mfma_f32_16x16x32_bf16 v[18:21], v[158:161], v[182:185], v[18:21]
	v_mfma_f32_16x16x32_bf16 v[6:9], v[150:153], v[190:193], v[6:9]
	v_mfma_f32_16x16x32_bf16 v[2:5], v[158:161], v[190:193], v[2:5]
	s_barrier
	s_setprio 0
	s_add_i32 s64, s64, 2
	s_add_u32 s34, s34, 0x100
	s_addc_u32 s35, s35, 0
	s_add_u32 s62, s62, 0x100
	s_addc_u32 s63, s63, 0
	s_cmp_gt_u32 s64, 29
	s_cbranch_scc0 .LBB0_1460
	s_and_b64 vcc, exec, s[14:15]
	s_cbranch_vccz .LBB0_1463
	s_barrier

; #define PG8_STAGE(bufoff, gbase, voff) do { _Pragma("unroll") for (int _i = 0; _i < 2; ++_i) \
;         __builtin_amdgcn_global_load_lds((const unsigned*)((const char*)(gbase) + (voff)[_i]), (LAS unsigned*)(lds + (bufoff) + ldsw + _i * 8192), 16, 0, 0); } while (0)
; #define PG8_LDA(dst, b, h) do { _Pragma("unroll") for (int m = 0; m < 4; ++m) _Pragma("unroll") for (int k = 0; k < 2; ++k) dst[m][k] = *(const LAS bf16x8*)(lds + PG8_SA(b, h) + aoff + m * 2048 + k * 1024); } while (0)
; #define PG8_LDB(dst, b, h) do { _Pragma("unroll") for (int n = 0; n < 2; ++n) _Pragma("unroll") for (int k = 0; k < 2; ++k) dst[n][k] = *(const LAS bf16x8*)(lds + PG8_SB(b, h) + boff + n * 2048 + k * 1024); } while (0)
; #define PG8_MMA(ai, bj, At, Bt) do { __builtin_amdgcn_s_setprio(1); _Pragma("unroll") for (int m = 0; m < 4; ++m) _Pragma("unroll") for (int n = 0; n < 2; ++n) _Pragma("unroll") for (int k = 0; k < 2; ++k) \
;         acc[ai][bj][m][n] = __builtin_amdgcn_mfma_f32_16x16x32_bf16(Bt[n][k], At[m][k], acc[ai][bj][m][n], 0, 0, 0); __builtin_amdgcn_s_setprio(0); } while (0)
; #define PG8_WAIT_V(n) asm volatile("s_waitcnt vmcnt(" #n ")" ::: "memory")
; #define PG8_WAIT_L(n) asm volatile("s_waitcnt lgkmcnt(" #n ")" ::: "memory")
; #define PG8_BAR __builtin_amdgcn_s_barrier()
; #define PG8_SCHED __builtin_amdgcn_sched_barrier(0)
; template <class Epi, class Sched, bool ALIGN_EPI = true, bool SP2 = true>
; __device__ __forceinline__ void gemm_phase(LAS unsigned char* lds, const Gemm g, const Sched& S, const Epi& E) {
;     ...
;             PG8_LDB(B0, 0, 0); PG8_LDB(B1, 0, 1); PG8_SCHED; PG8_LDA(At, 0, 0); PG8_STAGE(PG8_SA(1, 1), a1 + hstep, voffA);
;             PG8_WAIT_V(8); PG8_WAIT_L(0); PG8_BAR; PG8_MMA(0, 0, At, B0); PG8_MMA(0, 1, At, B1); PG8_BAR; PG8_SCHED;
;             PG8_LDA(At, 0, 1); PG8_STAGE(PG8_SB(0, 0), b2, voffB); PG8_STAGE(PG8_SB(0, 1), b2 + hstep, voffB); PG8_STAGE(PG8_SA(0, 0), a2, voffA);
;             PG8_WAIT_V(8); PG8_WAIT_L(0); PG8_BAR; PG8_MMA(1, 0, At, B0); PG8_MMA(1, 1, At, B1); PG8_BAR; PG8_SCHED;
.LBB0_1639:
	ds_read_b128 v[130:133], v203
	ds_read_b128 v[134:137], v203 offset:1024
	ds_read_b128 v[138:141], v203 offset:2048
	ds_read_b128 v[142:145], v203 offset:3072
	ds_read_b128 v[146:149], v204
	ds_read_b128 v[150:153], v204 offset:1024
	ds_read_b128 v[154:157], v204 offset:2048
	ds_read_b128 v[158:161], v204 offset:3072
	s_add_u32 s54, s52, 0xfff00080
	s_addc_u32 s55, s53, -1
	s_cmp_eq_u32 s74, 60
	s_cselect_b32 s57, s43, s55
	s_cselect_b32 s56, s49, s54
	s_cselect_b32 s55, s41, s73
	s_cselect_b32 s54, s71, s72
	s_add_i32 m0, s51, 0xc000
	ds_read_b128 v[162:165], v205
	ds_read_b128 v[166:169], v205 offset:1024
	ds_read_b128 v[170:173], v205 offset:2048
	ds_read_b128 v[174:177], v205 offset:3072
	ds_read_b128 v[194:197], v205 offset:4096
	ds_read_b128 v[208:211], v205 offset:5120
	ds_read_b128 v[212:215], v205 offset:6144
	ds_read_b128 v[216:219], v205 offset:7168
	global_load_lds_dwordx4 v186, s[52:53]
	s_add_i32 m0, s51, 0xe000
	s_nop 0
	global_load_lds_dwordx4 v188, s[52:53]
	s_waitcnt vmcnt(8)
	s_waitcnt lgkmcnt(0)
	s_setprio 1
	s_barrier
	v_mfma_f32_16x16x32_bf16 v[126:129], v[130:133], v[162:165], v[126:129]
	v_mfma_f32_16x16x32_bf16 v[122:125], v[138:141], v[162:165], v[122:125]
	v_mfma_f32_16x16x32_bf16 v[110:113], v[130:133], v[170:173], v[110:113]
	v_mfma_f32_16x16x32_bf16 v[106:109], v[138:141], v[170:173], v[106:109]
	v_mfma_f32_16x16x32_bf16 v[94:97], v[130:133], v[194:197], v[94:97]
	v_mfma_f32_16x16x32_bf16 v[90:93], v[138:141], v[194:197], v[90:93]
	v_mfma_f32_16x16x32_bf16 v[78:81], v[130:133], v[212:215], v[78:81]
	v_mfma_f32_16x16x32_bf16 v[74:77], v[138:141], v[212:215], v[74:77]
	v_mfma_f32_16x16x32_bf16 v[126:129], v[134:137], v[166:169], v[126:129]
	v_mfma_f32_16x16x32_bf16 v[122:125], v[142:145], v[166:169], v[122:125]
	v_mfma_f32_16x16x32_bf16 v[110:113], v[134:137], v[174:177], v[110:113]
	v_mfma_f32_16x16x32_bf16 v[106:109], v[142:145], v[174:177], v[106:109]
	v_mfma_f32_16x16x32_bf16 v[94:97], v[134:137], v[208:211], v[94:97]
	v_mfma_f32_16x16x32_bf16 v[90:93], v[142:145], v[208:211], v[90:93]
	v_mfma_f32_16x16x32_bf16 v[78:81], v[134:137], v[216:219], v[78:81]
	v_mfma_f32_16x16x32_bf16 v[74:77], v[142:145], v[216:219], v[74:77]
	v_mfma_f32_16x16x32_bf16 v[118:121], v[146:149], v[162:165], v[118:121]
	v_mfma_f32_16x16x32_bf16 v[114:117], v[154:157], v[162:165], v[114:117]
	v_mfma_f32_16x16x32_bf16 v[102:105], v[146:149], v[170:173], v[102:105]
	v_mfma_f32_16x16x32_bf16 v[98:101], v[154:157], v[170:173], v[98:101]
	v_mfma_f32_16x16x32_bf16 v[86:89], v[146:149], v[194:197], v[86:89]
	v_mfma_f32_16x16x32_bf16 v[82:85], v[154:157], v[194:197], v[82:85]
	v_mfma_f32_16x16x32_bf16 v[70:73], v[146:149], v[212:215], v[70:73]
	v_mfma_f32_16x16x32_bf16 v[66:69], v[154:157], v[212:215], v[66:69]
	v_mfma_f32_16x16x32_bf16 v[118:121], v[150:153], v[166:169], v[118:121]
	v_mfma_f32_16x16x32_bf16 v[114:117], v[158:161], v[166:169], v[114:117]
	v_mfma_f32_16x16x32_bf16 v[102:105], v[150:153], v[174:177], v[102:105]
	v_mfma_f32_16x16x32_bf16 v[98:101], v[158:161], v[174:177], v[98:101]
	v_mfma_f32_16x16x32_bf16 v[86:89], v[150:153], v[208:211], v[86:89]
	v_mfma_f32_16x16x32_bf16 v[82:85], v[158:161], v[208:211], v[82:85]
	v_mfma_f32_16x16x32_bf16 v[70:73], v[150:153], v[216:219], v[70:73]
	v_mfma_f32_16x16x32_bf16 v[66:69], v[158:161], v[216:219], v[66:69]
	s_barrier
	s_setprio 0
	s_add_i32 s75, s66, s33
	v_lshl_add_u64 v[198:199], s[54:55], 0, v[180:181]
	s_mov_b32 m0, s75
	ds_read_b128 v[162:165], v205 offset:16384
	ds_read_b128 v[166:169], v205 offset:17408
	ds_read_b128 v[170:173], v205 offset:18432
	ds_read_b128 v[174:177], v205 offset:19456
	ds_read_b128 v[194:197], v205 offset:20480
	ds_read_b128 v[208:211], v205 offset:21504
	ds_read_b128 v[212:215], v205 offset:22528
	ds_read_b128 v[216:219], v205 offset:23552
	global_load_lds_dwordx4 v[198:199], off
	s_add_i32 m0, s75, 0x2000
	s_add_u32 s76, s54, 0x100000
	v_lshl_add_u64 v[220:221], s[54:55], 0, v[184:185]
	s_addc_u32 s77, s55, 0
	s_add_i32 s75, s67, s33
	global_load_lds_dwordx4 v[220:221], off
	s_mov_b32 m0, s75
	v_lshl_add_u64 v[224:225], s[56:57], 0, v[182:183]
	global_load_lds_dwordx4 v180, s[76:77]
	s_add_i32 m0, s75, 0x2000
	s_nop 0
	global_load_lds_dwordx4 v184, s[76:77]
	v_lshl_add_u64 v[222:223], s[56:57], 0, v[178:179]
	s_mov_b32 m0, s51
	s_nop 0
	global_load_lds_dwordx4 v[222:223], off
	s_mov_b32 m0, s58
	s_nop 0
	global_load_lds_dwordx4 v[224:225], off
	s_waitcnt vmcnt(8)
	s_waitcnt lgkmcnt(0)
	s_setprio 1
	s_barrier
	v_mfma_f32_16x16x32_bf16 v[62:65], v[130:133], v[162:165], v[62:65]
	v_mfma_f32_16x16x32_bf16 v[58:61], v[138:141], v[162:165], v[58:61]
	v_mfma_f32_16x16x32_bf16 v[46:49], v[130:133], v[170:173], v[46:49]
	v_mfma_f32_16x16x32_bf16 v[42:45], v[138:141], v[170:173], v[42:45]
	v_mfma_f32_16x16x32_bf16 v[30:33], v[130:133], v[194:197], v[30:33]
	v_mfma_f32_16x16x32_bf16 v[26:29], v[138:141], v[194:197], v[26:29]
	v_mfma_f32_16x16x32_bf16 v[14:17], v[130:133], v[212:215], v[14:17]
	v_mfma_f32_16x16x32_bf16 v[10:13], v[138:141], v[212:215], v[10:13]
	v_mfma_f32_16x16x32_bf16 v[62:65], v[134:137], v[166:169], v[62:65]
	v_mfma_f32_16x16x32_bf16 v[58:61], v[142:145], v[166:169], v[58:61]
	v_mfma_f32_16x16x32_bf16 v[46:49], v[134:137], v[174:177], v[46:49]
	v_mfma_f32_16x16x32_bf16 v[42:45], v[142:145], v[174:177], v[42:45]
	v_mfma_f32_16x16x32_bf16 v[30:33], v[134:137], v[208:211], v[30:33]
	v_mfma_f32_16x16x32_bf16 v[26:29], v[142:145], v[208:211], v[26:29]
	v_mfma_f32_16x16x32_bf16 v[14:17], v[134:137], v[216:219], v[14:17]
	v_mfma_f32_16x16x32_bf16 v[10:13], v[142:145], v[216:219], v[10:13]
	v_mfma_f32_16x16x32_bf16 v[54:57], v[146:149], v[162:165], v[54:57]
	v_mfma_f32_16x16x32_bf16 v[50:53], v[154:157], v[162:165], v[50:53]
	v_mfma_f32_16x16x32_bf16 v[38:41], v[146:149], v[170:173], v[38:41]
	v_mfma_f32_16x16x32_bf16 v[34:37], v[154:157], v[170:173], v[34:37]
	v_mfma_f32_16x16x32_bf16 v[22:25], v[146:149], v[194:197], v[22:25]
	v_mfma_f32_16x16x32_bf16 v[18:21], v[154:157], v[194:197], v[18:21]
	v_mfma_f32_16x16x32_bf16 v[6:9], v[146:149], v[212:215], v[6:9]
	v_mfma_f32_16x16x32_bf16 v[2:5], v[154:157], v[212:215], v[2:5]
	v_mfma_f32_16x16x32_bf16 v[54:57], v[150:153], v[166:169], v[54:57]
	v_mfma_f32_16x16x32_bf16 v[50:53], v[158:161], v[166:169], v[50:53]
	v_mfma_f32_16x16x32_bf16 v[38:41], v[150:153], v[174:177], v[38:41]
	v_mfma_f32_16x16x32_bf16 v[34:37], v[158:161], v[174:177], v[34:37]
	v_mfma_f32_16x16x32_bf16 v[22:25], v[150:153], v[208:211], v[22:25]
	v_mfma_f32_16x16x32_bf16 v[18:21], v[158:161], v[208:211], v[18:21]
	v_mfma_f32_16x16x32_bf16 v[6:9], v[150:153], v[216:219], v[6:9]
	v_mfma_f32_16x16x32_bf16 v[2:5], v[158:161], v[216:219], v[2:5]
	s_barrier
; #define PG8_STAGE(bufoff, gbase, voff) do { _Pragma("unroll") for (int _i = 0; _i < 2; ++_i) \
;         __builtin_amdgcn_global_load_lds((const unsigned*)((const char*)(gbase) + (voff)[_i]), (LAS unsigned*)(lds + (bufoff) + ldsw + _i * 8192), 16, 0, 0); } while (0)
; #define PG8_LDA(dst, b, h) do { _Pragma("unroll") for (int m = 0; m < 4; ++m) _Pragma("unroll") for (int k = 0; k < 2; ++k) dst[m][k] = *(const LAS bf16x8*)(lds + PG8_SA(b, h) + aoff + m * 2048 + k * 1024); } while (0)
; #define PG8_LDB(dst, b, h) do { _Pragma("unroll") for (int n = 0; n < 2; ++n) _Pragma("unroll") for (int k = 0; k < 2; ++k) dst[n][k] = *(const LAS bf16x8*)(lds + PG8_SB(b, h) + boff + n * 2048 + k * 1024); } while (0)
; #define PG8_MMA(ai, bj, At, Bt) do { __builtin_amdgcn_s_setprio(1); _Pragma("unroll") for (int m = 0; m < 4; ++m) _Pragma("unroll") for (int n = 0; n < 2; ++n) _Pragma("unroll") for (int k = 0; k < 2; ++k) \
;         acc[ai][bj][m][n] = __builtin_amdgcn_mfma_f32_16x16x32_bf16(Bt[n][k], At[m][k], acc[ai][bj][m][n], 0, 0, 0); __builtin_amdgcn_s_setprio(0); } while (0)
; #define PG8_WAIT_V(n) asm volatile("s_waitcnt vmcnt(" #n ")" ::: "memory")
; #define PG8_WAIT_L(n) asm volatile("s_waitcnt lgkmcnt(" #n ")" ::: "memory")
; #define PG8_BAR __builtin_amdgcn_s_barrier()
; #define PG8_SCHED __builtin_amdgcn_sched_barrier(0)
; template <class Epi, class Sched, bool ALIGN_EPI = true, bool SP2 = true>
; __device__ __forceinline__ void gemm_phase(LAS unsigned char* lds, const Gemm g, const Sched& S, const Epi& E) {
;     ...
;             PG8_LDB(B0, 1, 0); PG8_LDB(B1, 1, 1); PG8_SCHED; PG8_LDA(At, 1, 0); PG8_STAGE(PG8_SA(0, 1), a2 + hstep, voffA);
;             PG8_WAIT_V(8); PG8_WAIT_L(0); PG8_BAR; PG8_MMA(0, 0, At, B0); PG8_MMA(0, 1, At, B1); PG8_BAR; PG8_SCHED;
;             PG8_LDA(At, 1, 1); PG8_STAGE(PG8_SB(1, 0), b3, voffB); PG8_STAGE(PG8_SB(1, 1), b3 + hstep, voffB); PG8_STAGE(PG8_SA(1, 0), a3, voffA);
;             PG8_WAIT_V(8); PG8_WAIT_L(0); PG8_BAR; PG8_MMA(1, 0, At, B0); PG8_MMA(1, 1, At, B1); PG8_BAR; PG8_SCHED;
	s_setprio 0
	s_add_i32 s75, 0, 0x18000
	s_add_i32 s76, 0, 0x1c000
	v_add_u32_e32 v142, s75, v201
	v_add_u32_e32 v158, s76, v201
	ds_read_b128 v[130:133], v142
	ds_read_b128 v[134:137], v142 offset:1024
	ds_read_b128 v[138:141], v142 offset:2048
	ds_read_b128 v[142:145], v142 offset:3072
	ds_read_b128 v[146:149], v158
	ds_read_b128 v[150:153], v158 offset:1024
	ds_read_b128 v[154:157], v158 offset:2048
	ds_read_b128 v[158:161], v158 offset:3072
	s_add_u32 s56, s56, 0x100000
	s_addc_u32 s57, s57, 0
	s_mov_b32 m0, s59
	ds_read_b128 v[162:165], v205 offset:32768
	ds_read_b128 v[166:169], v205 offset:33792
	ds_read_b128 v[170:173], v205 offset:34816
	ds_read_b128 v[174:177], v205 offset:35840
	ds_read_b128 v[194:197], v205 offset:36864
	ds_read_b128 v[208:211], v205 offset:37888
	ds_read_b128 v[212:215], v205 offset:38912
	ds_read_b128 v[216:219], v205 offset:39936
	global_load_lds_dwordx4 v178, s[56:57]
	s_mov_b32 m0, s60
	s_nop 0
	global_load_lds_dwordx4 v182, s[56:57]
	s_waitcnt vmcnt(8)
	s_waitcnt lgkmcnt(0)
	s_setprio 1
	s_barrier
	v_mfma_f32_16x16x32_bf16 v[126:129], v[130:133], v[162:165], v[126:129]
	v_mfma_f32_16x16x32_bf16 v[122:125], v[138:141], v[162:165], v[122:125]
	v_mfma_f32_16x16x32_bf16 v[110:113], v[130:133], v[170:173], v[110:113]
	v_mfma_f32_16x16x32_bf16 v[106:109], v[138:141], v[170:173], v[106:109]
	v_mfma_f32_16x16x32_bf16 v[94:97], v[130:133], v[194:197], v[94:97]
	v_mfma_f32_16x16x32_bf16 v[90:93], v[138:141], v[194:197], v[90:93]
	v_mfma_f32_16x16x32_bf16 v[78:81], v[130:133], v[212:215], v[78:81]
	v_mfma_f32_16x16x32_bf16 v[74:77], v[138:141], v[212:215], v[74:77]
	v_mfma_f32_16x16x32_bf16 v[126:129], v[134:137], v[166:169], v[126:129]
	v_mfma_f32_16x16x32_bf16 v[122:125], v[142:145], v[166:169], v[122:125]
	v_mfma_f32_16x16x32_bf16 v[110:113], v[134:137], v[174:177], v[110:113]
	v_mfma_f32_16x16x32_bf16 v[106:109], v[142:145], v[174:177], v[106:109]
	v_mfma_f32_16x16x32_bf16 v[94:97], v[134:137], v[208:211], v[94:97]
	v_mfma_f32_16x16x32_bf16 v[90:93], v[142:145], v[208:211], v[90:93]
	v_mfma_f32_16x16x32_bf16 v[78:81], v[134:137], v[216:219], v[78:81]
	v_mfma_f32_16x16x32_bf16 v[74:77], v[142:145], v[216:219], v[74:77]
	v_mfma_f32_16x16x32_bf16 v[118:121], v[146:149], v[162:165], v[118:121]
	v_mfma_f32_16x16x32_bf16 v[114:117], v[154:157], v[162:165], v[114:117]
	v_mfma_f32_16x16x32_bf16 v[102:105], v[146:149], v[170:173], v[102:105]
	v_mfma_f32_16x16x32_bf16 v[98:101], v[154:157], v[170:173], v[98:101]
	v_mfma_f32_16x16x32_bf16 v[86:89], v[146:149], v[194:197], v[86:89]
	v_mfma_f32_16x16x32_bf16 v[82:85], v[154:157], v[194:197], v[82:85]
	v_mfma_f32_16x16x32_bf16 v[70:73], v[146:149], v[212:215], v[70:73]
	v_mfma_f32_16x16x32_bf16 v[66:69], v[154:157], v[212:215], v[66:69]
	v_mfma_f32_16x16x32_bf16 v[118:121], v[150:153], v[166:169], v[118:121]
	v_mfma_f32_16x16x32_bf16 v[114:117], v[158:161], v[166:169], v[114:117]
	v_mfma_f32_16x16x32_bf16 v[102:105], v[150:153], v[174:177], v[102:105]
	v_mfma_f32_16x16x32_bf16 v[98:101], v[158:161], v[174:177], v[98:101]
	v_mfma_f32_16x16x32_bf16 v[86:89], v[150:153], v[208:211], v[86:89]
	v_mfma_f32_16x16x32_bf16 v[82:85], v[158:161], v[208:211], v[82:85]
	v_mfma_f32_16x16x32_bf16 v[70:73], v[150:153], v[216:219], v[70:73]
	v_mfma_f32_16x16x32_bf16 v[66:69], v[158:161], v[216:219], v[66:69]
	s_barrier
	s_setprio 0
	s_add_i32 s56, s75, s33
	v_lshl_add_u64 v[198:199], v[198:199], 0, s[22:23]
	s_mov_b32 m0, s56
	ds_read_b128 v[162:165], v205 offset:49152
	ds_read_b128 v[166:169], v205 offset:50176
	ds_read_b128 v[170:173], v205 offset:51200
	ds_read_b128 v[174:177], v205 offset:52224
	ds_read_b128 v[194:197], v205 offset:53248
	ds_read_b128 v[208:211], v205 offset:54272
	ds_read_b128 v[212:215], v205 offset:55296
	ds_read_b128 v[216:219], v205 offset:56320
	global_load_lds_dwordx4 v[198:199], off
	s_add_i32 m0, s56, 0x2000
	s_add_u32 s54, s54, 0x100080
	v_lshl_add_u64 v[198:199], v[220:221], 0, s[22:23]
	s_addc_u32 s55, s55, 0
	s_add_i32 s56, s76, s33
	global_load_lds_dwordx4 v[198:199], off
	s_mov_b32 m0, s56
	s_nop 0
	global_load_lds_dwordx4 v180, s[54:55]
	s_add_i32 m0, s56, 0x2000
	s_nop 0
	global_load_lds_dwordx4 v184, s[54:55]
	v_lshl_add_u64 v[198:199], v[222:223], 0, s[22:23]
	s_mov_b32 m0, s62
	s_nop 0
	global_load_lds_dwordx4 v[198:199], off
	v_lshl_add_u64 v[198:199], v[224:225], 0, s[22:23]
	s_mov_b32 m0, s63
	s_nop 0
	global_load_lds_dwordx4 v[198:199], off
	s_waitcnt vmcnt(8)
	s_waitcnt lgkmcnt(0)
	s_setprio 1
	s_barrier
	v_mfma_f32_16x16x32_bf16 v[62:65], v[130:133], v[162:165], v[62:65]
	v_mfma_f32_16x16x32_bf16 v[58:61], v[138:141], v[162:165], v[58:61]
	v_mfma_f32_16x16x32_bf16 v[46:49], v[130:133], v[170:173], v[46:49]
	v_mfma_f32_16x16x32_bf16 v[42:45], v[138:141], v[170:173], v[42:45]
	v_mfma_f32_16x16x32_bf16 v[30:33], v[130:133], v[194:197], v[30:33]
	v_mfma_f32_16x16x32_bf16 v[26:29], v[138:141], v[194:197], v[26:29]
	v_mfma_f32_16x16x32_bf16 v[14:17], v[130:133], v[212:215], v[14:17]
	v_mfma_f32_16x16x32_bf16 v[10:13], v[138:141], v[212:215], v[10:13]
	v_mfma_f32_16x16x32_bf16 v[62:65], v[134:137], v[166:169], v[62:65]
	v_mfma_f32_16x16x32_bf16 v[58:61], v[142:145], v[166:169], v[58:61]
	v_mfma_f32_16x16x32_bf16 v[46:49], v[134:137], v[174:177], v[46:49]
	v_mfma_f32_16x16x32_bf16 v[42:45], v[142:145], v[174:177], v[42:45]
	v_mfma_f32_16x16x32_bf16 v[30:33], v[134:137], v[208:211], v[30:33]
	v_mfma_f32_16x16x32_bf16 v[26:29], v[142:145], v[208:211], v[26:29]
	v_mfma_f32_16x16x32_bf16 v[14:17], v[134:137], v[216:219], v[14:17]
	v_mfma_f32_16x16x32_bf16 v[10:13], v[142:145], v[216:219], v[10:13]
	v_mfma_f32_16x16x32_bf16 v[54:57], v[146:149], v[162:165], v[54:57]
	v_mfma_f32_16x16x32_bf16 v[50:53], v[154:157], v[162:165], v[50:53]
	v_mfma_f32_16x16x32_bf16 v[38:41], v[146:149], v[170:173], v[38:41]
	v_mfma_f32_16x16x32_bf16 v[34:37], v[154:157], v[170:173], v[34:37]
	v_mfma_f32_16x16x32_bf16 v[22:25], v[146:149], v[194:197], v[22:25]
	v_mfma_f32_16x16x32_bf16 v[18:21], v[154:157], v[194:197], v[18:21]
	v_mfma_f32_16x16x32_bf16 v[6:9], v[146:149], v[212:215], v[6:9]
	v_mfma_f32_16x16x32_bf16 v[2:5], v[154:157], v[212:215], v[2:5]
	v_mfma_f32_16x16x32_bf16 v[54:57], v[150:153], v[166:169], v[54:57]
	v_mfma_f32_16x16x32_bf16 v[50:53], v[158:161], v[166:169], v[50:53]
	v_mfma_f32_16x16x32_bf16 v[38:41], v[150:153], v[174:177], v[38:41]
	v_mfma_f32_16x16x32_bf16 v[34:37], v[158:161], v[174:177], v[34:37]
	v_mfma_f32_16x16x32_bf16 v[22:25], v[150:153], v[208:211], v[22:25]
	v_mfma_f32_16x16x32_bf16 v[18:21], v[158:161], v[208:211], v[18:21]
	v_mfma_f32_16x16x32_bf16 v[6:9], v[150:153], v[216:219], v[6:9]
	v_mfma_f32_16x16x32_bf16 v[2:5], v[158:161], v[216:219], v[2:5]
	s_barrier
	s_setprio 0
	s_add_i32 s74, s74, 2
	s_add_u32 s52, s52, 0x100
	s_addc_u32 s53, s53, 0
	s_add_u32 s72, s72, 0x100
	s_addc_u32 s73, s73, 0
	s_cmp_gt_u32 s74, 61
	s_cbranch_scc0 .LBB0_1639
	s_and_b64 vcc, exec, s[26:27]
	s_cbranch_vccz .LBB0_1642
	s_barrier

; #define PG8_STAGE(bufoff, gbase, voff) do { _Pragma("unroll") for (int _i = 0; _i < 2; ++_i) \
;         __builtin_amdgcn_global_load_lds((const unsigned*)((const char*)(gbase) + (voff)[_i]), (LAS unsigned*)(lds + (bufoff) + ldsw + _i * 8192), 16, 0, 0); } while (0)
; #define PG8_LDA(dst, b, h) do { _Pragma("unroll") for (int m = 0; m < 4; ++m) _Pragma("unroll") for (int k = 0; k < 2; ++k) dst[m][k] = *(const LAS bf16x8*)(lds + PG8_SA(b, h) + aoff + m * 2048 + k * 1024); } while (0)
; #define PG8_LDB(dst, b, h) do { _Pragma("unroll") for (int n = 0; n < 2; ++n) _Pragma("unroll") for (int k = 0; k < 2; ++k) dst[n][k] = *(const LAS bf16x8*)(lds + PG8_SB(b, h) + boff + n * 2048 + k * 1024); } while (0)
; #define PG8_MMA(ai, bj, At, Bt) do { __builtin_amdgcn_s_setprio(1); _Pragma("unroll") for (int m = 0; m < 4; ++m) _Pragma("unroll") for (int n = 0; n < 2; ++n) _Pragma("unroll") for (int k = 0; k < 2; ++k) \
;         acc[ai][bj][m][n] = __builtin_amdgcn_mfma_f32_16x16x32_bf16(Bt[n][k], At[m][k], acc[ai][bj][m][n], 0, 0, 0); __builtin_amdgcn_s_setprio(0); } while (0)
; #define PG8_WAIT_V(n) asm volatile("s_waitcnt vmcnt(" #n ")" ::: "memory")
; #define PG8_WAIT_L(n) asm volatile("s_waitcnt lgkmcnt(" #n ")" ::: "memory")
; #define PG8_BAR __builtin_amdgcn_s_barrier()
; #define PG8_SCHED __builtin_amdgcn_sched_barrier(0)
; template <class Epi, class Sched, bool ALIGN_EPI = true, bool SP2 = true>
; __device__ __forceinline__ void gemm_phase(LAS unsigned char* lds, const Gemm g, const Sched& S, const Epi& E) {
;     ...
;             PG8_LDB(B0, 0, 0); PG8_LDB(B1, 0, 1); PG8_SCHED; PG8_LDA(At, 0, 0); PG8_STAGE(PG8_SA(1, 1), a1 + hstep, voffA);
;             PG8_WAIT_V(8); PG8_WAIT_L(0); PG8_BAR; PG8_MMA(0, 0, At, B0); PG8_MMA(0, 1, At, B1); PG8_BAR; PG8_SCHED;
;             PG8_LDA(At, 0, 1); PG8_STAGE(PG8_SB(0, 0), b2, voffB); PG8_STAGE(PG8_SB(0, 1), b2 + hstep, voffB); PG8_STAGE(PG8_SA(0, 0), a2, voffA);
;             PG8_WAIT_V(8); PG8_WAIT_L(0); PG8_BAR; PG8_MMA(1, 0, At, B0); PG8_MMA(1, 1, At, B1); PG8_BAR; PG8_SCHED;
.LBB0_1810:
	ds_read_b128 v[148:151], v168
	ds_read_b128 v[152:155], v168 offset:1024
	ds_read_b128 v[156:159], v168 offset:2048
	ds_read_b128 v[160:163], v168 offset:3072
	ds_read_b128 v[174:177], v169
	ds_read_b128 v[178:181], v169 offset:1024
	ds_read_b128 v[182:185], v169 offset:2048
	ds_read_b128 v[186:189], v169 offset:3072
	s_add_u32 s30, s4, 0xfff00080
	s_addc_u32 s31, s5, -1
	s_cmp_eq_u32 s56, 60
	s_cselect_b32 s35, s25, s31
	s_cselect_b32 s34, s52, s30
	s_cselect_b32 s31, s23, s55
	s_cselect_b32 s30, s53, s54
	s_add_i32 m0, s40, 0xc000
	ds_read_b128 v[190:193], v170
	ds_read_b128 v[194:197], v170 offset:1024
	ds_read_b128 v[198:201], v170 offset:2048
	ds_read_b128 v[202:205], v170 offset:3072
	ds_read_b128 v[206:209], v170 offset:4096
	ds_read_b128 v[210:213], v170 offset:5120
	ds_read_b128 v[214:217], v170 offset:6144
	ds_read_b128 v[218:221], v170 offset:7168
	global_load_lds_dwordx4 v140, s[4:5]
	s_add_i32 m0, s40, 0xe000
	s_nop 0
	global_load_lds_dwordx4 v142, s[4:5]
	s_waitcnt vmcnt(8)
	s_waitcnt lgkmcnt(0)
	s_setprio 1
	s_barrier
	v_mfma_f32_16x16x32_bf16 v[126:129], v[148:151], v[190:193], v[126:129]
	v_mfma_f32_16x16x32_bf16 v[122:125], v[156:159], v[190:193], v[122:125]
	v_mfma_f32_16x16x32_bf16 v[106:109], v[156:159], v[198:201], v[106:109]
	v_mfma_f32_16x16x32_bf16 v[110:113], v[148:151], v[198:201], v[110:113]
	v_mfma_f32_16x16x32_bf16 v[94:97], v[148:151], v[206:209], v[94:97]
	v_mfma_f32_16x16x32_bf16 v[90:93], v[156:159], v[206:209], v[90:93]
	v_mfma_f32_16x16x32_bf16 v[74:77], v[156:159], v[214:217], v[74:77]
	v_mfma_f32_16x16x32_bf16 v[78:81], v[148:151], v[214:217], v[78:81]
	v_mfma_f32_16x16x32_bf16 v[126:129], v[152:155], v[194:197], v[126:129]
	v_mfma_f32_16x16x32_bf16 v[122:125], v[160:163], v[194:197], v[122:125]
	v_mfma_f32_16x16x32_bf16 v[106:109], v[160:163], v[202:205], v[106:109]
	v_mfma_f32_16x16x32_bf16 v[110:113], v[152:155], v[202:205], v[110:113]
	v_mfma_f32_16x16x32_bf16 v[94:97], v[152:155], v[210:213], v[94:97]
	v_mfma_f32_16x16x32_bf16 v[90:93], v[160:163], v[210:213], v[90:93]
	v_mfma_f32_16x16x32_bf16 v[74:77], v[160:163], v[218:221], v[74:77]
	v_mfma_f32_16x16x32_bf16 v[78:81], v[152:155], v[218:221], v[78:81]
	v_mfma_f32_16x16x32_bf16 v[118:121], v[174:177], v[190:193], v[118:121]
	v_mfma_f32_16x16x32_bf16 v[114:117], v[182:185], v[190:193], v[114:117]
	v_mfma_f32_16x16x32_bf16 v[98:101], v[182:185], v[198:201], v[98:101]
	v_mfma_f32_16x16x32_bf16 v[102:105], v[174:177], v[198:201], v[102:105]
	v_mfma_f32_16x16x32_bf16 v[86:89], v[174:177], v[206:209], v[86:89]
	v_mfma_f32_16x16x32_bf16 v[82:85], v[182:185], v[206:209], v[82:85]
	v_mfma_f32_16x16x32_bf16 v[66:69], v[182:185], v[214:217], v[66:69]
	v_mfma_f32_16x16x32_bf16 v[70:73], v[174:177], v[214:217], v[70:73]
	v_mfma_f32_16x16x32_bf16 v[118:121], v[178:181], v[194:197], v[118:121]
	v_mfma_f32_16x16x32_bf16 v[114:117], v[186:189], v[194:197], v[114:117]
	v_mfma_f32_16x16x32_bf16 v[98:101], v[186:189], v[202:205], v[98:101]
	v_mfma_f32_16x16x32_bf16 v[102:105], v[178:181], v[202:205], v[102:105]
	v_mfma_f32_16x16x32_bf16 v[86:89], v[178:181], v[210:213], v[86:89]
	v_mfma_f32_16x16x32_bf16 v[82:85], v[186:189], v[210:213], v[82:85]
	v_mfma_f32_16x16x32_bf16 v[66:69], v[186:189], v[218:221], v[66:69]
	v_mfma_f32_16x16x32_bf16 v[70:73], v[178:181], v[218:221], v[70:73]
	s_barrier
	s_setprio 0
	s_add_i32 s57, s48, s37
	v_lshl_add_u64 v[164:165], s[30:31], 0, v[134:135]
	s_mov_b32 m0, s57
	ds_read_b128 v[190:193], v170 offset:16384
	ds_read_b128 v[194:197], v170 offset:17408
	ds_read_b128 v[198:201], v170 offset:18432
	ds_read_b128 v[202:205], v170 offset:19456
	ds_read_b128 v[206:209], v170 offset:20480
	ds_read_b128 v[210:213], v170 offset:21504
	ds_read_b128 v[214:217], v170 offset:22528
	ds_read_b128 v[218:221], v170 offset:23552
	global_load_lds_dwordx4 v[164:165], off
	s_add_i32 m0, s57, 0x2000
	s_add_u32 s58, s30, 0x100000
	v_lshl_add_u64 v[222:223], s[30:31], 0, v[130:131]
	s_addc_u32 s59, s31, 0
	s_add_i32 s57, s49, s37
	global_load_lds_dwordx4 v[222:223], off
	s_mov_b32 m0, s57
	v_lshl_add_u64 v[226:227], s[34:35], 0, v[132:133]
	global_load_lds_dwordx4 v134, s[58:59]
	s_add_i32 m0, s57, 0x2000
	s_nop 0
	global_load_lds_dwordx4 v130, s[58:59]
	v_lshl_add_u64 v[224:225], s[34:35], 0, v[136:137]
	s_mov_b32 m0, s40
	s_nop 0
	global_load_lds_dwordx4 v[224:225], off
	s_mov_b32 m0, s41
	s_nop 0
	global_load_lds_dwordx4 v[226:227], off
	s_waitcnt vmcnt(8)
	s_waitcnt lgkmcnt(0)
	s_setprio 1
	s_barrier
	v_mfma_f32_16x16x32_bf16 v[62:65], v[148:151], v[190:193], v[62:65]
	v_mfma_f32_16x16x32_bf16 v[58:61], v[156:159], v[190:193], v[58:61]
	v_mfma_f32_16x16x32_bf16 v[42:45], v[156:159], v[198:201], v[42:45]
	v_mfma_f32_16x16x32_bf16 v[46:49], v[148:151], v[198:201], v[46:49]
	v_mfma_f32_16x16x32_bf16 v[30:33], v[148:151], v[206:209], v[30:33]
	v_mfma_f32_16x16x32_bf16 v[26:29], v[156:159], v[206:209], v[26:29]
	v_mfma_f32_16x16x32_bf16 v[10:13], v[156:159], v[214:217], v[10:13]
	v_mfma_f32_16x16x32_bf16 v[14:17], v[148:151], v[214:217], v[14:17]
	v_mfma_f32_16x16x32_bf16 v[62:65], v[152:155], v[194:197], v[62:65]
	v_mfma_f32_16x16x32_bf16 v[58:61], v[160:163], v[194:197], v[58:61]
	v_mfma_f32_16x16x32_bf16 v[42:45], v[160:163], v[202:205], v[42:45]
	v_mfma_f32_16x16x32_bf16 v[46:49], v[152:155], v[202:205], v[46:49]
	v_mfma_f32_16x16x32_bf16 v[30:33], v[152:155], v[210:213], v[30:33]
	v_mfma_f32_16x16x32_bf16 v[26:29], v[160:163], v[210:213], v[26:29]
	v_mfma_f32_16x16x32_bf16 v[10:13], v[160:163], v[218:221], v[10:13]
	v_mfma_f32_16x16x32_bf16 v[14:17], v[152:155], v[218:221], v[14:17]
	v_mfma_f32_16x16x32_bf16 v[54:57], v[174:177], v[190:193], v[54:57]
	v_mfma_f32_16x16x32_bf16 v[50:53], v[182:185], v[190:193], v[50:53]
	v_mfma_f32_16x16x32_bf16 v[34:37], v[182:185], v[198:201], v[34:37]
	v_mfma_f32_16x16x32_bf16 v[38:41], v[174:177], v[198:201], v[38:41]
	v_mfma_f32_16x16x32_bf16 v[22:25], v[174:177], v[206:209], v[22:25]
	v_mfma_f32_16x16x32_bf16 v[18:21], v[182:185], v[206:209], v[18:21]
	v_mfma_f32_16x16x32_bf16 v[2:5], v[182:185], v[214:217], v[2:5]
	v_mfma_f32_16x16x32_bf16 v[6:9], v[174:177], v[214:217], v[6:9]
	v_mfma_f32_16x16x32_bf16 v[54:57], v[178:181], v[194:197], v[54:57]
	v_mfma_f32_16x16x32_bf16 v[50:53], v[186:189], v[194:197], v[50:53]
	v_mfma_f32_16x16x32_bf16 v[34:37], v[186:189], v[202:205], v[34:37]
	v_mfma_f32_16x16x32_bf16 v[38:41], v[178:181], v[202:205], v[38:41]
	v_mfma_f32_16x16x32_bf16 v[22:25], v[178:181], v[210:213], v[22:25]
	v_mfma_f32_16x16x32_bf16 v[18:21], v[186:189], v[210:213], v[18:21]
	v_mfma_f32_16x16x32_bf16 v[2:5], v[186:189], v[218:221], v[2:5]
	v_mfma_f32_16x16x32_bf16 v[6:9], v[178:181], v[218:221], v[6:9]
	s_barrier
; #define PG8_STAGE(bufoff, gbase, voff) do { _Pragma("unroll") for (int _i = 0; _i < 2; ++_i) \
;         __builtin_amdgcn_global_load_lds((const unsigned*)((const char*)(gbase) + (voff)[_i]), (LAS unsigned*)(lds + (bufoff) + ldsw + _i * 8192), 16, 0, 0); } while (0)
; #define PG8_LDA(dst, b, h) do { _Pragma("unroll") for (int m = 0; m < 4; ++m) _Pragma("unroll") for (int k = 0; k < 2; ++k) dst[m][k] = *(const LAS bf16x8*)(lds + PG8_SA(b, h) + aoff + m * 2048 + k * 1024); } while (0)
; #define PG8_LDB(dst, b, h) do { _Pragma("unroll") for (int n = 0; n < 2; ++n) _Pragma("unroll") for (int k = 0; k < 2; ++k) dst[n][k] = *(const LAS bf16x8*)(lds + PG8_SB(b, h) + boff + n * 2048 + k * 1024); } while (0)
; #define PG8_MMA(ai, bj, At, Bt) do { __builtin_amdgcn_s_setprio(1); _Pragma("unroll") for (int m = 0; m < 4; ++m) _Pragma("unroll") for (int n = 0; n < 2; ++n) _Pragma("unroll") for (int k = 0; k < 2; ++k) \
;         acc[ai][bj][m][n] = __builtin_amdgcn_mfma_f32_16x16x32_bf16(Bt[n][k], At[m][k], acc[ai][bj][m][n], 0, 0, 0); __builtin_amdgcn_s_setprio(0); } while (0)
; #define PG8_WAIT_V(n) asm volatile("s_waitcnt vmcnt(" #n ")" ::: "memory")
; #define PG8_WAIT_L(n) asm volatile("s_waitcnt lgkmcnt(" #n ")" ::: "memory")
; #define PG8_BAR __builtin_amdgcn_s_barrier()
; #define PG8_SCHED __builtin_amdgcn_sched_barrier(0)
; template <class Epi, class Sched, bool ALIGN_EPI = true, bool SP2 = true>
; __device__ __forceinline__ void gemm_phase(LAS unsigned char* lds, const Gemm g, const Sched& S, const Epi& E) {
;     ...
;             PG8_LDB(B0, 1, 0); PG8_LDB(B1, 1, 1); PG8_SCHED; PG8_LDA(At, 1, 0); PG8_STAGE(PG8_SA(0, 1), a2 + hstep, voffA);
;             PG8_WAIT_V(8); PG8_WAIT_L(0); PG8_BAR; PG8_MMA(0, 0, At, B0); PG8_MMA(0, 1, At, B1); PG8_BAR; PG8_SCHED;
;             PG8_LDA(At, 1, 1); PG8_STAGE(PG8_SB(1, 0), b3, voffB); PG8_STAGE(PG8_SB(1, 1), b3 + hstep, voffB); PG8_STAGE(PG8_SA(1, 0), a3, voffA);
;             PG8_WAIT_V(8); PG8_WAIT_L(0); PG8_BAR; PG8_MMA(1, 0, At, B0); PG8_MMA(1, 1, At, B1); PG8_BAR; PG8_SCHED;
	s_setprio 0
	s_add_i32 s57, 0, 0x18000
	s_add_i32 s58, 0, 0x1c000
	v_add_u32_e32 v160, s57, v167
	v_add_u32_e32 v173, s58, v167
	ds_read_b128 v[148:151], v160
	ds_read_b128 v[152:155], v160 offset:1024
	ds_read_b128 v[156:159], v160 offset:2048
	ds_read_b128 v[160:163], v160 offset:3072
	ds_read_b128 v[174:177], v173
	ds_read_b128 v[178:181], v173 offset:1024
	ds_read_b128 v[182:185], v173 offset:2048
	ds_read_b128 v[186:189], v173 offset:3072
	s_add_u32 s34, s34, 0x100000
	s_addc_u32 s35, s35, 0
	s_mov_b32 m0, s42
	ds_read_b128 v[190:193], v170 offset:32768
	ds_read_b128 v[194:197], v170 offset:33792
	ds_read_b128 v[198:201], v170 offset:34816
	ds_read_b128 v[202:205], v170 offset:35840
	ds_read_b128 v[206:209], v170 offset:36864
	ds_read_b128 v[210:213], v170 offset:37888
	ds_read_b128 v[214:217], v170 offset:38912
	ds_read_b128 v[218:221], v170 offset:39936
	global_load_lds_dwordx4 v136, s[34:35]
	s_mov_b32 m0, s43
	s_nop 0
	global_load_lds_dwordx4 v132, s[34:35]
	s_waitcnt vmcnt(8)
	s_waitcnt lgkmcnt(0)
	s_setprio 1
	s_barrier
	v_mfma_f32_16x16x32_bf16 v[126:129], v[148:151], v[190:193], v[126:129]
	v_mfma_f32_16x16x32_bf16 v[122:125], v[156:159], v[190:193], v[122:125]
	v_mfma_f32_16x16x32_bf16 v[106:109], v[156:159], v[198:201], v[106:109]
	v_mfma_f32_16x16x32_bf16 v[110:113], v[148:151], v[198:201], v[110:113]
	v_mfma_f32_16x16x32_bf16 v[94:97], v[148:151], v[206:209], v[94:97]
	v_mfma_f32_16x16x32_bf16 v[90:93], v[156:159], v[206:209], v[90:93]
	v_mfma_f32_16x16x32_bf16 v[74:77], v[156:159], v[214:217], v[74:77]
	v_mfma_f32_16x16x32_bf16 v[78:81], v[148:151], v[214:217], v[78:81]
	v_mfma_f32_16x16x32_bf16 v[126:129], v[152:155], v[194:197], v[126:129]
	v_mfma_f32_16x16x32_bf16 v[122:125], v[160:163], v[194:197], v[122:125]
	v_mfma_f32_16x16x32_bf16 v[106:109], v[160:163], v[202:205], v[106:109]
	v_mfma_f32_16x16x32_bf16 v[110:113], v[152:155], v[202:205], v[110:113]
	v_mfma_f32_16x16x32_bf16 v[94:97], v[152:155], v[210:213], v[94:97]
	v_mfma_f32_16x16x32_bf16 v[90:93], v[160:163], v[210:213], v[90:93]
	v_mfma_f32_16x16x32_bf16 v[74:77], v[160:163], v[218:221], v[74:77]
	v_mfma_f32_16x16x32_bf16 v[78:81], v[152:155], v[218:221], v[78:81]
	v_mfma_f32_16x16x32_bf16 v[118:121], v[174:177], v[190:193], v[118:121]
	v_mfma_f32_16x16x32_bf16 v[114:117], v[182:185], v[190:193], v[114:117]
	v_mfma_f32_16x16x32_bf16 v[98:101], v[182:185], v[198:201], v[98:101]
	v_mfma_f32_16x16x32_bf16 v[102:105], v[174:177], v[198:201], v[102:105]
	v_mfma_f32_16x16x32_bf16 v[86:89], v[174:177], v[206:209], v[86:89]
	v_mfma_f32_16x16x32_bf16 v[82:85], v[182:185], v[206:209], v[82:85]
	v_mfma_f32_16x16x32_bf16 v[66:69], v[182:185], v[214:217], v[66:69]
	v_mfma_f32_16x16x32_bf16 v[70:73], v[174:177], v[214:217], v[70:73]
	v_mfma_f32_16x16x32_bf16 v[118:121], v[178:181], v[194:197], v[118:121]
	v_mfma_f32_16x16x32_bf16 v[114:117], v[186:189], v[194:197], v[114:117]
	v_mfma_f32_16x16x32_bf16 v[98:101], v[186:189], v[202:205], v[98:101]
	v_mfma_f32_16x16x32_bf16 v[102:105], v[178:181], v[202:205], v[102:105]
	v_mfma_f32_16x16x32_bf16 v[86:89], v[178:181], v[210:213], v[86:89]
	v_mfma_f32_16x16x32_bf16 v[82:85], v[186:189], v[210:213], v[82:85]
	v_mfma_f32_16x16x32_bf16 v[66:69], v[186:189], v[218:221], v[66:69]
	v_mfma_f32_16x16x32_bf16 v[70:73], v[178:181], v[218:221], v[70:73]
	s_barrier
	s_setprio 0
	s_add_i32 s34, s57, s37
	v_lshl_add_u64 v[164:165], v[164:165], 0, s[18:19]
	s_mov_b32 m0, s34
	ds_read_b128 v[190:193], v170 offset:49152
	ds_read_b128 v[194:197], v170 offset:50176
	ds_read_b128 v[198:201], v170 offset:51200
	ds_read_b128 v[202:205], v170 offset:52224
	ds_read_b128 v[206:209], v170 offset:53248
	ds_read_b128 v[210:213], v170 offset:54272
	ds_read_b128 v[214:217], v170 offset:55296
	ds_read_b128 v[218:221], v170 offset:56320
	global_load_lds_dwordx4 v[164:165], off
	s_add_i32 m0, s34, 0x2000
	s_add_u32 s30, s30, 0x100080
	v_lshl_add_u64 v[164:165], v[222:223], 0, s[18:19]
	s_addc_u32 s31, s31, 0
	s_add_i32 s34, s58, s37
	global_load_lds_dwordx4 v[164:165], off
	s_mov_b32 m0, s34
	s_nop 0
	global_load_lds_dwordx4 v134, s[30:31]
	s_add_i32 m0, s34, 0x2000
	s_nop 0
	global_load_lds_dwordx4 v130, s[30:31]
	v_lshl_add_u64 v[164:165], v[224:225], 0, s[18:19]
	s_mov_b32 m0, s45
	s_nop 0
	global_load_lds_dwordx4 v[164:165], off
	v_lshl_add_u64 v[164:165], v[226:227], 0, s[18:19]
	s_mov_b32 m0, s46
	s_nop 0
	global_load_lds_dwordx4 v[164:165], off
	s_waitcnt vmcnt(8)
	s_waitcnt lgkmcnt(0)
	s_setprio 1
	s_barrier
	v_mfma_f32_16x16x32_bf16 v[62:65], v[148:151], v[190:193], v[62:65]
	v_mfma_f32_16x16x32_bf16 v[58:61], v[156:159], v[190:193], v[58:61]
	v_mfma_f32_16x16x32_bf16 v[42:45], v[156:159], v[198:201], v[42:45]
	v_mfma_f32_16x16x32_bf16 v[46:49], v[148:151], v[198:201], v[46:49]
	v_mfma_f32_16x16x32_bf16 v[30:33], v[148:151], v[206:209], v[30:33]
	v_mfma_f32_16x16x32_bf16 v[26:29], v[156:159], v[206:209], v[26:29]
	v_mfma_f32_16x16x32_bf16 v[10:13], v[156:159], v[214:217], v[10:13]
	v_mfma_f32_16x16x32_bf16 v[14:17], v[148:151], v[214:217], v[14:17]
	v_mfma_f32_16x16x32_bf16 v[62:65], v[152:155], v[194:197], v[62:65]
	v_mfma_f32_16x16x32_bf16 v[58:61], v[160:163], v[194:197], v[58:61]
	v_mfma_f32_16x16x32_bf16 v[42:45], v[160:163], v[202:205], v[42:45]
	v_mfma_f32_16x16x32_bf16 v[46:49], v[152:155], v[202:205], v[46:49]
	v_mfma_f32_16x16x32_bf16 v[30:33], v[152:155], v[210:213], v[30:33]
	v_mfma_f32_16x16x32_bf16 v[26:29], v[160:163], v[210:213], v[26:29]
	v_mfma_f32_16x16x32_bf16 v[10:13], v[160:163], v[218:221], v[10:13]
	v_mfma_f32_16x16x32_bf16 v[14:17], v[152:155], v[218:221], v[14:17]
	v_mfma_f32_16x16x32_bf16 v[54:57], v[174:177], v[190:193], v[54:57]
	v_mfma_f32_16x16x32_bf16 v[50:53], v[182:185], v[190:193], v[50:53]
	v_mfma_f32_16x16x32_bf16 v[34:37], v[182:185], v[198:201], v[34:37]
	v_mfma_f32_16x16x32_bf16 v[38:41], v[174:177], v[198:201], v[38:41]
	v_mfma_f32_16x16x32_bf16 v[22:25], v[174:177], v[206:209], v[22:25]
	v_mfma_f32_16x16x32_bf16 v[18:21], v[182:185], v[206:209], v[18:21]
	v_mfma_f32_16x16x32_bf16 v[2:5], v[182:185], v[214:217], v[2:5]
	v_mfma_f32_16x16x32_bf16 v[6:9], v[174:177], v[214:217], v[6:9]
	v_mfma_f32_16x16x32_bf16 v[54:57], v[178:181], v[194:197], v[54:57]
	v_mfma_f32_16x16x32_bf16 v[50:53], v[186:189], v[194:197], v[50:53]
	v_mfma_f32_16x16x32_bf16 v[34:37], v[186:189], v[202:205], v[34:37]
	v_mfma_f32_16x16x32_bf16 v[38:41], v[178:181], v[202:205], v[38:41]
	v_mfma_f32_16x16x32_bf16 v[22:25], v[178:181], v[210:213], v[22:25]
	v_mfma_f32_16x16x32_bf16 v[18:21], v[186:189], v[210:213], v[18:21]
	v_mfma_f32_16x16x32_bf16 v[2:5], v[186:189], v[218:221], v[2:5]
	v_mfma_f32_16x16x32_bf16 v[6:9], v[178:181], v[218:221], v[6:9]
	s_barrier
	s_setprio 0
	s_add_i32 s56, s56, 2
	s_add_u32 s4, s4, 0x100
	s_addc_u32 s5, s5, 0
	s_add_u32 s54, s54, 0x100
	s_addc_u32 s55, s55, 0
	s_cmp_gt_u32 s56, 61
	s_cbranch_scc0 .LBB0_1810
	s_and_b64 vcc, exec, s[20:21]
	s_cbranch_vccz .LBB0_1813
	s_barrier

; #define PG8_STAGE(bufoff, gbase, voff) do { _Pragma("unroll") for (int _i = 0; _i < 2; ++_i) \
;         __builtin_amdgcn_global_load_lds((const unsigned*)((const char*)(gbase) + (voff)[_i]), (LAS unsigned*)(lds + (bufoff) + ldsw + _i * 8192), 16, 0, 0); } while (0)
; #define PG8_LDA(dst, b, h) do { _Pragma("unroll") for (int m = 0; m < 4; ++m) _Pragma("unroll") for (int k = 0; k < 2; ++k) dst[m][k] = *(const LAS bf16x8*)(lds + PG8_SA(b, h) + aoff + m * 2048 + k * 1024); } while (0)
; #define PG8_LDB(dst, b, h) do { _Pragma("unroll") for (int n = 0; n < 2; ++n) _Pragma("unroll") for (int k = 0; k < 2; ++k) dst[n][k] = *(const LAS bf16x8*)(lds + PG8_SB(b, h) + boff + n * 2048 + k * 1024); } while (0)
; #define PG8_MMA(ai, bj, At, Bt) do { __builtin_amdgcn_s_setprio(1); _Pragma("unroll") for (int m = 0; m < 4; ++m) _Pragma("unroll") for (int n = 0; n < 2; ++n) _Pragma("unroll") for (int k = 0; k < 2; ++k) \
;         acc[ai][bj][m][n] = __builtin_amdgcn_mfma_f32_16x16x32_bf16(Bt[n][k], At[m][k], acc[ai][bj][m][n], 0, 0, 0); __builtin_amdgcn_s_setprio(0); } while (0)
; #define PG8_WAIT_V(n) asm volatile("s_waitcnt vmcnt(" #n ")" ::: "memory")
; #define PG8_WAIT_L(n) asm volatile("s_waitcnt lgkmcnt(" #n ")" ::: "memory")
; #define PG8_BAR __builtin_amdgcn_s_barrier()
; #define PG8_SCHED __builtin_amdgcn_sched_barrier(0)
; template <class Epi, class Sched, bool ALIGN_EPI = true, bool SP2 = true>
; __device__ __forceinline__ void gemm_phase(LAS unsigned char* lds, const Gemm g, const Sched& S, const Epi& E) {
;     ...
;             PG8_LDB(B0, 0, 0); PG8_LDB(B1, 0, 1); PG8_SCHED; PG8_LDA(At, 0, 0); PG8_STAGE(PG8_SA(1, 1), a1 + hstep, voffA);
;             PG8_WAIT_V(8); PG8_WAIT_L(0); PG8_BAR; PG8_MMA(0, 0, At, B0); PG8_MMA(0, 1, At, B1); PG8_BAR; PG8_SCHED;
;             PG8_LDA(At, 0, 1); PG8_STAGE(PG8_SB(0, 0), b2, voffB); PG8_STAGE(PG8_SB(0, 1), b2 + hstep, voffB); PG8_STAGE(PG8_SA(0, 0), a2, voffA);
;             PG8_WAIT_V(8); PG8_WAIT_L(0); PG8_BAR; PG8_MMA(1, 0, At, B0); PG8_MMA(1, 1, At, B1); PG8_BAR; PG8_SCHED;
.LBB0_2060:
	ds_read_b128 v[130:133], v187
	ds_read_b128 v[134:137], v187 offset:1024
	ds_read_b128 v[138:141], v187 offset:2048
	ds_read_b128 v[142:145], v187 offset:3072
	ds_read_b128 v[146:149], v188
	ds_read_b128 v[150:153], v188 offset:1024
	ds_read_b128 v[170:173], v188 offset:2048
	ds_read_b128 v[192:195], v188 offset:3072
	s_add_u32 s26, s24, 0xffd50080
	s_addc_u32 s27, s25, -1
	s_cmpk_eq_i32 s53, 0xa8
	s_cselect_b32 s29, s7, s27
	s_cselect_b32 s28, s6, s26
	s_cselect_b32 s27, s23, s52
	s_cselect_b32 s26, s22, s51
	s_add_i32 m0, s36, 0xc000
	ds_read_b128 v[196:199], v189
	ds_read_b128 v[200:203], v189 offset:1024
	ds_read_b128 v[204:207], v189 offset:2048
	ds_read_b128 v[208:211], v189 offset:3072
	ds_read_b128 v[212:215], v189 offset:4096
	ds_read_b128 v[216:219], v189 offset:5120
	ds_read_b128 v[220:223], v189 offset:6144
	ds_read_b128 v[224:227], v189 offset:7168
	global_load_lds_dwordx4 v162, s[24:25]
	s_add_i32 m0, s36, 0xe000
	s_nop 0
	global_load_lds_dwordx4 v164, s[24:25]
	s_waitcnt vmcnt(8)
	s_waitcnt lgkmcnt(0)
	s_setprio 1
	s_barrier
	v_mfma_f32_16x16x32_bf16 v[126:129], v[130:133], v[196:199], v[126:129]
	v_mfma_f32_16x16x32_bf16 v[122:125], v[138:141], v[196:199], v[122:125]
	v_mfma_f32_16x16x32_bf16 v[110:113], v[130:133], v[204:207], v[110:113]
	v_mfma_f32_16x16x32_bf16 v[106:109], v[138:141], v[204:207], v[106:109]
	v_mfma_f32_16x16x32_bf16 v[94:97], v[130:133], v[212:215], v[94:97]
	v_mfma_f32_16x16x32_bf16 v[90:93], v[138:141], v[212:215], v[90:93]
	v_mfma_f32_16x16x32_bf16 v[78:81], v[130:133], v[220:223], v[78:81]
	v_mfma_f32_16x16x32_bf16 v[74:77], v[138:141], v[220:223], v[74:77]
	v_mfma_f32_16x16x32_bf16 v[126:129], v[134:137], v[200:203], v[126:129]
	v_mfma_f32_16x16x32_bf16 v[122:125], v[142:145], v[200:203], v[122:125]
	v_mfma_f32_16x16x32_bf16 v[110:113], v[134:137], v[208:211], v[110:113]
	v_mfma_f32_16x16x32_bf16 v[106:109], v[142:145], v[208:211], v[106:109]
	v_mfma_f32_16x16x32_bf16 v[94:97], v[134:137], v[216:219], v[94:97]
	v_mfma_f32_16x16x32_bf16 v[90:93], v[142:145], v[216:219], v[90:93]
	v_mfma_f32_16x16x32_bf16 v[78:81], v[134:137], v[224:227], v[78:81]
	v_mfma_f32_16x16x32_bf16 v[74:77], v[142:145], v[224:227], v[74:77]
	v_mfma_f32_16x16x32_bf16 v[118:121], v[146:149], v[196:199], v[118:121]
	v_mfma_f32_16x16x32_bf16 v[114:117], v[170:173], v[196:199], v[114:117]
	v_mfma_f32_16x16x32_bf16 v[102:105], v[146:149], v[204:207], v[102:105]
	v_mfma_f32_16x16x32_bf16 v[98:101], v[170:173], v[204:207], v[98:101]
	v_mfma_f32_16x16x32_bf16 v[86:89], v[146:149], v[212:215], v[86:89]
	v_mfma_f32_16x16x32_bf16 v[82:85], v[170:173], v[212:215], v[82:85]
	v_mfma_f32_16x16x32_bf16 v[70:73], v[146:149], v[220:223], v[70:73]
	v_mfma_f32_16x16x32_bf16 v[66:69], v[170:173], v[220:223], v[66:69]
	v_mfma_f32_16x16x32_bf16 v[118:121], v[150:153], v[200:203], v[118:121]
	v_mfma_f32_16x16x32_bf16 v[114:117], v[192:195], v[200:203], v[114:117]
	v_mfma_f32_16x16x32_bf16 v[102:105], v[150:153], v[208:211], v[102:105]
	v_mfma_f32_16x16x32_bf16 v[98:101], v[192:195], v[208:211], v[98:101]
	v_mfma_f32_16x16x32_bf16 v[86:89], v[150:153], v[216:219], v[86:89]
	v_mfma_f32_16x16x32_bf16 v[82:85], v[192:195], v[216:219], v[82:85]
	v_mfma_f32_16x16x32_bf16 v[70:73], v[150:153], v[224:227], v[70:73]
	v_mfma_f32_16x16x32_bf16 v[66:69], v[192:195], v[224:227], v[66:69]
	s_barrier
	s_setprio 0
	s_add_i32 s54, s45, s35
	v_lshl_add_u64 v[174:175], s[26:27], 0, v[156:157]
	s_mov_b32 m0, s54
	ds_read_b128 v[196:199], v189 offset:16384
	ds_read_b128 v[200:203], v189 offset:17408
	ds_read_b128 v[204:207], v189 offset:18432
	ds_read_b128 v[208:211], v189 offset:19456
	ds_read_b128 v[212:215], v189 offset:20480
	ds_read_b128 v[216:219], v189 offset:21504
	ds_read_b128 v[220:223], v189 offset:22528
	ds_read_b128 v[224:227], v189 offset:23552
	global_load_lds_dwordx4 v[174:175], off
	s_add_i32 m0, s54, 0x2000
	s_add_u32 s54, s26, 0x2b0000
	v_lshl_add_u64 v[228:229], s[26:27], 0, v[160:161]
	s_addc_u32 s55, s27, 0
	s_add_i32 s56, s46, s35
	global_load_lds_dwordx4 v[228:229], off
	s_mov_b32 m0, s56
	v_lshl_add_u64 v[232:233], s[28:29], 0, v[158:159]
	global_load_lds_dwordx4 v156, s[54:55]
	s_add_i32 m0, s56, 0x2000
	s_nop 0
	global_load_lds_dwordx4 v160, s[54:55]
	v_lshl_add_u64 v[230:231], s[28:29], 0, v[154:155]
	s_mov_b32 m0, s36
	s_nop 0
	global_load_lds_dwordx4 v[230:231], off
	s_mov_b32 m0, s37
	s_nop 0
	global_load_lds_dwordx4 v[232:233], off
	s_waitcnt vmcnt(8)
	s_waitcnt lgkmcnt(0)
	s_setprio 1
	s_barrier
	v_mfma_f32_16x16x32_bf16 v[62:65], v[130:133], v[196:199], v[62:65]
	v_mfma_f32_16x16x32_bf16 v[58:61], v[138:141], v[196:199], v[58:61]
	v_mfma_f32_16x16x32_bf16 v[46:49], v[130:133], v[204:207], v[46:49]
	v_mfma_f32_16x16x32_bf16 v[42:45], v[138:141], v[204:207], v[42:45]
	v_mfma_f32_16x16x32_bf16 v[30:33], v[130:133], v[212:215], v[30:33]
	v_mfma_f32_16x16x32_bf16 v[26:29], v[138:141], v[212:215], v[26:29]
	v_mfma_f32_16x16x32_bf16 v[14:17], v[130:133], v[220:223], v[14:17]
	v_mfma_f32_16x16x32_bf16 v[10:13], v[138:141], v[220:223], v[10:13]
	v_mfma_f32_16x16x32_bf16 v[62:65], v[134:137], v[200:203], v[62:65]
	v_mfma_f32_16x16x32_bf16 v[58:61], v[142:145], v[200:203], v[58:61]
	v_mfma_f32_16x16x32_bf16 v[46:49], v[134:137], v[208:211], v[46:49]
	v_mfma_f32_16x16x32_bf16 v[42:45], v[142:145], v[208:211], v[42:45]
	v_mfma_f32_16x16x32_bf16 v[30:33], v[134:137], v[216:219], v[30:33]
	v_mfma_f32_16x16x32_bf16 v[26:29], v[142:145], v[216:219], v[26:29]
	v_mfma_f32_16x16x32_bf16 v[14:17], v[134:137], v[224:227], v[14:17]
	v_mfma_f32_16x16x32_bf16 v[10:13], v[142:145], v[224:227], v[10:13]
	v_mfma_f32_16x16x32_bf16 v[54:57], v[146:149], v[196:199], v[54:57]
	v_mfma_f32_16x16x32_bf16 v[50:53], v[170:173], v[196:199], v[50:53]
	v_mfma_f32_16x16x32_bf16 v[38:41], v[146:149], v[204:207], v[38:41]
	v_mfma_f32_16x16x32_bf16 v[34:37], v[170:173], v[204:207], v[34:37]
	v_mfma_f32_16x16x32_bf16 v[22:25], v[146:149], v[212:215], v[22:25]
	v_mfma_f32_16x16x32_bf16 v[18:21], v[170:173], v[212:215], v[18:21]
	v_mfma_f32_16x16x32_bf16 v[6:9], v[146:149], v[220:223], v[6:9]
	v_mfma_f32_16x16x32_bf16 v[2:5], v[170:173], v[220:223], v[2:5]
	v_mfma_f32_16x16x32_bf16 v[54:57], v[150:153], v[200:203], v[54:57]
	v_mfma_f32_16x16x32_bf16 v[50:53], v[192:195], v[200:203], v[50:53]
	v_mfma_f32_16x16x32_bf16 v[38:41], v[150:153], v[208:211], v[38:41]
	v_mfma_f32_16x16x32_bf16 v[34:37], v[192:195], v[208:211], v[34:37]
	v_mfma_f32_16x16x32_bf16 v[22:25], v[150:153], v[216:219], v[22:25]
	v_mfma_f32_16x16x32_bf16 v[18:21], v[192:195], v[216:219], v[18:21]
	v_mfma_f32_16x16x32_bf16 v[6:9], v[150:153], v[224:227], v[6:9]
	v_mfma_f32_16x16x32_bf16 v[2:5], v[192:195], v[224:227], v[2:5]
	s_barrier
; #define PG8_STAGE(bufoff, gbase, voff) do { _Pragma("unroll") for (int _i = 0; _i < 2; ++_i) \
;         __builtin_amdgcn_global_load_lds((const unsigned*)((const char*)(gbase) + (voff)[_i]), (LAS unsigned*)(lds + (bufoff) + ldsw + _i * 8192), 16, 0, 0); } while (0)
; #define PG8_LDA(dst, b, h) do { _Pragma("unroll") for (int m = 0; m < 4; ++m) _Pragma("unroll") for (int k = 0; k < 2; ++k) dst[m][k] = *(const LAS bf16x8*)(lds + PG8_SA(b, h) + aoff + m * 2048 + k * 1024); } while (0)
; #define PG8_LDB(dst, b, h) do { _Pragma("unroll") for (int n = 0; n < 2; ++n) _Pragma("unroll") for (int k = 0; k < 2; ++k) dst[n][k] = *(const LAS bf16x8*)(lds + PG8_SB(b, h) + boff + n * 2048 + k * 1024); } while (0)
; #define PG8_MMA(ai, bj, At, Bt) do { __builtin_amdgcn_s_setprio(1); _Pragma("unroll") for (int m = 0; m < 4; ++m) _Pragma("unroll") for (int n = 0; n < 2; ++n) _Pragma("unroll") for (int k = 0; k < 2; ++k) \
;         acc[ai][bj][m][n] = __builtin_amdgcn_mfma_f32_16x16x32_bf16(Bt[n][k], At[m][k], acc[ai][bj][m][n], 0, 0, 0); __builtin_amdgcn_s_setprio(0); } while (0)
; #define PG8_WAIT_V(n) asm volatile("s_waitcnt vmcnt(" #n ")" ::: "memory")
; #define PG8_WAIT_L(n) asm volatile("s_waitcnt lgkmcnt(" #n ")" ::: "memory")
; #define PG8_BAR __builtin_amdgcn_s_barrier()
; #define PG8_SCHED __builtin_amdgcn_sched_barrier(0)
; template <class Epi, class Sched, bool ALIGN_EPI = true, bool SP2 = true>
; __device__ __forceinline__ void gemm_phase(LAS unsigned char* lds, const Gemm g, const Sched& S, const Epi& E) {
;     ...
;             PG8_LDB(B0, 1, 0); PG8_LDB(B1, 1, 1); PG8_SCHED; PG8_LDA(At, 1, 0); PG8_STAGE(PG8_SA(0, 1), a2 + hstep, voffA);
;             PG8_WAIT_V(8); PG8_WAIT_L(0); PG8_BAR; PG8_MMA(0, 0, At, B0); PG8_MMA(0, 1, At, B1); PG8_BAR; PG8_SCHED;
;             PG8_LDA(At, 1, 1); PG8_STAGE(PG8_SB(1, 0), b3, voffB); PG8_STAGE(PG8_SB(1, 1), b3 + hstep, voffB); PG8_STAGE(PG8_SA(1, 0), a3, voffA);
;             PG8_WAIT_V(8); PG8_WAIT_L(0); PG8_BAR; PG8_MMA(1, 0, At, B0); PG8_MMA(1, 1, At, B1); PG8_BAR; PG8_SCHED;
	s_setprio 0
	s_add_i32 s54, 0, 0x18000
	s_add_i32 s55, 0, 0x1c000
	v_add_u32_e32 v142, s54, v185
	v_add_u32_e32 v191, s55, v185
	ds_read_b128 v[130:133], v142
	ds_read_b128 v[134:137], v142 offset:1024
	ds_read_b128 v[138:141], v142 offset:2048
	ds_read_b128 v[142:145], v142 offset:3072
	ds_read_b128 v[146:149], v191
	ds_read_b128 v[150:153], v191 offset:1024
	ds_read_b128 v[170:173], v191 offset:2048
	ds_read_b128 v[192:195], v191 offset:3072
	s_add_u32 s28, s28, 0x2b0000
	s_addc_u32 s29, s29, 0
	s_mov_b32 m0, s38
	ds_read_b128 v[196:199], v189 offset:32768
	ds_read_b128 v[200:203], v189 offset:33792
	ds_read_b128 v[204:207], v189 offset:34816
	ds_read_b128 v[208:211], v189 offset:35840
	ds_read_b128 v[212:215], v189 offset:36864
	ds_read_b128 v[216:219], v189 offset:37888
	ds_read_b128 v[220:223], v189 offset:38912
	ds_read_b128 v[224:227], v189 offset:39936
	global_load_lds_dwordx4 v154, s[28:29]
	s_mov_b32 m0, s39
	s_nop 0
	global_load_lds_dwordx4 v158, s[28:29]
	s_waitcnt vmcnt(8)
	s_waitcnt lgkmcnt(0)
	s_setprio 1
	s_barrier
	v_mfma_f32_16x16x32_bf16 v[126:129], v[130:133], v[196:199], v[126:129]
	v_mfma_f32_16x16x32_bf16 v[122:125], v[138:141], v[196:199], v[122:125]
	v_mfma_f32_16x16x32_bf16 v[110:113], v[130:133], v[204:207], v[110:113]
	v_mfma_f32_16x16x32_bf16 v[106:109], v[138:141], v[204:207], v[106:109]
	v_mfma_f32_16x16x32_bf16 v[94:97], v[130:133], v[212:215], v[94:97]
	v_mfma_f32_16x16x32_bf16 v[90:93], v[138:141], v[212:215], v[90:93]
	v_mfma_f32_16x16x32_bf16 v[78:81], v[130:133], v[220:223], v[78:81]
	v_mfma_f32_16x16x32_bf16 v[74:77], v[138:141], v[220:223], v[74:77]
	v_mfma_f32_16x16x32_bf16 v[126:129], v[134:137], v[200:203], v[126:129]
	v_mfma_f32_16x16x32_bf16 v[122:125], v[142:145], v[200:203], v[122:125]
	v_mfma_f32_16x16x32_bf16 v[110:113], v[134:137], v[208:211], v[110:113]
	v_mfma_f32_16x16x32_bf16 v[106:109], v[142:145], v[208:211], v[106:109]
	v_mfma_f32_16x16x32_bf16 v[94:97], v[134:137], v[216:219], v[94:97]
	v_mfma_f32_16x16x32_bf16 v[90:93], v[142:145], v[216:219], v[90:93]
	v_mfma_f32_16x16x32_bf16 v[78:81], v[134:137], v[224:227], v[78:81]
	v_mfma_f32_16x16x32_bf16 v[74:77], v[142:145], v[224:227], v[74:77]
	v_mfma_f32_16x16x32_bf16 v[118:121], v[146:149], v[196:199], v[118:121]
	v_mfma_f32_16x16x32_bf16 v[114:117], v[170:173], v[196:199], v[114:117]
	v_mfma_f32_16x16x32_bf16 v[102:105], v[146:149], v[204:207], v[102:105]
	v_mfma_f32_16x16x32_bf16 v[98:101], v[170:173], v[204:207], v[98:101]
	v_mfma_f32_16x16x32_bf16 v[86:89], v[146:149], v[212:215], v[86:89]
	v_mfma_f32_16x16x32_bf16 v[82:85], v[170:173], v[212:215], v[82:85]
	v_mfma_f32_16x16x32_bf16 v[70:73], v[146:149], v[220:223], v[70:73]
	v_mfma_f32_16x16x32_bf16 v[66:69], v[170:173], v[220:223], v[66:69]
	v_mfma_f32_16x16x32_bf16 v[118:121], v[150:153], v[200:203], v[118:121]
	v_mfma_f32_16x16x32_bf16 v[114:117], v[192:195], v[200:203], v[114:117]
	v_mfma_f32_16x16x32_bf16 v[102:105], v[150:153], v[208:211], v[102:105]
	v_mfma_f32_16x16x32_bf16 v[98:101], v[192:195], v[208:211], v[98:101]
	v_mfma_f32_16x16x32_bf16 v[86:89], v[150:153], v[216:219], v[86:89]
	v_mfma_f32_16x16x32_bf16 v[82:85], v[192:195], v[216:219], v[82:85]
	v_mfma_f32_16x16x32_bf16 v[70:73], v[150:153], v[224:227], v[70:73]
	v_mfma_f32_16x16x32_bf16 v[66:69], v[192:195], v[224:227], v[66:69]
	s_barrier
	s_setprio 0
	s_add_i32 s28, s54, s35
	v_lshl_add_u64 v[174:175], v[174:175], 0, s[18:19]
	s_mov_b32 m0, s28
	ds_read_b128 v[196:199], v189 offset:49152
	ds_read_b128 v[200:203], v189 offset:50176
	ds_read_b128 v[204:207], v189 offset:51200
	ds_read_b128 v[208:211], v189 offset:52224
	ds_read_b128 v[212:215], v189 offset:53248
	ds_read_b128 v[216:219], v189 offset:54272
	ds_read_b128 v[220:223], v189 offset:55296
	ds_read_b128 v[224:227], v189 offset:56320
	global_load_lds_dwordx4 v[174:175], off
	s_add_i32 m0, s28, 0x2000
	s_add_u32 s26, s26, 0x2b0080
	v_lshl_add_u64 v[174:175], v[228:229], 0, s[18:19]
	s_addc_u32 s27, s27, 0
	s_add_i32 s28, s55, s35
	global_load_lds_dwordx4 v[174:175], off
	s_mov_b32 m0, s28
	s_nop 0
	global_load_lds_dwordx4 v156, s[26:27]
	s_add_i32 m0, s28, 0x2000
	s_nop 0
	global_load_lds_dwordx4 v160, s[26:27]
	v_lshl_add_u64 v[174:175], v[230:231], 0, s[18:19]
	s_mov_b32 m0, s41
	s_nop 0
	global_load_lds_dwordx4 v[174:175], off
	v_lshl_add_u64 v[174:175], v[232:233], 0, s[18:19]
	s_mov_b32 m0, s42
	s_nop 0
	global_load_lds_dwordx4 v[174:175], off
	s_waitcnt vmcnt(8)
	s_waitcnt lgkmcnt(0)
	s_setprio 1
	s_barrier
	v_mfma_f32_16x16x32_bf16 v[62:65], v[130:133], v[196:199], v[62:65]
	v_mfma_f32_16x16x32_bf16 v[58:61], v[138:141], v[196:199], v[58:61]
	v_mfma_f32_16x16x32_bf16 v[46:49], v[130:133], v[204:207], v[46:49]
	v_mfma_f32_16x16x32_bf16 v[42:45], v[138:141], v[204:207], v[42:45]
	v_mfma_f32_16x16x32_bf16 v[30:33], v[130:133], v[212:215], v[30:33]
	v_mfma_f32_16x16x32_bf16 v[26:29], v[138:141], v[212:215], v[26:29]
	v_mfma_f32_16x16x32_bf16 v[14:17], v[130:133], v[220:223], v[14:17]
	v_mfma_f32_16x16x32_bf16 v[10:13], v[138:141], v[220:223], v[10:13]
	v_mfma_f32_16x16x32_bf16 v[62:65], v[134:137], v[200:203], v[62:65]
	v_mfma_f32_16x16x32_bf16 v[58:61], v[142:145], v[200:203], v[58:61]
	v_mfma_f32_16x16x32_bf16 v[46:49], v[134:137], v[208:211], v[46:49]
	v_mfma_f32_16x16x32_bf16 v[42:45], v[142:145], v[208:211], v[42:45]
	v_mfma_f32_16x16x32_bf16 v[30:33], v[134:137], v[216:219], v[30:33]
	v_mfma_f32_16x16x32_bf16 v[26:29], v[142:145], v[216:219], v[26:29]
	v_mfma_f32_16x16x32_bf16 v[14:17], v[134:137], v[224:227], v[14:17]
	v_mfma_f32_16x16x32_bf16 v[10:13], v[142:145], v[224:227], v[10:13]
	v_mfma_f32_16x16x32_bf16 v[54:57], v[146:149], v[196:199], v[54:57]
	v_mfma_f32_16x16x32_bf16 v[50:53], v[170:173], v[196:199], v[50:53]
	v_mfma_f32_16x16x32_bf16 v[38:41], v[146:149], v[204:207], v[38:41]
	v_mfma_f32_16x16x32_bf16 v[34:37], v[170:173], v[204:207], v[34:37]
	v_mfma_f32_16x16x32_bf16 v[22:25], v[146:149], v[212:215], v[22:25]
	v_mfma_f32_16x16x32_bf16 v[18:21], v[170:173], v[212:215], v[18:21]
	v_mfma_f32_16x16x32_bf16 v[6:9], v[146:149], v[220:223], v[6:9]
	v_mfma_f32_16x16x32_bf16 v[2:5], v[170:173], v[220:223], v[2:5]
	v_mfma_f32_16x16x32_bf16 v[54:57], v[150:153], v[200:203], v[54:57]
	v_mfma_f32_16x16x32_bf16 v[50:53], v[192:195], v[200:203], v[50:53]
	v_mfma_f32_16x16x32_bf16 v[38:41], v[150:153], v[208:211], v[38:41]
	v_mfma_f32_16x16x32_bf16 v[34:37], v[192:195], v[208:211], v[34:37]
	v_mfma_f32_16x16x32_bf16 v[22:25], v[150:153], v[216:219], v[22:25]
	v_mfma_f32_16x16x32_bf16 v[18:21], v[192:195], v[216:219], v[18:21]
	v_mfma_f32_16x16x32_bf16 v[6:9], v[150:153], v[224:227], v[6:9]
	v_mfma_f32_16x16x32_bf16 v[2:5], v[192:195], v[224:227], v[2:5]
	s_barrier
	s_setprio 0
	s_add_i32 s53, s53, 2
	s_add_u32 s24, s24, 0x100
	s_addc_u32 s25, s25, 0
	s_add_u32 s51, s51, 0x100
	s_addc_u32 s52, s52, 0
	s_cmpk_gt_u32 s53, 0xa9
	s_cbranch_scc0 .LBB0_2060
	s_and_b64 vcc, exec, s[20:21]
	s_cbranch_vccz .LBB0_2063
	s_barrier

; #define PG8_STAGE(bufoff, gbase, voff) do { _Pragma("unroll") for (int _i = 0; _i < 2; ++_i) \
;         __builtin_amdgcn_global_load_lds((const unsigned*)((const char*)(gbase) + (voff)[_i]), (LAS unsigned*)(lds + (bufoff) + ldsw + _i * 8192), 16, 0, 0); } while (0)
; #define PG8_LDA(dst, b, h) do { _Pragma("unroll") for (int m = 0; m < 4; ++m) _Pragma("unroll") for (int k = 0; k < 2; ++k) dst[m][k] = *(const LAS bf16x8*)(lds + PG8_SA(b, h) + aoff + m * 2048 + k * 1024); } while (0)
; #define PG8_LDB(dst, b, h) do { _Pragma("unroll") for (int n = 0; n < 2; ++n) _Pragma("unroll") for (int k = 0; k < 2; ++k) dst[n][k] = *(const LAS bf16x8*)(lds + PG8_SB(b, h) + boff + n * 2048 + k * 1024); } while (0)
; #define PG8_MMA(ai, bj, At, Bt) do { __builtin_amdgcn_s_setprio(1); _Pragma("unroll") for (int m = 0; m < 4; ++m) _Pragma("unroll") for (int n = 0; n < 2; ++n) _Pragma("unroll") for (int k = 0; k < 2; ++k) \
;         acc[ai][bj][m][n] = __builtin_amdgcn_mfma_f32_16x16x32_bf16(Bt[n][k], At[m][k], acc[ai][bj][m][n], 0, 0, 0); __builtin_amdgcn_s_setprio(0); } while (0)
; #define PG8_BAR __builtin_amdgcn_s_barrier()
; template <class Epi, class Sched, bool ALIGN_EPI = true, bool SP2 = true>
; __device__ __forceinline__ void gemm_phase(LAS unsigned char* lds, const Gemm g, const Sched& S, const Epi& E) {
;     ...
;         const char* nA = has_next ? PG8_ABASE(nxt) : cA; const char* nB = has_next ? PG8_BBASE(nxt) : cB;
;         for (int t = 0; t < nt; t += 2) {
;             const bool last = (t == nt - 2);
;             const char* a1 = cA + (size_t)(t + 1) * kstep;
;             const char* a2 = last ? nA : cA + (size_t)(t + 2) * kstep; const char* b2 = last ? nB : cB + (size_t)(t + 2) * kstep;
;             const char* a3 = a2 + kstep; const char* b3 = b2 + kstep;
;             if (last && has_next) S.a_ready(nxt);
;             if constexpr (SP2) {
;             PG8_LDB(B0, 0, 0); PG8_LDB(B1, 0, 1); PG8_SCHED; PG8_LDA(At, 0, 0); PG8_STAGE(PG8_SA(1, 1), a1 + hstep, voffA);
;             PG8_WAIT_V(8); PG8_WAIT_L(0); PG8_BAR; PG8_MMA(0, 0, At, B0); PG8_MMA(0, 1, At, B1); PG8_BAR; PG8_SCHED;
;             PG8_LDA(At, 0, 1); PG8_STAGE(PG8_SB(0, 0), b2, voffB); PG8_STAGE(PG8_SB(0, 1), b2 + hstep, voffB); PG8_STAGE(PG8_SA(0, 0), a2, voffA);
;             PG8_WAIT_V(8); PG8_WAIT_L(0); PG8_BAR; PG8_MMA(1, 0, At, B0); PG8_MMA(1, 1, At, B1); PG8_BAR; PG8_SCHED;
.LBB0_2100:
	s_add_u32 s31, s24, s30
	s_addc_u32 s38, s25, 0
	s_add_u32 s36, s31, 0x100
	s_addc_u32 s37, s38, 0
	s_and_b64 s[34:35], s[28:29], exec
	s_cselect_b32 s35, s15, s37
	s_cselect_b32 s34, s57, s36
	s_add_u32 s30, s22, s30
	s_addc_u32 s36, s23, 0
	s_add_u32 s30, s30, 0x100
	s_addc_u32 s36, s36, 0
	s_and_b64 s[28:29], s[28:29], exec
	s_cselect_b32 s37, s13, s36
	s_cselect_b32 s36, s58, s30
	s_add_u32 s40, s31, 0x10080
	ds_read_b128 v[142:145], v148
	ds_read_b128 v[152:155], v148 offset:1024
	ds_read_b128 v[156:159], v148 offset:2048
	ds_read_b128 v[160:163], v148 offset:3072
	ds_read_b128 v[164:167], v149
	ds_read_b128 v[168:171], v149 offset:1024
	ds_read_b128 v[172:175], v149 offset:2048
	ds_read_b128 v[176:179], v149 offset:3072
	s_addc_u32 s41, s38, 0
	s_add_i32 s66, s54, s46
	s_add_i32 m0, s21, 0xc000
	s_add_i32 s69, s21, 0xe000
	s_add_i32 s63, s66, 0x2000
	s_add_u32 s38, s36, 0x10000
	s_addc_u32 s39, s37, 0
	s_add_i32 s65, s55, s46
	s_add_i32 s64, s65, 0x2000
	s_add_i32 s62, 0, 0x18000
	s_add_i32 s61, 0, 0x1c000
	s_add_u32 s30, s34, 0x10000
	s_addc_u32 s31, s35, 0
	s_add_i32 s60, s62, s46
	s_add_i32 s59, s60, 0x2000
	s_add_u32 s28, s36, 0x10080
	s_addc_u32 s29, s37, 0
	s_add_i32 s68, s61, s46
	s_add_i32 s67, s68, 0x2000
	ds_read_b128 v[180:183], v150
	ds_read_b128 v[184:187], v150 offset:1024
	ds_read_b128 v[188:191], v150 offset:2048
	ds_read_b128 v[192:195], v150 offset:3072
	ds_read_b128 v[196:199], v150 offset:4096
	ds_read_b128 v[200:203], v150 offset:5120
	ds_read_b128 v[204:207], v150 offset:6144
	ds_read_b128 v[208:211], v150 offset:7168
	global_load_lds_dwordx4 v130, s[40:41]
	s_mov_b32 m0, s69
	s_nop 0
	global_load_lds_dwordx4 v134, s[40:41]
	s_waitcnt vmcnt(8)
	s_waitcnt lgkmcnt(0)
	s_setprio 1
	s_barrier
	v_mfma_f32_16x16x32_bf16 v[126:129], v[142:145], v[180:183], v[126:129]
	v_mfma_f32_16x16x32_bf16 v[122:125], v[156:159], v[180:183], v[122:125]
	v_mfma_f32_16x16x32_bf16 v[118:121], v[142:145], v[188:191], v[118:121]
	v_mfma_f32_16x16x32_bf16 v[110:113], v[156:159], v[188:191], v[110:113]
	v_mfma_f32_16x16x32_bf16 v[102:105], v[142:145], v[196:199], v[102:105]
	v_mfma_f32_16x16x32_bf16 v[94:97], v[156:159], v[196:199], v[94:97]
	v_mfma_f32_16x16x32_bf16 v[86:89], v[142:145], v[204:207], v[86:89]
	v_mfma_f32_16x16x32_bf16 v[78:81], v[156:159], v[204:207], v[78:81]
	v_mfma_f32_16x16x32_bf16 v[126:129], v[152:155], v[184:187], v[126:129]
	v_mfma_f32_16x16x32_bf16 v[122:125], v[160:163], v[184:187], v[122:125]
	v_mfma_f32_16x16x32_bf16 v[118:121], v[152:155], v[192:195], v[118:121]
	v_mfma_f32_16x16x32_bf16 v[110:113], v[160:163], v[192:195], v[110:113]
	v_mfma_f32_16x16x32_bf16 v[102:105], v[152:155], v[200:203], v[102:105]
	v_mfma_f32_16x16x32_bf16 v[94:97], v[160:163], v[200:203], v[94:97]
	v_mfma_f32_16x16x32_bf16 v[86:89], v[152:155], v[208:211], v[86:89]
	v_mfma_f32_16x16x32_bf16 v[78:81], v[160:163], v[208:211], v[78:81]
	v_mfma_f32_16x16x32_bf16 v[114:117], v[164:167], v[180:183], v[114:117]
	v_mfma_f32_16x16x32_bf16 v[106:109], v[172:175], v[180:183], v[106:109]
	v_mfma_f32_16x16x32_bf16 v[98:101], v[164:167], v[188:191], v[98:101]
	v_mfma_f32_16x16x32_bf16 v[90:93], v[172:175], v[188:191], v[90:93]
	v_mfma_f32_16x16x32_bf16 v[82:85], v[164:167], v[196:199], v[82:85]
	v_mfma_f32_16x16x32_bf16 v[74:77], v[172:175], v[196:199], v[74:77]
	v_mfma_f32_16x16x32_bf16 v[70:73], v[164:167], v[204:207], v[70:73]
	v_mfma_f32_16x16x32_bf16 v[66:69], v[172:175], v[204:207], v[66:69]
	v_mfma_f32_16x16x32_bf16 v[114:117], v[168:171], v[184:187], v[114:117]
	v_mfma_f32_16x16x32_bf16 v[106:109], v[176:179], v[184:187], v[106:109]
	v_mfma_f32_16x16x32_bf16 v[98:101], v[168:171], v[192:195], v[98:101]
	v_mfma_f32_16x16x32_bf16 v[90:93], v[176:179], v[192:195], v[90:93]
	v_mfma_f32_16x16x32_bf16 v[82:85], v[168:171], v[200:203], v[82:85]
	v_mfma_f32_16x16x32_bf16 v[74:77], v[176:179], v[200:203], v[74:77]
	v_mfma_f32_16x16x32_bf16 v[70:73], v[168:171], v[208:211], v[70:73]
	v_mfma_f32_16x16x32_bf16 v[66:69], v[176:179], v[208:211], v[66:69]
	s_barrier
	s_setprio 0
	s_mov_b32 m0, s66
	v_lshl_add_u64 v[212:213], s[36:37], 0, v[132:133]
	ds_read_b128 v[180:183], v150 offset:16384
	ds_read_b128 v[184:187], v150 offset:17408
	ds_read_b128 v[188:191], v150 offset:18432
	ds_read_b128 v[192:195], v150 offset:19456
	ds_read_b128 v[196:199], v150 offset:20480
	ds_read_b128 v[200:203], v150 offset:21504
	ds_read_b128 v[204:207], v150 offset:22528
	ds_read_b128 v[208:211], v150 offset:23552
	global_load_lds_dwordx4 v[212:213], off
	v_lshl_add_u64 v[214:215], s[36:37], 0, v[136:137]
	s_mov_b32 m0, s63
	s_nop 0
	global_load_lds_dwordx4 v[214:215], off
	s_mov_b32 m0, s65
	v_lshl_add_u64 v[218:219], s[34:35], 0, v[134:135]
	global_load_lds_dwordx4 v132, s[38:39]
	s_mov_b32 m0, s64
	s_nop 0
	global_load_lds_dwordx4 v136, s[38:39]
	v_lshl_add_u64 v[216:217], s[34:35], 0, v[130:131]
	s_mov_b32 m0, s21
	s_nop 0
	global_load_lds_dwordx4 v[216:217], off
	s_mov_b32 m0, s47
	s_nop 0
	global_load_lds_dwordx4 v[218:219], off
	s_waitcnt vmcnt(8)
	s_waitcnt lgkmcnt(0)
	s_setprio 1
	s_barrier
; #define PG8_STAGE(bufoff, gbase, voff) do { _Pragma("unroll") for (int _i = 0; _i < 2; ++_i) \
;         __builtin_amdgcn_global_load_lds((const unsigned*)((const char*)(gbase) + (voff)[_i]), (LAS unsigned*)(lds + (bufoff) + ldsw + _i * 8192), 16, 0, 0); } while (0)
; #define PG8_LDA(dst, b, h) do { _Pragma("unroll") for (int m = 0; m < 4; ++m) _Pragma("unroll") for (int k = 0; k < 2; ++k) dst[m][k] = *(const LAS bf16x8*)(lds + PG8_SA(b, h) + aoff + m * 2048 + k * 1024); } while (0)
; #define PG8_LDB(dst, b, h) do { _Pragma("unroll") for (int n = 0; n < 2; ++n) _Pragma("unroll") for (int k = 0; k < 2; ++k) dst[n][k] = *(const LAS bf16x8*)(lds + PG8_SB(b, h) + boff + n * 2048 + k * 1024); } while (0)
; #define PG8_MMA(ai, bj, At, Bt) do { __builtin_amdgcn_s_setprio(1); _Pragma("unroll") for (int m = 0; m < 4; ++m) _Pragma("unroll") for (int n = 0; n < 2; ++n) _Pragma("unroll") for (int k = 0; k < 2; ++k) \
;         acc[ai][bj][m][n] = __builtin_amdgcn_mfma_f32_16x16x32_bf16(Bt[n][k], At[m][k], acc[ai][bj][m][n], 0, 0, 0); __builtin_amdgcn_s_setprio(0); } while (0)
; #define PG8_WAIT_V(n) asm volatile("s_waitcnt vmcnt(" #n ")" ::: "memory")
; #define PG8_WAIT_L(n) asm volatile("s_waitcnt lgkmcnt(" #n ")" ::: "memory")
; #define PG8_BAR __builtin_amdgcn_s_barrier()
; #define PG8_SCHED __builtin_amdgcn_sched_barrier(0)
; template <class Epi, class Sched, bool ALIGN_EPI = true, bool SP2 = true>
; __device__ __forceinline__ void gemm_phase(LAS unsigned char* lds, const Gemm g, const Sched& S, const Epi& E) {
;     ...
;             PG8_WAIT_V(8); PG8_WAIT_L(0); PG8_BAR; PG8_MMA(1, 0, At, B0); PG8_MMA(1, 1, At, B1); PG8_BAR; PG8_SCHED;
;             PG8_LDB(B0, 1, 0); PG8_LDB(B1, 1, 1); PG8_SCHED; PG8_LDA(At, 1, 0); PG8_STAGE(PG8_SA(0, 1), a2 + hstep, voffA);
;             PG8_WAIT_V(8); PG8_WAIT_L(0); PG8_BAR; PG8_MMA(0, 0, At, B0); PG8_MMA(0, 1, At, B1); PG8_BAR; PG8_SCHED;
	v_mfma_f32_16x16x32_bf16 v[62:65], v[142:145], v[180:183], v[62:65]
	v_mfma_f32_16x16x32_bf16 v[58:61], v[156:159], v[180:183], v[58:61]
	v_mfma_f32_16x16x32_bf16 v[54:57], v[142:145], v[188:191], v[54:57]
	v_mfma_f32_16x16x32_bf16 v[46:49], v[156:159], v[188:191], v[46:49]
	v_mfma_f32_16x16x32_bf16 v[38:41], v[142:145], v[196:199], v[38:41]
	v_mfma_f32_16x16x32_bf16 v[30:33], v[156:159], v[196:199], v[30:33]
	v_mfma_f32_16x16x32_bf16 v[22:25], v[142:145], v[204:207], v[22:25]
	v_mfma_f32_16x16x32_bf16 v[14:17], v[156:159], v[204:207], v[14:17]
	v_mfma_f32_16x16x32_bf16 v[62:65], v[152:155], v[184:187], v[62:65]
	v_mfma_f32_16x16x32_bf16 v[58:61], v[160:163], v[184:187], v[58:61]
	v_mfma_f32_16x16x32_bf16 v[54:57], v[152:155], v[192:195], v[54:57]
	v_mfma_f32_16x16x32_bf16 v[46:49], v[160:163], v[192:195], v[46:49]
	v_mfma_f32_16x16x32_bf16 v[38:41], v[152:155], v[200:203], v[38:41]
	v_mfma_f32_16x16x32_bf16 v[30:33], v[160:163], v[200:203], v[30:33]
	v_mfma_f32_16x16x32_bf16 v[22:25], v[152:155], v[208:211], v[22:25]
	v_mfma_f32_16x16x32_bf16 v[14:17], v[160:163], v[208:211], v[14:17]
	v_mfma_f32_16x16x32_bf16 v[50:53], v[164:167], v[180:183], v[50:53]
	v_mfma_f32_16x16x32_bf16 v[42:45], v[172:175], v[180:183], v[42:45]
	v_mfma_f32_16x16x32_bf16 v[34:37], v[164:167], v[188:191], v[34:37]
	v_mfma_f32_16x16x32_bf16 v[26:29], v[172:175], v[188:191], v[26:29]
	v_mfma_f32_16x16x32_bf16 v[18:21], v[164:167], v[196:199], v[18:21]
	v_mfma_f32_16x16x32_bf16 v[10:13], v[172:175], v[196:199], v[10:13]
	v_mfma_f32_16x16x32_bf16 v[6:9], v[164:167], v[204:207], v[6:9]
	v_mfma_f32_16x16x32_bf16 v[2:5], v[172:175], v[204:207], v[2:5]
	v_mfma_f32_16x16x32_bf16 v[50:53], v[168:171], v[184:187], v[50:53]
	v_mfma_f32_16x16x32_bf16 v[42:45], v[176:179], v[184:187], v[42:45]
	v_mfma_f32_16x16x32_bf16 v[34:37], v[168:171], v[192:195], v[34:37]
	v_mfma_f32_16x16x32_bf16 v[26:29], v[176:179], v[192:195], v[26:29]
	v_mfma_f32_16x16x32_bf16 v[18:21], v[168:171], v[200:203], v[18:21]
	v_mfma_f32_16x16x32_bf16 v[10:13], v[176:179], v[200:203], v[10:13]
	v_mfma_f32_16x16x32_bf16 v[6:9], v[168:171], v[208:211], v[6:9]
	v_mfma_f32_16x16x32_bf16 v[2:5], v[176:179], v[208:211], v[2:5]
	s_barrier
	s_setprio 0
	v_add_u32_e32 v151, s62, v147
	ds_read_b128 v[142:145], v151
	ds_read_b128 v[152:155], v151 offset:1024
	ds_read_b128 v[156:159], v151 offset:2048
	ds_read_b128 v[160:163], v151 offset:3072
	v_add_u32_e32 v151, s61, v147
	ds_read_b128 v[164:167], v151
	ds_read_b128 v[168:171], v151 offset:1024
	ds_read_b128 v[172:175], v151 offset:2048
	ds_read_b128 v[176:179], v151 offset:3072
	s_mov_b32 m0, s48
	ds_read_b128 v[180:183], v150 offset:32768
	ds_read_b128 v[184:187], v150 offset:33792
	ds_read_b128 v[188:191], v150 offset:34816
	ds_read_b128 v[192:195], v150 offset:35840
	ds_read_b128 v[196:199], v150 offset:36864
	ds_read_b128 v[200:203], v150 offset:37888
	ds_read_b128 v[204:207], v150 offset:38912
	ds_read_b128 v[208:211], v150 offset:39936
	global_load_lds_dwordx4 v130, s[30:31]
	s_mov_b32 m0, s49
	s_nop 0
	global_load_lds_dwordx4 v134, s[30:31]
	s_waitcnt vmcnt(8)
	s_waitcnt lgkmcnt(0)
	s_setprio 1
	s_barrier
	v_mfma_f32_16x16x32_bf16 v[126:129], v[142:145], v[180:183], v[126:129]
	v_mfma_f32_16x16x32_bf16 v[122:125], v[156:159], v[180:183], v[122:125]
	v_mfma_f32_16x16x32_bf16 v[118:121], v[142:145], v[188:191], v[118:121]
	v_mfma_f32_16x16x32_bf16 v[110:113], v[156:159], v[188:191], v[110:113]
	v_mfma_f32_16x16x32_bf16 v[102:105], v[142:145], v[196:199], v[102:105]
	v_mfma_f32_16x16x32_bf16 v[94:97], v[156:159], v[196:199], v[94:97]
	v_mfma_f32_16x16x32_bf16 v[86:89], v[142:145], v[204:207], v[86:89]
	v_mfma_f32_16x16x32_bf16 v[78:81], v[156:159], v[204:207], v[78:81]
	v_mfma_f32_16x16x32_bf16 v[126:129], v[152:155], v[184:187], v[126:129]
	v_mfma_f32_16x16x32_bf16 v[122:125], v[160:163], v[184:187], v[122:125]
	v_mfma_f32_16x16x32_bf16 v[118:121], v[152:155], v[192:195], v[118:121]
	v_mfma_f32_16x16x32_bf16 v[110:113], v[160:163], v[192:195], v[110:113]
	v_mfma_f32_16x16x32_bf16 v[102:105], v[152:155], v[200:203], v[102:105]
	v_mfma_f32_16x16x32_bf16 v[94:97], v[160:163], v[200:203], v[94:97]
	v_mfma_f32_16x16x32_bf16 v[86:89], v[152:155], v[208:211], v[86:89]
	v_mfma_f32_16x16x32_bf16 v[78:81], v[160:163], v[208:211], v[78:81]
	v_mfma_f32_16x16x32_bf16 v[114:117], v[164:167], v[180:183], v[114:117]
	v_mfma_f32_16x16x32_bf16 v[106:109], v[172:175], v[180:183], v[106:109]
	v_mfma_f32_16x16x32_bf16 v[98:101], v[164:167], v[188:191], v[98:101]
	v_mfma_f32_16x16x32_bf16 v[90:93], v[172:175], v[188:191], v[90:93]
	v_mfma_f32_16x16x32_bf16 v[82:85], v[164:167], v[196:199], v[82:85]
	v_mfma_f32_16x16x32_bf16 v[74:77], v[172:175], v[196:199], v[74:77]
	v_mfma_f32_16x16x32_bf16 v[70:73], v[164:167], v[204:207], v[70:73]
	v_mfma_f32_16x16x32_bf16 v[66:69], v[172:175], v[204:207], v[66:69]
	v_mfma_f32_16x16x32_bf16 v[114:117], v[168:171], v[184:187], v[114:117]
	v_mfma_f32_16x16x32_bf16 v[106:109], v[176:179], v[184:187], v[106:109]
	v_mfma_f32_16x16x32_bf16 v[98:101], v[168:171], v[192:195], v[98:101]
	v_mfma_f32_16x16x32_bf16 v[90:93], v[176:179], v[192:195], v[90:93]
	v_mfma_f32_16x16x32_bf16 v[82:85], v[168:171], v[200:203], v[82:85]
	v_mfma_f32_16x16x32_bf16 v[74:77], v[176:179], v[200:203], v[74:77]
	v_mfma_f32_16x16x32_bf16 v[70:73], v[168:171], v[208:211], v[70:73]
	v_mfma_f32_16x16x32_bf16 v[66:69], v[176:179], v[208:211], v[66:69]
	s_barrier
; #define PG8_STAGE(bufoff, gbase, voff) do { _Pragma("unroll") for (int _i = 0; _i < 2; ++_i) \
;         __builtin_amdgcn_global_load_lds((const unsigned*)((const char*)(gbase) + (voff)[_i]), (LAS unsigned*)(lds + (bufoff) + ldsw + _i * 8192), 16, 0, 0); } while (0)
; #define PG8_LDA(dst, b, h) do { _Pragma("unroll") for (int m = 0; m < 4; ++m) _Pragma("unroll") for (int k = 0; k < 2; ++k) dst[m][k] = *(const LAS bf16x8*)(lds + PG8_SA(b, h) + aoff + m * 2048 + k * 1024); } while (0)
; #define PG8_MMA(ai, bj, At, Bt) do { __builtin_amdgcn_s_setprio(1); _Pragma("unroll") for (int m = 0; m < 4; ++m) _Pragma("unroll") for (int n = 0; n < 2; ++n) _Pragma("unroll") for (int k = 0; k < 2; ++k) \
;         acc[ai][bj][m][n] = __builtin_amdgcn_mfma_f32_16x16x32_bf16(Bt[n][k], At[m][k], acc[ai][bj][m][n], 0, 0, 0); __builtin_amdgcn_s_setprio(0); } while (0)
; #define PG8_WAIT_V(n) asm volatile("s_waitcnt vmcnt(" #n ")" ::: "memory")
; #define PG8_WAIT_L(n) asm volatile("s_waitcnt lgkmcnt(" #n ")" ::: "memory")
; #define PG8_BAR __builtin_amdgcn_s_barrier()
; #define PG8_SCHED __builtin_amdgcn_sched_barrier(0)
; template <class Epi, class Sched, bool ALIGN_EPI = true, bool SP2 = true>
; __device__ __forceinline__ void gemm_phase(LAS unsigned char* lds, const Gemm g, const Sched& S, const Epi& E) {
;     ...
;             PG8_LDA(At, 1, 1); PG8_STAGE(PG8_SB(1, 0), b3, voffB); PG8_STAGE(PG8_SB(1, 1), b3 + hstep, voffB); PG8_STAGE(PG8_SA(1, 0), a3, voffA);
;             PG8_WAIT_V(8); PG8_WAIT_L(0); PG8_BAR; PG8_MMA(1, 0, At, B0); PG8_MMA(1, 1, At, B1); PG8_BAR; PG8_SCHED;
	s_setprio 0
	s_mov_b32 m0, s60
	v_lshl_add_u64 v[212:213], v[212:213], 0, s[6:7]
	ds_read_b128 v[180:183], v150 offset:49152
	ds_read_b128 v[184:187], v150 offset:50176
	ds_read_b128 v[188:191], v150 offset:51200
	ds_read_b128 v[192:195], v150 offset:52224
	ds_read_b128 v[196:199], v150 offset:53248
	ds_read_b128 v[200:203], v150 offset:54272
	ds_read_b128 v[204:207], v150 offset:55296
	ds_read_b128 v[208:211], v150 offset:56320
	global_load_lds_dwordx4 v[212:213], off
	v_lshl_add_u64 v[212:213], v[214:215], 0, s[6:7]
	s_mov_b32 m0, s59
	s_nop 0
	global_load_lds_dwordx4 v[212:213], off
	s_mov_b32 m0, s68
	s_nop 0
	global_load_lds_dwordx4 v132, s[28:29]
	s_mov_b32 m0, s67
	s_nop 0
	global_load_lds_dwordx4 v136, s[28:29]
	v_lshl_add_u64 v[212:213], v[216:217], 0, s[6:7]
	s_mov_b32 m0, s51
	s_nop 0
	global_load_lds_dwordx4 v[212:213], off
	v_lshl_add_u64 v[212:213], v[218:219], 0, s[6:7]
	s_mov_b32 m0, s52
	s_nop 0
	global_load_lds_dwordx4 v[212:213], off
	s_waitcnt vmcnt(8)
	s_waitcnt lgkmcnt(0)
	s_setprio 1
	s_barrier
	v_mfma_f32_16x16x32_bf16 v[62:65], v[142:145], v[180:183], v[62:65]
	v_mfma_f32_16x16x32_bf16 v[58:61], v[156:159], v[180:183], v[58:61]
	v_mfma_f32_16x16x32_bf16 v[54:57], v[142:145], v[188:191], v[54:57]
	v_mfma_f32_16x16x32_bf16 v[46:49], v[156:159], v[188:191], v[46:49]
	v_mfma_f32_16x16x32_bf16 v[38:41], v[142:145], v[196:199], v[38:41]
	v_mfma_f32_16x16x32_bf16 v[30:33], v[156:159], v[196:199], v[30:33]
	v_mfma_f32_16x16x32_bf16 v[22:25], v[142:145], v[204:207], v[22:25]
	v_mfma_f32_16x16x32_bf16 v[14:17], v[156:159], v[204:207], v[14:17]
	v_mfma_f32_16x16x32_bf16 v[62:65], v[152:155], v[184:187], v[62:65]
	v_mfma_f32_16x16x32_bf16 v[58:61], v[160:163], v[184:187], v[58:61]
	v_mfma_f32_16x16x32_bf16 v[54:57], v[152:155], v[192:195], v[54:57]
	v_mfma_f32_16x16x32_bf16 v[46:49], v[160:163], v[192:195], v[46:49]
	v_mfma_f32_16x16x32_bf16 v[38:41], v[152:155], v[200:203], v[38:41]
	v_mfma_f32_16x16x32_bf16 v[30:33], v[160:163], v[200:203], v[30:33]
	v_mfma_f32_16x16x32_bf16 v[22:25], v[152:155], v[208:211], v[22:25]
	v_mfma_f32_16x16x32_bf16 v[14:17], v[160:163], v[208:211], v[14:17]
	v_mfma_f32_16x16x32_bf16 v[50:53], v[164:167], v[180:183], v[50:53]
	v_mfma_f32_16x16x32_bf16 v[42:45], v[172:175], v[180:183], v[42:45]
	v_mfma_f32_16x16x32_bf16 v[34:37], v[164:167], v[188:191], v[34:37]
	v_mfma_f32_16x16x32_bf16 v[26:29], v[172:175], v[188:191], v[26:29]
	v_mfma_f32_16x16x32_bf16 v[18:21], v[164:167], v[196:199], v[18:21]
	v_mfma_f32_16x16x32_bf16 v[10:13], v[172:175], v[196:199], v[10:13]
	v_mfma_f32_16x16x32_bf16 v[6:9], v[164:167], v[204:207], v[6:9]
	v_mfma_f32_16x16x32_bf16 v[2:5], v[172:175], v[204:207], v[2:5]
	v_mfma_f32_16x16x32_bf16 v[50:53], v[168:171], v[184:187], v[50:53]
	v_mfma_f32_16x16x32_bf16 v[42:45], v[176:179], v[184:187], v[42:45]
	v_mfma_f32_16x16x32_bf16 v[34:37], v[168:171], v[192:195], v[34:37]
	v_mfma_f32_16x16x32_bf16 v[26:29], v[176:179], v[192:195], v[26:29]
	v_mfma_f32_16x16x32_bf16 v[18:21], v[168:171], v[200:203], v[18:21]
	v_mfma_f32_16x16x32_bf16 v[10:13], v[176:179], v[200:203], v[10:13]
	v_mfma_f32_16x16x32_bf16 v[6:9], v[168:171], v[208:211], v[6:9]
	v_mfma_f32_16x16x32_bf16 v[2:5], v[176:179], v[208:211], v[2:5]
	s_barrier
	s_setprio 0
	s_movk_i32 s30, 0x100
	s_andn2_b64 vcc, exec, s[26:27]
	s_mov_b64 s[28:29], -1
	s_mov_b64 s[26:27], 0
	s_cbranch_vccz .LBB0_2100
	s_and_b64 vcc, exec, s[10:11]
	s_cbranch_vccz .LBB0_2103
	s_barrier

; #define PG8_STAGE(bufoff, gbase, voff) do { _Pragma("unroll") for (int _i = 0; _i < 2; ++_i) \
;         __builtin_amdgcn_global_load_lds((const unsigned*)((const char*)(gbase) + (voff)[_i]), (LAS unsigned*)(lds + (bufoff) + ldsw + _i * 8192), 16, 0, 0); } while (0)
; #define PG8_LDA(dst, b, h) do { _Pragma("unroll") for (int m = 0; m < 4; ++m) _Pragma("unroll") for (int k = 0; k < 2; ++k) dst[m][k] = *(const LAS bf16x8*)(lds + PG8_SA(b, h) + aoff + m * 2048 + k * 1024); } while (0)
; #define PG8_LDB(dst, b, h) do { _Pragma("unroll") for (int n = 0; n < 2; ++n) _Pragma("unroll") for (int k = 0; k < 2; ++k) dst[n][k] = *(const LAS bf16x8*)(lds + PG8_SB(b, h) + boff + n * 2048 + k * 1024); } while (0)
; #define PG8_MMA(ai, bj, At, Bt) do { __builtin_amdgcn_s_setprio(1); _Pragma("unroll") for (int m = 0; m < 4; ++m) _Pragma("unroll") for (int n = 0; n < 2; ++n) _Pragma("unroll") for (int k = 0; k < 2; ++k) \
;         acc[ai][bj][m][n] = __builtin_amdgcn_mfma_f32_16x16x32_bf16(Bt[n][k], At[m][k], acc[ai][bj][m][n], 0, 0, 0); __builtin_amdgcn_s_setprio(0); } while (0)
; #define PG8_WAIT_V(n) asm volatile("s_waitcnt vmcnt(" #n ")" ::: "memory")
; #define PG8_WAIT_L(n) asm volatile("s_waitcnt lgkmcnt(" #n ")" ::: "memory")
; #define PG8_BAR __builtin_amdgcn_s_barrier()
; #define PG8_SCHED __builtin_amdgcn_sched_barrier(0)
; template <class Epi, class Sched, bool ALIGN_EPI = true, bool SP2 = true>
; __device__ __forceinline__ void gemm_phase(LAS unsigned char* lds, const Gemm g, const Sched& S, const Epi& E) {
;     ...
;             PG8_LDB(B0, 0, 0); PG8_LDB(B1, 0, 1); PG8_SCHED; PG8_LDA(At, 0, 0); PG8_STAGE(PG8_SA(1, 1), a1 + hstep, voffA);
;             PG8_WAIT_V(8); PG8_WAIT_L(0); PG8_BAR; PG8_MMA(0, 0, At, B0); PG8_MMA(0, 1, At, B1); PG8_BAR; PG8_SCHED;
;             PG8_LDA(At, 0, 1); PG8_STAGE(PG8_SB(0, 0), b2, voffB); PG8_STAGE(PG8_SB(0, 1), b2 + hstep, voffB); PG8_STAGE(PG8_SA(0, 0), a2, voffA);
;             PG8_WAIT_V(8); PG8_WAIT_L(0); PG8_BAR; PG8_MMA(1, 0, At, B0); PG8_MMA(1, 1, At, B1); PG8_BAR; PG8_SCHED;
.LBB0_2179:
	ds_read_b128 v[120:123], v201
	ds_read_b128 v[124:127], v201 offset:1024
	ds_read_b128 v[132:135], v201 offset:2048
	ds_read_b128 v[140:143], v201 offset:3072
	ds_read_b128 v[144:147], v202
	ds_read_b128 v[148:151], v202 offset:1024
	ds_read_b128 v[152:155], v202 offset:2048
	ds_read_b128 v[156:159], v202 offset:3072
	s_add_u32 s36, s34, 0xfff00080
	s_addc_u32 s37, s35, -1
	s_cmp_eq_u32 s61, 60
	s_cselect_b32 s39, s27, s37
	s_cselect_b32 s38, s57, s36
	s_cselect_b32 s37, s25, s60
	s_cselect_b32 s36, s58, s59
	s_add_i32 m0, s43, 0xc000
	ds_read_b128 v[160:163], v203
	ds_read_b128 v[164:167], v203 offset:1024
	ds_read_b128 v[168:171], v203 offset:2048
	ds_read_b128 v[172:175], v203 offset:3072
	ds_read_b128 v[192:195], v203 offset:4096
	ds_read_b128 v[206:209], v203 offset:5120
	ds_read_b128 v[210:213], v203 offset:6144
	ds_read_b128 v[214:217], v203 offset:7168
	global_load_lds_dwordx4 v184, s[34:35]
	s_add_i32 m0, s43, 0xe000
	s_nop 0
	global_load_lds_dwordx4 v186, s[34:35]
	s_waitcnt vmcnt(8)
	s_waitcnt lgkmcnt(0)
	s_setprio 1
	s_barrier
	v_mfma_f32_16x16x32_bf16 v[136:139], v[120:123], v[160:163], v[136:139]
	v_mfma_f32_16x16x32_bf16 v[128:131], v[132:135], v[160:163], v[128:131]
	v_mfma_f32_16x16x32_bf16 v[108:111], v[120:123], v[168:171], v[108:111]
	v_mfma_f32_16x16x32_bf16 v[104:107], v[132:135], v[168:171], v[104:107]
	v_mfma_f32_16x16x32_bf16 v[92:95], v[120:123], v[192:195], v[92:95]
	v_mfma_f32_16x16x32_bf16 v[88:91], v[132:135], v[192:195], v[88:91]
	v_mfma_f32_16x16x32_bf16 v[76:79], v[120:123], v[210:213], v[76:79]
	v_mfma_f32_16x16x32_bf16 v[72:75], v[132:135], v[210:213], v[72:75]
	v_mfma_f32_16x16x32_bf16 v[136:139], v[124:127], v[164:167], v[136:139]
	v_mfma_f32_16x16x32_bf16 v[128:131], v[140:143], v[164:167], v[128:131]
	v_mfma_f32_16x16x32_bf16 v[108:111], v[124:127], v[172:175], v[108:111]
	v_mfma_f32_16x16x32_bf16 v[104:107], v[140:143], v[172:175], v[104:107]
	v_mfma_f32_16x16x32_bf16 v[92:95], v[124:127], v[206:209], v[92:95]
	v_mfma_f32_16x16x32_bf16 v[88:91], v[140:143], v[206:209], v[88:91]
	v_mfma_f32_16x16x32_bf16 v[76:79], v[124:127], v[214:217], v[76:79]
	v_mfma_f32_16x16x32_bf16 v[72:75], v[140:143], v[214:217], v[72:75]
	v_mfma_f32_16x16x32_bf16 v[116:119], v[144:147], v[160:163], v[116:119]
	v_mfma_f32_16x16x32_bf16 v[112:115], v[152:155], v[160:163], v[112:115]
	v_mfma_f32_16x16x32_bf16 v[100:103], v[144:147], v[168:171], v[100:103]
	v_mfma_f32_16x16x32_bf16 v[96:99], v[152:155], v[168:171], v[96:99]
	v_mfma_f32_16x16x32_bf16 v[84:87], v[144:147], v[192:195], v[84:87]
	v_mfma_f32_16x16x32_bf16 v[80:83], v[152:155], v[192:195], v[80:83]
	v_mfma_f32_16x16x32_bf16 v[68:71], v[144:147], v[210:213], v[68:71]
	v_mfma_f32_16x16x32_bf16 v[64:67], v[152:155], v[210:213], v[64:67]
	v_mfma_f32_16x16x32_bf16 v[116:119], v[148:151], v[164:167], v[116:119]
	v_mfma_f32_16x16x32_bf16 v[112:115], v[156:159], v[164:167], v[112:115]
	v_mfma_f32_16x16x32_bf16 v[100:103], v[148:151], v[172:175], v[100:103]
	v_mfma_f32_16x16x32_bf16 v[96:99], v[156:159], v[172:175], v[96:99]
	v_mfma_f32_16x16x32_bf16 v[84:87], v[148:151], v[206:209], v[84:87]
	v_mfma_f32_16x16x32_bf16 v[80:83], v[156:159], v[206:209], v[80:83]
	v_mfma_f32_16x16x32_bf16 v[68:71], v[148:151], v[214:217], v[68:71]
	v_mfma_f32_16x16x32_bf16 v[64:67], v[156:159], v[214:217], v[64:67]
	s_barrier
	s_setprio 0
	s_add_i32 s62, s51, s42
	v_lshl_add_u64 v[196:197], s[36:37], 0, v[178:179]
	s_mov_b32 m0, s62
	ds_read_b128 v[160:163], v203 offset:16384
	ds_read_b128 v[164:167], v203 offset:17408
	ds_read_b128 v[168:171], v203 offset:18432
	ds_read_b128 v[172:175], v203 offset:19456
	ds_read_b128 v[192:195], v203 offset:20480
	ds_read_b128 v[206:209], v203 offset:21504
	ds_read_b128 v[210:213], v203 offset:22528
	ds_read_b128 v[214:217], v203 offset:23552
	global_load_lds_dwordx4 v[196:197], off
	s_add_i32 m0, s62, 0x2000
	s_add_u32 s62, s36, 0x100000
	v_lshl_add_u64 v[218:219], s[36:37], 0, v[182:183]
	s_addc_u32 s63, s37, 0
	s_add_i32 s64, s52, s42
	global_load_lds_dwordx4 v[218:219], off
	s_mov_b32 m0, s64
	v_lshl_add_u64 v[222:223], s[38:39], 0, v[180:181]
	global_load_lds_dwordx4 v178, s[62:63]
	s_add_i32 m0, s64, 0x2000
	s_nop 0
	global_load_lds_dwordx4 v182, s[62:63]
	v_lshl_add_u64 v[220:221], s[38:39], 0, v[176:177]
	s_mov_b32 m0, s43
	s_nop 0
	global_load_lds_dwordx4 v[220:221], off
	s_mov_b32 m0, s44
	s_nop 0
	global_load_lds_dwordx4 v[222:223], off
	s_waitcnt vmcnt(8)
	s_waitcnt lgkmcnt(0)
	s_setprio 1
	s_barrier
	v_mfma_f32_16x16x32_bf16 v[60:63], v[120:123], v[160:163], v[60:63]
	v_mfma_f32_16x16x32_bf16 v[56:59], v[132:135], v[160:163], v[56:59]
	v_mfma_f32_16x16x32_bf16 v[44:47], v[120:123], v[168:171], v[44:47]
	v_mfma_f32_16x16x32_bf16 v[40:43], v[132:135], v[168:171], v[40:43]
	v_mfma_f32_16x16x32_bf16 v[28:31], v[120:123], v[192:195], v[28:31]
	v_mfma_f32_16x16x32_bf16 v[24:27], v[132:135], v[192:195], v[24:27]
	v_mfma_f32_16x16x32_bf16 v[12:15], v[120:123], v[210:213], v[12:15]
	v_mfma_f32_16x16x32_bf16 v[8:11], v[132:135], v[210:213], v[8:11]
	v_mfma_f32_16x16x32_bf16 v[60:63], v[124:127], v[164:167], v[60:63]
	v_mfma_f32_16x16x32_bf16 v[56:59], v[140:143], v[164:167], v[56:59]
	v_mfma_f32_16x16x32_bf16 v[44:47], v[124:127], v[172:175], v[44:47]
	v_mfma_f32_16x16x32_bf16 v[40:43], v[140:143], v[172:175], v[40:43]
	v_mfma_f32_16x16x32_bf16 v[28:31], v[124:127], v[206:209], v[28:31]
	v_mfma_f32_16x16x32_bf16 v[24:27], v[140:143], v[206:209], v[24:27]
	v_mfma_f32_16x16x32_bf16 v[12:15], v[124:127], v[214:217], v[12:15]
	v_mfma_f32_16x16x32_bf16 v[8:11], v[140:143], v[214:217], v[8:11]
	v_mfma_f32_16x16x32_bf16 v[52:55], v[144:147], v[160:163], v[52:55]
	v_mfma_f32_16x16x32_bf16 v[48:51], v[152:155], v[160:163], v[48:51]
	v_mfma_f32_16x16x32_bf16 v[36:39], v[144:147], v[168:171], v[36:39]
	v_mfma_f32_16x16x32_bf16 v[32:35], v[152:155], v[168:171], v[32:35]
	v_mfma_f32_16x16x32_bf16 v[20:23], v[144:147], v[192:195], v[20:23]
	v_mfma_f32_16x16x32_bf16 v[16:19], v[152:155], v[192:195], v[16:19]
	v_mfma_f32_16x16x32_bf16 v[4:7], v[144:147], v[210:213], v[4:7]
	v_mfma_f32_16x16x32_bf16 v[0:3], v[152:155], v[210:213], v[0:3]
	v_mfma_f32_16x16x32_bf16 v[52:55], v[148:151], v[164:167], v[52:55]
	v_mfma_f32_16x16x32_bf16 v[48:51], v[156:159], v[164:167], v[48:51]
	v_mfma_f32_16x16x32_bf16 v[36:39], v[148:151], v[172:175], v[36:39]
	v_mfma_f32_16x16x32_bf16 v[32:35], v[156:159], v[172:175], v[32:35]
	v_mfma_f32_16x16x32_bf16 v[20:23], v[148:151], v[206:209], v[20:23]
	v_mfma_f32_16x16x32_bf16 v[16:19], v[156:159], v[206:209], v[16:19]
	v_mfma_f32_16x16x32_bf16 v[4:7], v[148:151], v[214:217], v[4:7]
	v_mfma_f32_16x16x32_bf16 v[0:3], v[156:159], v[214:217], v[0:3]
	s_barrier
; #define PG8_STAGE(bufoff, gbase, voff) do { _Pragma("unroll") for (int _i = 0; _i < 2; ++_i) \
;         __builtin_amdgcn_global_load_lds((const unsigned*)((const char*)(gbase) + (voff)[_i]), (LAS unsigned*)(lds + (bufoff) + ldsw + _i * 8192), 16, 0, 0); } while (0)
; #define PG8_LDA(dst, b, h) do { _Pragma("unroll") for (int m = 0; m < 4; ++m) _Pragma("unroll") for (int k = 0; k < 2; ++k) dst[m][k] = *(const LAS bf16x8*)(lds + PG8_SA(b, h) + aoff + m * 2048 + k * 1024); } while (0)
; #define PG8_LDB(dst, b, h) do { _Pragma("unroll") for (int n = 0; n < 2; ++n) _Pragma("unroll") for (int k = 0; k < 2; ++k) dst[n][k] = *(const LAS bf16x8*)(lds + PG8_SB(b, h) + boff + n * 2048 + k * 1024); } while (0)
; #define PG8_MMA(ai, bj, At, Bt) do { __builtin_amdgcn_s_setprio(1); _Pragma("unroll") for (int m = 0; m < 4; ++m) _Pragma("unroll") for (int n = 0; n < 2; ++n) _Pragma("unroll") for (int k = 0; k < 2; ++k) \
;         acc[ai][bj][m][n] = __builtin_amdgcn_mfma_f32_16x16x32_bf16(Bt[n][k], At[m][k], acc[ai][bj][m][n], 0, 0, 0); __builtin_amdgcn_s_setprio(0); } while (0)
; #define PG8_WAIT_V(n) asm volatile("s_waitcnt vmcnt(" #n ")" ::: "memory")
; #define PG8_WAIT_L(n) asm volatile("s_waitcnt lgkmcnt(" #n ")" ::: "memory")
; #define PG8_BAR __builtin_amdgcn_s_barrier()
; #define PG8_SCHED __builtin_amdgcn_sched_barrier(0)
; template <class Epi, class Sched, bool ALIGN_EPI = true, bool SP2 = true>
; __device__ __forceinline__ void gemm_phase(LAS unsigned char* lds, const Gemm g, const Sched& S, const Epi& E) {
;     ...
;             PG8_LDB(B0, 1, 0); PG8_LDB(B1, 1, 1); PG8_SCHED; PG8_LDA(At, 1, 0); PG8_STAGE(PG8_SA(0, 1), a2 + hstep, voffA);
;             PG8_WAIT_V(8); PG8_WAIT_L(0); PG8_BAR; PG8_MMA(0, 0, At, B0); PG8_MMA(0, 1, At, B1); PG8_BAR; PG8_SCHED;
;             PG8_LDA(At, 1, 1); PG8_STAGE(PG8_SB(1, 0), b3, voffB); PG8_STAGE(PG8_SB(1, 1), b3 + hstep, voffB); PG8_STAGE(PG8_SA(1, 0), a3, voffA);
;             PG8_WAIT_V(8); PG8_WAIT_L(0); PG8_BAR; PG8_MMA(1, 0, At, B0); PG8_MMA(1, 1, At, B1); PG8_BAR; PG8_SCHED;
	s_setprio 0
	s_add_i32 s62, 0, 0x18000
	s_add_i32 s63, 0, 0x1c000
	v_add_u32_e32 v140, s62, v199
	v_add_u32_e32 v156, s63, v199
	ds_read_b128 v[120:123], v140
	ds_read_b128 v[124:127], v140 offset:1024
	ds_read_b128 v[132:135], v140 offset:2048
	ds_read_b128 v[140:143], v140 offset:3072
	ds_read_b128 v[144:147], v156
	ds_read_b128 v[148:151], v156 offset:1024
	ds_read_b128 v[152:155], v156 offset:2048
	ds_read_b128 v[156:159], v156 offset:3072
	s_add_u32 s38, s38, 0x100000
	s_addc_u32 s39, s39, 0
	s_mov_b32 m0, s45
	ds_read_b128 v[160:163], v203 offset:32768
	ds_read_b128 v[164:167], v203 offset:33792
	ds_read_b128 v[168:171], v203 offset:34816
	ds_read_b128 v[172:175], v203 offset:35840
	ds_read_b128 v[192:195], v203 offset:36864
	ds_read_b128 v[206:209], v203 offset:37888
	ds_read_b128 v[210:213], v203 offset:38912
	ds_read_b128 v[214:217], v203 offset:39936
	global_load_lds_dwordx4 v176, s[38:39]
	s_mov_b32 m0, s46
	s_nop 0
	global_load_lds_dwordx4 v180, s[38:39]
	s_waitcnt vmcnt(8)
	s_waitcnt lgkmcnt(0)
	s_setprio 1
	s_barrier
	v_mfma_f32_16x16x32_bf16 v[136:139], v[120:123], v[160:163], v[136:139]
	v_mfma_f32_16x16x32_bf16 v[128:131], v[132:135], v[160:163], v[128:131]
	v_mfma_f32_16x16x32_bf16 v[108:111], v[120:123], v[168:171], v[108:111]
	v_mfma_f32_16x16x32_bf16 v[104:107], v[132:135], v[168:171], v[104:107]
	v_mfma_f32_16x16x32_bf16 v[92:95], v[120:123], v[192:195], v[92:95]
	v_mfma_f32_16x16x32_bf16 v[88:91], v[132:135], v[192:195], v[88:91]
	v_mfma_f32_16x16x32_bf16 v[76:79], v[120:123], v[210:213], v[76:79]
	v_mfma_f32_16x16x32_bf16 v[72:75], v[132:135], v[210:213], v[72:75]
	v_mfma_f32_16x16x32_bf16 v[136:139], v[124:127], v[164:167], v[136:139]
	v_mfma_f32_16x16x32_bf16 v[128:131], v[140:143], v[164:167], v[128:131]
	v_mfma_f32_16x16x32_bf16 v[108:111], v[124:127], v[172:175], v[108:111]
	v_mfma_f32_16x16x32_bf16 v[104:107], v[140:143], v[172:175], v[104:107]
	v_mfma_f32_16x16x32_bf16 v[92:95], v[124:127], v[206:209], v[92:95]
	v_mfma_f32_16x16x32_bf16 v[88:91], v[140:143], v[206:209], v[88:91]
	v_mfma_f32_16x16x32_bf16 v[76:79], v[124:127], v[214:217], v[76:79]
	v_mfma_f32_16x16x32_bf16 v[72:75], v[140:143], v[214:217], v[72:75]
	v_mfma_f32_16x16x32_bf16 v[116:119], v[144:147], v[160:163], v[116:119]
	v_mfma_f32_16x16x32_bf16 v[112:115], v[152:155], v[160:163], v[112:115]
	v_mfma_f32_16x16x32_bf16 v[100:103], v[144:147], v[168:171], v[100:103]
	v_mfma_f32_16x16x32_bf16 v[96:99], v[152:155], v[168:171], v[96:99]
	v_mfma_f32_16x16x32_bf16 v[84:87], v[144:147], v[192:195], v[84:87]
	v_mfma_f32_16x16x32_bf16 v[80:83], v[152:155], v[192:195], v[80:83]
	v_mfma_f32_16x16x32_bf16 v[68:71], v[144:147], v[210:213], v[68:71]
	v_mfma_f32_16x16x32_bf16 v[64:67], v[152:155], v[210:213], v[64:67]
	v_mfma_f32_16x16x32_bf16 v[116:119], v[148:151], v[164:167], v[116:119]
	v_mfma_f32_16x16x32_bf16 v[112:115], v[156:159], v[164:167], v[112:115]
	v_mfma_f32_16x16x32_bf16 v[100:103], v[148:151], v[172:175], v[100:103]
	v_mfma_f32_16x16x32_bf16 v[96:99], v[156:159], v[172:175], v[96:99]
	v_mfma_f32_16x16x32_bf16 v[84:87], v[148:151], v[206:209], v[84:87]
	v_mfma_f32_16x16x32_bf16 v[80:83], v[156:159], v[206:209], v[80:83]
	v_mfma_f32_16x16x32_bf16 v[68:71], v[148:151], v[214:217], v[68:71]
	v_mfma_f32_16x16x32_bf16 v[64:67], v[156:159], v[214:217], v[64:67]
	s_barrier
	s_setprio 0
	s_add_i32 s38, s62, s42
	v_lshl_add_u64 v[196:197], v[196:197], 0, s[14:15]
	s_mov_b32 m0, s38
	ds_read_b128 v[160:163], v203 offset:49152
	ds_read_b128 v[164:167], v203 offset:50176
	ds_read_b128 v[168:171], v203 offset:51200
	ds_read_b128 v[172:175], v203 offset:52224
	ds_read_b128 v[192:195], v203 offset:53248
	ds_read_b128 v[206:209], v203 offset:54272
	ds_read_b128 v[210:213], v203 offset:55296
	ds_read_b128 v[214:217], v203 offset:56320
	global_load_lds_dwordx4 v[196:197], off
	s_add_i32 m0, s38, 0x2000
	s_add_u32 s36, s36, 0x100080
	v_lshl_add_u64 v[196:197], v[218:219], 0, s[14:15]
	s_addc_u32 s37, s37, 0
	s_add_i32 s38, s63, s42
	global_load_lds_dwordx4 v[196:197], off
	s_mov_b32 m0, s38
	s_nop 0
	global_load_lds_dwordx4 v178, s[36:37]
	s_add_i32 m0, s38, 0x2000
	s_nop 0
	global_load_lds_dwordx4 v182, s[36:37]
	v_lshl_add_u64 v[196:197], v[220:221], 0, s[14:15]
	s_mov_b32 m0, s48
	s_nop 0
	global_load_lds_dwordx4 v[196:197], off
	v_lshl_add_u64 v[196:197], v[222:223], 0, s[14:15]
	s_mov_b32 m0, s49
	s_nop 0
	global_load_lds_dwordx4 v[196:197], off
	s_waitcnt vmcnt(8)
	s_waitcnt lgkmcnt(0)
	s_setprio 1
	s_barrier
	v_mfma_f32_16x16x32_bf16 v[60:63], v[120:123], v[160:163], v[60:63]
	v_mfma_f32_16x16x32_bf16 v[56:59], v[132:135], v[160:163], v[56:59]
	v_mfma_f32_16x16x32_bf16 v[44:47], v[120:123], v[168:171], v[44:47]
	v_mfma_f32_16x16x32_bf16 v[40:43], v[132:135], v[168:171], v[40:43]
	v_mfma_f32_16x16x32_bf16 v[28:31], v[120:123], v[192:195], v[28:31]
	v_mfma_f32_16x16x32_bf16 v[24:27], v[132:135], v[192:195], v[24:27]
	v_mfma_f32_16x16x32_bf16 v[12:15], v[120:123], v[210:213], v[12:15]
	v_mfma_f32_16x16x32_bf16 v[8:11], v[132:135], v[210:213], v[8:11]
	v_mfma_f32_16x16x32_bf16 v[60:63], v[124:127], v[164:167], v[60:63]
	v_mfma_f32_16x16x32_bf16 v[56:59], v[140:143], v[164:167], v[56:59]
	v_mfma_f32_16x16x32_bf16 v[44:47], v[124:127], v[172:175], v[44:47]
	v_mfma_f32_16x16x32_bf16 v[40:43], v[140:143], v[172:175], v[40:43]
	v_mfma_f32_16x16x32_bf16 v[28:31], v[124:127], v[206:209], v[28:31]
	v_mfma_f32_16x16x32_bf16 v[24:27], v[140:143], v[206:209], v[24:27]
	v_mfma_f32_16x16x32_bf16 v[12:15], v[124:127], v[214:217], v[12:15]
	v_mfma_f32_16x16x32_bf16 v[8:11], v[140:143], v[214:217], v[8:11]
	v_mfma_f32_16x16x32_bf16 v[52:55], v[144:147], v[160:163], v[52:55]
	v_mfma_f32_16x16x32_bf16 v[48:51], v[152:155], v[160:163], v[48:51]
	v_mfma_f32_16x16x32_bf16 v[36:39], v[144:147], v[168:171], v[36:39]
	v_mfma_f32_16x16x32_bf16 v[32:35], v[152:155], v[168:171], v[32:35]
	v_mfma_f32_16x16x32_bf16 v[20:23], v[144:147], v[192:195], v[20:23]
	v_mfma_f32_16x16x32_bf16 v[16:19], v[152:155], v[192:195], v[16:19]
	v_mfma_f32_16x16x32_bf16 v[4:7], v[144:147], v[210:213], v[4:7]
	v_mfma_f32_16x16x32_bf16 v[0:3], v[152:155], v[210:213], v[0:3]
	v_mfma_f32_16x16x32_bf16 v[52:55], v[148:151], v[164:167], v[52:55]
	v_mfma_f32_16x16x32_bf16 v[48:51], v[156:159], v[164:167], v[48:51]
	v_mfma_f32_16x16x32_bf16 v[36:39], v[148:151], v[172:175], v[36:39]
	v_mfma_f32_16x16x32_bf16 v[32:35], v[156:159], v[172:175], v[32:35]
	v_mfma_f32_16x16x32_bf16 v[20:23], v[148:151], v[206:209], v[20:23]
	v_mfma_f32_16x16x32_bf16 v[16:19], v[156:159], v[206:209], v[16:19]
	v_mfma_f32_16x16x32_bf16 v[4:7], v[148:151], v[214:217], v[4:7]
	v_mfma_f32_16x16x32_bf16 v[0:3], v[156:159], v[214:217], v[0:3]
	s_barrier
	s_setprio 0
	s_add_i32 s61, s61, 2
	s_add_u32 s34, s34, 0x100
	s_addc_u32 s35, s35, 0
	s_add_u32 s59, s59, 0x100
	s_addc_u32 s60, s60, 0
	s_cmp_gt_u32 s61, 61
	s_cbranch_scc0 .LBB0_2179
	s_and_b64 vcc, exec, s[16:17]
	s_cbranch_vccz .LBB0_2182
	s_barrier
